# GEMM mainloops: snake MFMA order (consecutive MFMAs share one operand), bit-identical reorder
# speedup vs baseline: 1.0026x; 1.0026x over previous
; #define PG8_STAGE(bufoff, gbase, voff) do { _Pragma("unroll") for (int _i = 0; _i < 2; ++_i) \
;         __builtin_amdgcn_global_load_lds((const unsigned*)((const char*)(gbase) + (voff)[_i]), (PG8_LAS unsigned*)(lds + (bufoff) + ldsw + _i * 8192), 16, 0, 0); } while (0)
; #define PG8_LDA(dst, b, h) do { _Pragma("unroll") for (int m = 0; m < 4; ++m) _Pragma("unroll") for (int k = 0; k < 2; ++k) dst[m][k] = *(const PG8_LAS bf16x8*)(lds + PG8_SA(b, h) + aoff + m * 2048 + k * 1024); } while (0)
; #define PG8_LDB(dst, b, h) do { _Pragma("unroll") for (int n = 0; n < 2; ++n) _Pragma("unroll") for (int k = 0; k < 2; ++k) dst[n][k] = *(const PG8_LAS bf16x8*)(lds + PG8_SB(b, h) + boff + n * 2048 + k * 1024); } while (0)
; #define PG8_MMA(ai, bj, At, Bt) do { __builtin_amdgcn_s_setprio(1); _Pragma("unroll") for (int m = 0; m < 4; ++m) _Pragma("unroll") for (int n = 0; n < 2; ++n) _Pragma("unroll") for (int k = 0; k < 2; ++k) \
;         acc[ai][bj][m][n] = __builtin_amdgcn_mfma_f32_16x16x32_bf16(Bt[n][k], At[m][k], acc[ai][bj][m][n], 0, 0, 0); __builtin_amdgcn_s_setprio(0); } while (0)
; #define PG8_WAIT_V(n) asm volatile("s_waitcnt vmcnt(" #n ")" ::: "memory")
; #define PG8_WAIT_L(n) asm volatile("s_waitcnt lgkmcnt(" #n ")" ::: "memory")
; #define PG8_BAR __builtin_amdgcn_s_barrier()
; #define PG8_SCHED __builtin_amdgcn_sched_barrier(0)
; template <class Epi, class Sched, bool ALIGN_EPI = false, bool SP2 = false>
; __device__ __forceinline__ void gemm_phase(PG8_LAS unsigned char* lds, const Gemm g, const Sched& S, const Epi& E) {
;     ...
;             PG8_LDB(B0, 0, 0); PG8_LDB(B1, 0, 1); PG8_SCHED; PG8_LDA(At, 0, 0); PG8_STAGE(PG8_SA(1, 1), a1 + hstep, voffA);
;             PG8_WAIT_V(8); PG8_WAIT_L(0); PG8_BAR; PG8_MMA(0, 0, At, B0); PG8_MMA(0, 1, At, B1); PG8_BAR; PG8_SCHED;
;             PG8_LDA(At, 0, 1); PG8_STAGE(PG8_SB(0, 0), b2, voffB); PG8_STAGE(PG8_SB(0, 1), b2 + hstep, voffB); PG8_STAGE(PG8_SA(0, 0), a2, voffA);
.LBB0_510:
	ds_read_b128 v[128:131], v184
	ds_read_b128 v[148:151], v184 offset:1024
	ds_read_b128 v[152:155], v184 offset:2048
	ds_read_b128 v[158:161], v184 offset:3072
	ds_read_b128 v[190:193], v185
	ds_read_b128 v[194:197], v185 offset:1024
	ds_read_b128 v[198:201], v185 offset:2048
	ds_read_b128 v[202:205], v185 offset:3072
	s_add_u32 s34, s10, 0xfffc0080
	s_addc_u32 s35, s11, -1
	s_cmp_eq_u32 vcc_lo, 12
	s_cselect_b32 s69, s57, s35
	s_cselect_b32 s68, s63, s34
	s_cselect_b32 s67, s55, s97
	s_cselect_b32 s66, s95, s96
	v_lshl_add_u64 v[238:239], s[10:11], 0, v[142:143]
	s_add_i32 m0, s65, 0xc000
	ds_read_b128 v[206:209], v186
	ds_read_b128 v[210:213], v186 offset:1024
	ds_read_b128 v[214:217], v186 offset:2048
	ds_read_b128 v[218:221], v186 offset:3072
	ds_read_b128 v[222:225], v186 offset:4096
	ds_read_b128 v[226:229], v186 offset:5120
	ds_read_b128 v[230:233], v186 offset:6144
	ds_read_b128 v[234:237], v186 offset:7168
	global_load_lds_dwordx4 v[238:239], off
	v_lshl_add_u64 v[238:239], s[10:11], 0, v[140:141]
	s_add_i32 m0, s65, 0xe000
	s_nop 0
	global_load_lds_dwordx4 v[238:239], off
	s_waitcnt vmcnt(8)
	s_waitcnt lgkmcnt(0)
	s_barrier
	s_setprio 1
	s_waitcnt lgkmcnt(0)
	v_mfma_f32_16x16x32_bf16 v[124:127], v[128:131], v[206:209], v[124:127]
	v_mfma_f32_16x16x32_bf16 v[120:123], v[152:155], v[206:209], v[120:123]
	v_mfma_f32_16x16x32_bf16 v[104:107], v[152:155], v[214:217], v[104:107]
	v_mfma_f32_16x16x32_bf16 v[108:111], v[128:131], v[214:217], v[108:111]
	v_mfma_f32_16x16x32_bf16 v[92:95], v[128:131], v[222:225], v[92:95]
	v_mfma_f32_16x16x32_bf16 v[88:91], v[152:155], v[222:225], v[88:91]
	v_mfma_f32_16x16x32_bf16 v[72:75], v[152:155], v[230:233], v[72:75]
	v_mfma_f32_16x16x32_bf16 v[76:79], v[128:131], v[230:233], v[76:79]
	v_mfma_f32_16x16x32_bf16 v[124:127], v[148:151], v[210:213], v[124:127]
	v_mfma_f32_16x16x32_bf16 v[120:123], v[158:161], v[210:213], v[120:123]
	v_mfma_f32_16x16x32_bf16 v[104:107], v[158:161], v[218:221], v[104:107]
	v_mfma_f32_16x16x32_bf16 v[108:111], v[148:151], v[218:221], v[108:111]
	v_mfma_f32_16x16x32_bf16 v[92:95], v[148:151], v[226:229], v[92:95]
	v_mfma_f32_16x16x32_bf16 v[88:91], v[158:161], v[226:229], v[88:91]
	v_mfma_f32_16x16x32_bf16 v[72:75], v[158:161], v[234:237], v[72:75]
	v_mfma_f32_16x16x32_bf16 v[76:79], v[148:151], v[234:237], v[76:79]
	s_setprio 0
	s_setprio 1
	v_mfma_f32_16x16x32_bf16 v[116:119], v[190:193], v[206:209], v[116:119]
	v_mfma_f32_16x16x32_bf16 v[112:115], v[198:201], v[206:209], v[112:115]
	v_mfma_f32_16x16x32_bf16 v[96:99], v[198:201], v[214:217], v[96:99]
	v_mfma_f32_16x16x32_bf16 v[100:103], v[190:193], v[214:217], v[100:103]
	v_mfma_f32_16x16x32_bf16 v[84:87], v[190:193], v[222:225], v[84:87]
	v_mfma_f32_16x16x32_bf16 v[80:83], v[198:201], v[222:225], v[80:83]
	v_mfma_f32_16x16x32_bf16 v[64:67], v[198:201], v[230:233], v[64:67]
	v_mfma_f32_16x16x32_bf16 v[68:71], v[190:193], v[230:233], v[68:71]
	v_mfma_f32_16x16x32_bf16 v[116:119], v[194:197], v[210:213], v[116:119]
	v_mfma_f32_16x16x32_bf16 v[112:115], v[202:205], v[210:213], v[112:115]
	v_mfma_f32_16x16x32_bf16 v[96:99], v[202:205], v[218:221], v[96:99]
	v_mfma_f32_16x16x32_bf16 v[100:103], v[194:197], v[218:221], v[100:103]
	v_mfma_f32_16x16x32_bf16 v[84:87], v[194:197], v[226:229], v[84:87]
	v_mfma_f32_16x16x32_bf16 v[80:83], v[202:205], v[226:229], v[80:83]
	v_mfma_f32_16x16x32_bf16 v[64:67], v[202:205], v[234:237], v[64:67]
	v_mfma_f32_16x16x32_bf16 v[68:71], v[194:197], v[234:237], v[68:71]
	s_setprio 0
	s_barrier
	s_add_i32 s34, s84, s71
	v_lshl_add_u64 v[238:239], s[66:67], 0, v[134:135]
	s_mov_b32 m0, s34
	ds_read_b128 v[206:209], v186 offset:16384
	ds_read_b128 v[210:213], v186 offset:17408
	ds_read_b128 v[214:217], v186 offset:18432
	ds_read_b128 v[218:221], v186 offset:19456
	ds_read_b128 v[222:225], v186 offset:20480
	ds_read_b128 v[226:229], v186 offset:21504
	ds_read_b128 v[230:233], v186 offset:22528
	ds_read_b128 v[234:237], v186 offset:23552
	global_load_lds_dwordx4 v[238:239], off
	s_add_i32 m0, s34, 0x2000
	s_add_u32 s34, s66, 0x40000
	v_lshl_add_u64 v[240:241], s[66:67], 0, v[138:139]
	s_addc_u32 s35, s67, 0
	s_add_i32 vcc_hi, s85, s71
	global_load_lds_dwordx4 v[240:241], off
	v_lshl_add_u64 v[242:243], s[34:35], 0, v[134:135]
	s_mov_b32 m0, vcc_hi
	v_lshl_add_u64 v[244:245], s[68:69], 0, v[136:137]
	global_load_lds_dwordx4 v[242:243], off
	v_lshl_add_u64 v[242:243], s[34:35], 0, v[138:139]
	s_add_i32 m0, vcc_hi, 0x2000
	s_nop 0
	global_load_lds_dwordx4 v[242:243], off
	v_lshl_add_u64 v[242:243], s[68:69], 0, v[132:133]
	s_mov_b32 m0, s65
	s_nop 0
	global_load_lds_dwordx4 v[242:243], off
	s_mov_b32 m0, s73
	s_nop 0
	global_load_lds_dwordx4 v[244:245], off
	s_waitcnt vmcnt(8)
	s_waitcnt lgkmcnt(0)
	s_barrier
; #define PG8_STAGE(bufoff, gbase, voff) do { _Pragma("unroll") for (int _i = 0; _i < 2; ++_i) \
;         __builtin_amdgcn_global_load_lds((const unsigned*)((const char*)(gbase) + (voff)[_i]), (PG8_LAS unsigned*)(lds + (bufoff) + ldsw + _i * 8192), 16, 0, 0); } while (0)
; #define PG8_LDA(dst, b, h) do { _Pragma("unroll") for (int m = 0; m < 4; ++m) _Pragma("unroll") for (int k = 0; k < 2; ++k) dst[m][k] = *(const PG8_LAS bf16x8*)(lds + PG8_SA(b, h) + aoff + m * 2048 + k * 1024); } while (0)
; #define PG8_LDB(dst, b, h) do { _Pragma("unroll") for (int n = 0; n < 2; ++n) _Pragma("unroll") for (int k = 0; k < 2; ++k) dst[n][k] = *(const PG8_LAS bf16x8*)(lds + PG8_SB(b, h) + boff + n * 2048 + k * 1024); } while (0)
; #define PG8_MMA(ai, bj, At, Bt) do { __builtin_amdgcn_s_setprio(1); _Pragma("unroll") for (int m = 0; m < 4; ++m) _Pragma("unroll") for (int n = 0; n < 2; ++n) _Pragma("unroll") for (int k = 0; k < 2; ++k) \
;         acc[ai][bj][m][n] = __builtin_amdgcn_mfma_f32_16x16x32_bf16(Bt[n][k], At[m][k], acc[ai][bj][m][n], 0, 0, 0); __builtin_amdgcn_s_setprio(0); } while (0)
; #define PG8_WAIT_V(n) asm volatile("s_waitcnt vmcnt(" #n ")" ::: "memory")
; #define PG8_WAIT_L(n) asm volatile("s_waitcnt lgkmcnt(" #n ")" ::: "memory")
; #define PG8_BAR __builtin_amdgcn_s_barrier()
; #define PG8_SCHED __builtin_amdgcn_sched_barrier(0)
; template <class Epi, class Sched, bool ALIGN_EPI = false, bool SP2 = false>
; __device__ __forceinline__ void gemm_phase(PG8_LAS unsigned char* lds, const Gemm g, const Sched& S, const Epi& E) {
;     ...
;             PG8_WAIT_V(8); PG8_WAIT_L(0); PG8_BAR; PG8_MMA(1, 0, At, B0); PG8_MMA(1, 1, At, B1); PG8_BAR; PG8_SCHED;
;             PG8_LDB(B0, 1, 0); PG8_LDB(B1, 1, 1); PG8_SCHED; PG8_LDA(At, 1, 0); PG8_STAGE(PG8_SA(0, 1), a2 + hstep, voffA);
;             PG8_WAIT_V(8); PG8_WAIT_L(0); PG8_BAR; PG8_MMA(0, 0, At, B0); PG8_MMA(0, 1, At, B1); PG8_BAR; PG8_SCHED;
	s_setprio 1
	s_waitcnt lgkmcnt(0)
	v_mfma_f32_16x16x32_bf16 v[60:63], v[128:131], v[206:209], v[60:63]
	v_mfma_f32_16x16x32_bf16 v[56:59], v[152:155], v[206:209], v[56:59]
	v_mfma_f32_16x16x32_bf16 v[40:43], v[152:155], v[214:217], v[40:43]
	v_mfma_f32_16x16x32_bf16 v[44:47], v[128:131], v[214:217], v[44:47]
	v_mfma_f32_16x16x32_bf16 v[28:31], v[128:131], v[222:225], v[28:31]
	v_mfma_f32_16x16x32_bf16 v[24:27], v[152:155], v[222:225], v[24:27]
	v_mfma_f32_16x16x32_bf16 v[8:11], v[152:155], v[230:233], v[8:11]
	v_mfma_f32_16x16x32_bf16 v[12:15], v[128:131], v[230:233], v[12:15]
	v_mfma_f32_16x16x32_bf16 v[60:63], v[148:151], v[210:213], v[60:63]
	v_mfma_f32_16x16x32_bf16 v[56:59], v[158:161], v[210:213], v[56:59]
	v_mfma_f32_16x16x32_bf16 v[40:43], v[158:161], v[218:221], v[40:43]
	v_mfma_f32_16x16x32_bf16 v[44:47], v[148:151], v[218:221], v[44:47]
	v_mfma_f32_16x16x32_bf16 v[28:31], v[148:151], v[226:229], v[28:31]
	v_mfma_f32_16x16x32_bf16 v[24:27], v[158:161], v[226:229], v[24:27]
	v_mfma_f32_16x16x32_bf16 v[8:11], v[158:161], v[234:237], v[8:11]
	v_mfma_f32_16x16x32_bf16 v[12:15], v[148:151], v[234:237], v[12:15]
	s_setprio 0
	s_setprio 1
	v_mfma_f32_16x16x32_bf16 v[52:55], v[190:193], v[206:209], v[52:55]
	v_mfma_f32_16x16x32_bf16 v[48:51], v[198:201], v[206:209], v[48:51]
	v_mfma_f32_16x16x32_bf16 v[32:35], v[198:201], v[214:217], v[32:35]
	v_mfma_f32_16x16x32_bf16 v[36:39], v[190:193], v[214:217], v[36:39]
	v_mfma_f32_16x16x32_bf16 v[20:23], v[190:193], v[222:225], v[20:23]
	v_mfma_f32_16x16x32_bf16 v[16:19], v[198:201], v[222:225], v[16:19]
	v_mfma_f32_16x16x32_bf16 v[0:3], v[198:201], v[230:233], v[0:3]
	v_mfma_f32_16x16x32_bf16 v[4:7], v[190:193], v[230:233], v[4:7]
	v_mfma_f32_16x16x32_bf16 v[52:55], v[194:197], v[210:213], v[52:55]
	v_mfma_f32_16x16x32_bf16 v[48:51], v[202:205], v[210:213], v[48:51]
	v_mfma_f32_16x16x32_bf16 v[32:35], v[202:205], v[218:221], v[32:35]
	v_mfma_f32_16x16x32_bf16 v[36:39], v[194:197], v[218:221], v[36:39]
	v_mfma_f32_16x16x32_bf16 v[20:23], v[194:197], v[226:229], v[20:23]
	v_mfma_f32_16x16x32_bf16 v[16:19], v[202:205], v[226:229], v[16:19]
	v_mfma_f32_16x16x32_bf16 v[0:3], v[202:205], v[234:237], v[0:3]
	v_mfma_f32_16x16x32_bf16 v[4:7], v[194:197], v[234:237], v[4:7]
	s_setprio 0
	s_barrier
	s_add_i32 vcc_hi, 0, 0x18000
	s_add_i32 s14, 0, 0x1c000
	v_add_u32_e32 v158, vcc_hi, v163
	v_add_u32_e32 v202, s14, v163
	ds_read_b128 v[128:131], v158
	ds_read_b128 v[148:151], v158 offset:1024
	ds_read_b128 v[152:155], v158 offset:2048
	ds_read_b128 v[158:161], v158 offset:3072
	ds_read_b128 v[190:193], v202
	ds_read_b128 v[194:197], v202 offset:1024
	ds_read_b128 v[198:201], v202 offset:2048
	ds_read_b128 v[202:205], v202 offset:3072
	s_add_u32 s34, s68, 0x40000
	s_addc_u32 s35, s69, 0
	s_mov_b32 m0, s74
	v_lshl_add_u64 v[246:247], s[34:35], 0, v[132:133]
	ds_read_b128 v[206:209], v186 offset:32768
	ds_read_b128 v[210:213], v186 offset:33792
	ds_read_b128 v[214:217], v186 offset:34816
	ds_read_b128 v[218:221], v186 offset:35840
	ds_read_b128 v[222:225], v186 offset:36864
	ds_read_b128 v[226:229], v186 offset:37888
	ds_read_b128 v[230:233], v186 offset:38912
	ds_read_b128 v[234:237], v186 offset:39936
	global_load_lds_dwordx4 v[246:247], off
	v_lshl_add_u64 v[246:247], s[34:35], 0, v[136:137]
	s_mov_b32 m0, s75
	s_nop 0
	global_load_lds_dwordx4 v[246:247], off
	s_waitcnt vmcnt(8)
	s_waitcnt lgkmcnt(0)
	s_barrier
	s_setprio 1
	s_waitcnt lgkmcnt(0)
	v_mfma_f32_16x16x32_bf16 v[124:127], v[128:131], v[206:209], v[124:127]
	v_mfma_f32_16x16x32_bf16 v[120:123], v[152:155], v[206:209], v[120:123]
	v_mfma_f32_16x16x32_bf16 v[104:107], v[152:155], v[214:217], v[104:107]
	v_mfma_f32_16x16x32_bf16 v[108:111], v[128:131], v[214:217], v[108:111]
	v_mfma_f32_16x16x32_bf16 v[92:95], v[128:131], v[222:225], v[92:95]
	v_mfma_f32_16x16x32_bf16 v[88:91], v[152:155], v[222:225], v[88:91]
	v_mfma_f32_16x16x32_bf16 v[72:75], v[152:155], v[230:233], v[72:75]
	v_mfma_f32_16x16x32_bf16 v[76:79], v[128:131], v[230:233], v[76:79]
	v_mfma_f32_16x16x32_bf16 v[124:127], v[148:151], v[210:213], v[124:127]
	v_mfma_f32_16x16x32_bf16 v[120:123], v[158:161], v[210:213], v[120:123]
	v_mfma_f32_16x16x32_bf16 v[104:107], v[158:161], v[218:221], v[104:107]
	v_mfma_f32_16x16x32_bf16 v[108:111], v[148:151], v[218:221], v[108:111]
	v_mfma_f32_16x16x32_bf16 v[92:95], v[148:151], v[226:229], v[92:95]
	v_mfma_f32_16x16x32_bf16 v[88:91], v[158:161], v[226:229], v[88:91]
	v_mfma_f32_16x16x32_bf16 v[72:75], v[158:161], v[234:237], v[72:75]
	v_mfma_f32_16x16x32_bf16 v[76:79], v[148:151], v[234:237], v[76:79]
	s_setprio 0
	s_setprio 1
	v_mfma_f32_16x16x32_bf16 v[116:119], v[190:193], v[206:209], v[116:119]
	v_mfma_f32_16x16x32_bf16 v[112:115], v[198:201], v[206:209], v[112:115]
	v_mfma_f32_16x16x32_bf16 v[96:99], v[198:201], v[214:217], v[96:99]
	v_mfma_f32_16x16x32_bf16 v[100:103], v[190:193], v[214:217], v[100:103]
	v_mfma_f32_16x16x32_bf16 v[84:87], v[190:193], v[222:225], v[84:87]
	v_mfma_f32_16x16x32_bf16 v[80:83], v[198:201], v[222:225], v[80:83]
	v_mfma_f32_16x16x32_bf16 v[64:67], v[198:201], v[230:233], v[64:67]
	v_mfma_f32_16x16x32_bf16 v[68:71], v[190:193], v[230:233], v[68:71]
	v_mfma_f32_16x16x32_bf16 v[116:119], v[194:197], v[210:213], v[116:119]
	v_mfma_f32_16x16x32_bf16 v[112:115], v[202:205], v[210:213], v[112:115]
	v_mfma_f32_16x16x32_bf16 v[96:99], v[202:205], v[218:221], v[96:99]
	v_mfma_f32_16x16x32_bf16 v[100:103], v[194:197], v[218:221], v[100:103]
	v_mfma_f32_16x16x32_bf16 v[84:87], v[194:197], v[226:229], v[84:87]
	v_mfma_f32_16x16x32_bf16 v[80:83], v[202:205], v[226:229], v[80:83]
	v_mfma_f32_16x16x32_bf16 v[64:67], v[202:205], v[234:237], v[64:67]
	v_mfma_f32_16x16x32_bf16 v[68:71], v[194:197], v[234:237], v[68:71]
	s_setprio 0
	s_barrier
; #define PG8_STAGE(bufoff, gbase, voff) do { _Pragma("unroll") for (int _i = 0; _i < 2; ++_i) \
;         __builtin_amdgcn_global_load_lds((const unsigned*)((const char*)(gbase) + (voff)[_i]), (PG8_LAS unsigned*)(lds + (bufoff) + ldsw + _i * 8192), 16, 0, 0); } while (0)
; #define PG8_LDA(dst, b, h) do { _Pragma("unroll") for (int m = 0; m < 4; ++m) _Pragma("unroll") for (int k = 0; k < 2; ++k) dst[m][k] = *(const PG8_LAS bf16x8*)(lds + PG8_SA(b, h) + aoff + m * 2048 + k * 1024); } while (0)
; #define PG8_MMA(ai, bj, At, Bt) do { __builtin_amdgcn_s_setprio(1); _Pragma("unroll") for (int m = 0; m < 4; ++m) _Pragma("unroll") for (int n = 0; n < 2; ++n) _Pragma("unroll") for (int k = 0; k < 2; ++k) \
;         acc[ai][bj][m][n] = __builtin_amdgcn_mfma_f32_16x16x32_bf16(Bt[n][k], At[m][k], acc[ai][bj][m][n], 0, 0, 0); __builtin_amdgcn_s_setprio(0); } while (0)
; #define PG8_WAIT_V(n) asm volatile("s_waitcnt vmcnt(" #n ")" ::: "memory")
; #define PG8_WAIT_L(n) asm volatile("s_waitcnt lgkmcnt(" #n ")" ::: "memory")
; #define PG8_BAR __builtin_amdgcn_s_barrier()
; #define PG8_SCHED __builtin_amdgcn_sched_barrier(0)
; template <class Epi, class Sched, bool ALIGN_EPI = false, bool SP2 = false>
; __device__ __forceinline__ void gemm_phase(PG8_LAS unsigned char* lds, const Gemm g, const Sched& S, const Epi& E) {
;     ...
;         for (int t = 0; t < nt; t += 2) {
;             const bool last = (t == nt - 2);
;             const char* a1 = cA + (size_t)(t + 1) * kstep;
;             const char* a2 = last ? nA : cA + (size_t)(t + 2) * kstep; const char* b2 = last ? nB : cB + (size_t)(t + 2) * kstep;
;             const char* a3 = a2 + kstep; const char* b3 = b2 + kstep;
;     ...
;             PG8_LDA(At, 1, 1); PG8_STAGE(PG8_SB(1, 0), b3, voffB); PG8_STAGE(PG8_SB(1, 1), b3 + hstep, voffB); PG8_STAGE(PG8_SA(1, 0), a3, voffA);
;             PG8_WAIT_V(8); PG8_WAIT_L(0); PG8_BAR; PG8_MMA(1, 0, At, B0); PG8_MMA(1, 1, At, B1); PG8_BAR; PG8_SCHED;
	s_add_i32 s15, vcc_hi, s71
	v_lshl_add_u64 v[238:239], v[238:239], 0, s[42:43]
	s_mov_b32 m0, s15
	ds_read_b128 v[206:209], v186 offset:49152
	ds_read_b128 v[210:213], v186 offset:50176
	ds_read_b128 v[214:217], v186 offset:51200
	ds_read_b128 v[218:221], v186 offset:52224
	ds_read_b128 v[222:225], v186 offset:53248
	ds_read_b128 v[226:229], v186 offset:54272
	ds_read_b128 v[230:233], v186 offset:55296
	ds_read_b128 v[234:237], v186 offset:56320
	global_load_lds_dwordx4 v[238:239], off
	s_add_i32 m0, s15, 0x2000
	s_add_u32 s34, s66, 0x40080
	v_lshl_add_u64 v[238:239], v[240:241], 0, s[42:43]
	s_addc_u32 s35, s67, 0
	s_add_i32 s14, s14, s71
	global_load_lds_dwordx4 v[238:239], off
	v_lshl_add_u64 v[238:239], s[34:35], 0, v[134:135]
	s_mov_b32 m0, s14
	s_nop 0
	global_load_lds_dwordx4 v[238:239], off
	v_lshl_add_u64 v[238:239], s[34:35], 0, v[138:139]
	s_add_i32 m0, s14, 0x2000
	s_nop 0
	global_load_lds_dwordx4 v[238:239], off
	v_lshl_add_u64 v[238:239], v[242:243], 0, s[42:43]
	s_mov_b32 m0, s78
	s_nop 0
	global_load_lds_dwordx4 v[238:239], off
	v_lshl_add_u64 v[238:239], v[244:245], 0, s[42:43]
	s_mov_b32 m0, s79
	s_nop 0
	global_load_lds_dwordx4 v[238:239], off
	s_waitcnt vmcnt(8)
	s_waitcnt lgkmcnt(0)
	s_barrier
	s_setprio 1
	s_waitcnt lgkmcnt(0)
	v_mfma_f32_16x16x32_bf16 v[60:63], v[128:131], v[206:209], v[60:63]
	v_mfma_f32_16x16x32_bf16 v[56:59], v[152:155], v[206:209], v[56:59]
	v_mfma_f32_16x16x32_bf16 v[40:43], v[152:155], v[214:217], v[40:43]
	v_mfma_f32_16x16x32_bf16 v[44:47], v[128:131], v[214:217], v[44:47]
	v_mfma_f32_16x16x32_bf16 v[28:31], v[128:131], v[222:225], v[28:31]
	v_mfma_f32_16x16x32_bf16 v[24:27], v[152:155], v[222:225], v[24:27]
	v_mfma_f32_16x16x32_bf16 v[8:11], v[152:155], v[230:233], v[8:11]
	v_mfma_f32_16x16x32_bf16 v[12:15], v[128:131], v[230:233], v[12:15]
	v_mfma_f32_16x16x32_bf16 v[60:63], v[148:151], v[210:213], v[60:63]
	v_mfma_f32_16x16x32_bf16 v[56:59], v[158:161], v[210:213], v[56:59]
	v_mfma_f32_16x16x32_bf16 v[40:43], v[158:161], v[218:221], v[40:43]
	v_mfma_f32_16x16x32_bf16 v[44:47], v[148:151], v[218:221], v[44:47]
	v_mfma_f32_16x16x32_bf16 v[28:31], v[148:151], v[226:229], v[28:31]
	v_mfma_f32_16x16x32_bf16 v[24:27], v[158:161], v[226:229], v[24:27]
	v_mfma_f32_16x16x32_bf16 v[8:11], v[158:161], v[234:237], v[8:11]
	v_mfma_f32_16x16x32_bf16 v[12:15], v[148:151], v[234:237], v[12:15]
	s_setprio 0
	s_setprio 1
	v_mfma_f32_16x16x32_bf16 v[52:55], v[190:193], v[206:209], v[52:55]
	v_mfma_f32_16x16x32_bf16 v[48:51], v[198:201], v[206:209], v[48:51]
	v_mfma_f32_16x16x32_bf16 v[32:35], v[198:201], v[214:217], v[32:35]
	v_mfma_f32_16x16x32_bf16 v[36:39], v[190:193], v[214:217], v[36:39]
	v_mfma_f32_16x16x32_bf16 v[20:23], v[190:193], v[222:225], v[20:23]
	v_mfma_f32_16x16x32_bf16 v[16:19], v[198:201], v[222:225], v[16:19]
	v_mfma_f32_16x16x32_bf16 v[0:3], v[198:201], v[230:233], v[0:3]
	v_mfma_f32_16x16x32_bf16 v[4:7], v[190:193], v[230:233], v[4:7]
	v_mfma_f32_16x16x32_bf16 v[52:55], v[194:197], v[210:213], v[52:55]
	v_mfma_f32_16x16x32_bf16 v[48:51], v[202:205], v[210:213], v[48:51]
	v_mfma_f32_16x16x32_bf16 v[32:35], v[202:205], v[218:221], v[32:35]
	v_mfma_f32_16x16x32_bf16 v[36:39], v[194:197], v[218:221], v[36:39]
	v_mfma_f32_16x16x32_bf16 v[20:23], v[194:197], v[226:229], v[20:23]
	v_mfma_f32_16x16x32_bf16 v[16:19], v[202:205], v[226:229], v[16:19]
	v_mfma_f32_16x16x32_bf16 v[0:3], v[202:205], v[234:237], v[0:3]
	v_mfma_f32_16x16x32_bf16 v[4:7], v[194:197], v[234:237], v[4:7]
	s_setprio 0
	s_barrier
	s_add_i32 vcc_lo, vcc_lo, 2
	s_add_u32 s96, s96, 0x100
	s_addc_u32 s97, s97, 0
	s_add_u32 s10, s10, 0x100
	s_addc_u32 s11, s11, 0
	s_cmp_gt_u32 vcc_lo, 13
	s_cbranch_scc0 .LBB0_510
	s_and_b64 vcc, exec, s[44:45]
	s_cbranch_vccz .LBB0_513
	s_barrier

; #define PG8_STAGE(bufoff, gbase, voff) do { _Pragma("unroll") for (int _i = 0; _i < 2; ++_i) \
;         __builtin_amdgcn_global_load_lds((const unsigned*)((const char*)(gbase) + (voff)[_i]), (PG8_LAS unsigned*)(lds + (bufoff) + ldsw + _i * 8192), 16, 0, 0); } while (0)
; #define PG8_LDA(dst, b, h) do { _Pragma("unroll") for (int m = 0; m < 4; ++m) _Pragma("unroll") for (int k = 0; k < 2; ++k) dst[m][k] = *(const PG8_LAS bf16x8*)(lds + PG8_SA(b, h) + aoff + m * 2048 + k * 1024); } while (0)
; #define PG8_LDB(dst, b, h) do { _Pragma("unroll") for (int n = 0; n < 2; ++n) _Pragma("unroll") for (int k = 0; k < 2; ++k) dst[n][k] = *(const PG8_LAS bf16x8*)(lds + PG8_SB(b, h) + boff + n * 2048 + k * 1024); } while (0)
; #define PG8_MMA(ai, bj, At, Bt) do { __builtin_amdgcn_s_setprio(1); _Pragma("unroll") for (int m = 0; m < 4; ++m) _Pragma("unroll") for (int n = 0; n < 2; ++n) _Pragma("unroll") for (int k = 0; k < 2; ++k) \
;         acc[ai][bj][m][n] = __builtin_amdgcn_mfma_f32_16x16x32_bf16(Bt[n][k], At[m][k], acc[ai][bj][m][n], 0, 0, 0); __builtin_amdgcn_s_setprio(0); } while (0)
; #define PG8_WAIT_V(n) asm volatile("s_waitcnt vmcnt(" #n ")" ::: "memory")
; #define PG8_WAIT_L(n) asm volatile("s_waitcnt lgkmcnt(" #n ")" ::: "memory")
; #define PG8_BAR __builtin_amdgcn_s_barrier()
; #define PG8_SCHED __builtin_amdgcn_sched_barrier(0)
; template <class Epi, class Sched, bool ALIGN_EPI = false, bool SP2 = false>
; __device__ __forceinline__ void gemm_phase(PG8_LAS unsigned char* lds, const Gemm g, const Sched& S, const Epi& E) {
;     ...
;             PG8_LDB(B0, 0, 0); PG8_LDB(B1, 0, 1); PG8_SCHED; PG8_LDA(At, 0, 0); PG8_STAGE(PG8_SA(1, 1), a1 + hstep, voffA);
;             PG8_WAIT_V(8); PG8_WAIT_L(0); PG8_BAR; PG8_MMA(0, 0, At, B0); PG8_MMA(0, 1, At, B1); PG8_BAR; PG8_SCHED;
;             PG8_LDA(At, 0, 1); PG8_STAGE(PG8_SB(0, 0), b2, voffB); PG8_STAGE(PG8_SB(0, 1), b2 + hstep, voffB); PG8_STAGE(PG8_SA(0, 0), a2, voffA);
.LBB0_710:
	ds_read_b128 v[128:131], v169
	ds_read_b128 v[132:135], v169 offset:1024
	ds_read_b128 v[136:139], v169 offset:2048
	ds_read_b128 v[140:143], v169 offset:3072
	ds_read_b128 v[162:165], v170
	ds_read_b128 v[172:175], v170 offset:1024
	ds_read_b128 v[176:179], v170 offset:2048
	ds_read_b128 v[184:187], v170 offset:3072
	s_add_u32 s14, s54, 0xfffc0080
	s_addc_u32 s15, s55, -1
	s_cmp_eq_u32 s84, 12
	s_cselect_b32 s59, s45, s15
	s_cselect_b32 s58, s51, s14
	s_cselect_b32 s57, s43, s83
	s_cselect_b32 s56, s53, s82
	v_lshl_add_u64 v[180:181], s[54:55], 0, v[154:155]
	s_add_i32 m0, s64, 0xc000
	ds_read_b128 v[188:191], v171
	ds_read_b128 v[192:195], v171 offset:1024
	ds_read_b128 v[196:199], v171 offset:2048
	ds_read_b128 v[200:203], v171 offset:3072
	ds_read_b128 v[204:207], v171 offset:4096
	ds_read_b128 v[208:211], v171 offset:5120
	ds_read_b128 v[212:215], v171 offset:6144
	ds_read_b128 v[216:219], v171 offset:7168
	global_load_lds_dwordx4 v[180:181], off
	v_lshl_add_u64 v[180:181], s[54:55], 0, v[152:153]
	s_add_i32 m0, s64, 0xe000
	s_nop 0
	global_load_lds_dwordx4 v[180:181], off
	s_waitcnt vmcnt(8)
	s_waitcnt lgkmcnt(0)
	s_barrier
	s_setprio 1
	s_waitcnt lgkmcnt(0)
	v_mfma_f32_16x16x32_bf16 v[124:127], v[128:131], v[188:191], v[124:127]
	v_mfma_f32_16x16x32_bf16 v[120:123], v[136:139], v[188:191], v[120:123]
	v_mfma_f32_16x16x32_bf16 v[108:111], v[136:139], v[196:199], v[108:111]
	v_mfma_f32_16x16x32_bf16 v[116:119], v[128:131], v[196:199], v[116:119]
	v_mfma_f32_16x16x32_bf16 v[100:103], v[128:131], v[204:207], v[100:103]
	v_mfma_f32_16x16x32_bf16 v[92:95], v[136:139], v[204:207], v[92:95]
	v_mfma_f32_16x16x32_bf16 v[76:79], v[136:139], v[212:215], v[76:79]
	v_mfma_f32_16x16x32_bf16 v[84:87], v[128:131], v[212:215], v[84:87]
	v_mfma_f32_16x16x32_bf16 v[124:127], v[132:135], v[192:195], v[124:127]
	v_mfma_f32_16x16x32_bf16 v[120:123], v[140:143], v[192:195], v[120:123]
	v_mfma_f32_16x16x32_bf16 v[108:111], v[140:143], v[200:203], v[108:111]
	v_mfma_f32_16x16x32_bf16 v[116:119], v[132:135], v[200:203], v[116:119]
	v_mfma_f32_16x16x32_bf16 v[100:103], v[132:135], v[208:211], v[100:103]
	v_mfma_f32_16x16x32_bf16 v[92:95], v[140:143], v[208:211], v[92:95]
	v_mfma_f32_16x16x32_bf16 v[76:79], v[140:143], v[216:219], v[76:79]
	v_mfma_f32_16x16x32_bf16 v[84:87], v[132:135], v[216:219], v[84:87]
	s_setprio 0
	s_setprio 1
	v_mfma_f32_16x16x32_bf16 v[112:115], v[162:165], v[188:191], v[112:115]
	v_mfma_f32_16x16x32_bf16 v[104:107], v[176:179], v[188:191], v[104:107]
	v_mfma_f32_16x16x32_bf16 v[88:91], v[176:179], v[196:199], v[88:91]
	v_mfma_f32_16x16x32_bf16 v[96:99], v[162:165], v[196:199], v[96:99]
	v_mfma_f32_16x16x32_bf16 v[80:83], v[162:165], v[204:207], v[80:83]
	v_mfma_f32_16x16x32_bf16 v[72:75], v[176:179], v[204:207], v[72:75]
	v_mfma_f32_16x16x32_bf16 v[64:67], v[176:179], v[212:215], v[64:67]
	v_mfma_f32_16x16x32_bf16 v[68:71], v[162:165], v[212:215], v[68:71]
	v_mfma_f32_16x16x32_bf16 v[112:115], v[172:175], v[192:195], v[112:115]
	v_mfma_f32_16x16x32_bf16 v[104:107], v[184:187], v[192:195], v[104:107]
	v_mfma_f32_16x16x32_bf16 v[88:91], v[184:187], v[200:203], v[88:91]
	v_mfma_f32_16x16x32_bf16 v[96:99], v[172:175], v[200:203], v[96:99]
	v_mfma_f32_16x16x32_bf16 v[80:83], v[172:175], v[208:211], v[80:83]
	v_mfma_f32_16x16x32_bf16 v[72:75], v[184:187], v[208:211], v[72:75]
	v_mfma_f32_16x16x32_bf16 v[64:67], v[184:187], v[216:219], v[64:67]
	v_mfma_f32_16x16x32_bf16 v[68:71], v[172:175], v[216:219], v[68:71]
	s_setprio 0
	s_barrier
	s_add_i32 s14, s80, s63
	v_lshl_add_u64 v[180:181], s[56:57], 0, v[146:147]
	s_mov_b32 m0, s14
	ds_read_b128 v[188:191], v171 offset:16384
	ds_read_b128 v[192:195], v171 offset:17408
	ds_read_b128 v[196:199], v171 offset:18432
	ds_read_b128 v[200:203], v171 offset:19456
	ds_read_b128 v[204:207], v171 offset:20480
	ds_read_b128 v[208:211], v171 offset:21504
	ds_read_b128 v[212:215], v171 offset:22528
	ds_read_b128 v[216:219], v171 offset:23552
	global_load_lds_dwordx4 v[180:181], off
	s_add_i32 m0, s14, 0x2000
	s_add_u32 s34, s56, 0x40000
	v_lshl_add_u64 v[220:221], s[56:57], 0, v[150:151]
	s_addc_u32 s35, s57, 0
	s_add_i32 s14, s81, s63
	global_load_lds_dwordx4 v[220:221], off
	v_lshl_add_u64 v[222:223], s[34:35], 0, v[146:147]
	s_mov_b32 m0, s14
	v_lshl_add_u64 v[224:225], s[58:59], 0, v[148:149]
	global_load_lds_dwordx4 v[222:223], off
	v_lshl_add_u64 v[222:223], s[34:35], 0, v[150:151]
	s_add_i32 m0, s14, 0x2000
	s_nop 0
	global_load_lds_dwordx4 v[222:223], off
	v_lshl_add_u64 v[222:223], s[58:59], 0, v[144:145]
	s_mov_b32 m0, s64
	s_nop 0
	global_load_lds_dwordx4 v[222:223], off
	s_mov_b32 m0, s65
	s_nop 0
	global_load_lds_dwordx4 v[224:225], off
	s_waitcnt vmcnt(8)
	s_waitcnt lgkmcnt(0)
	s_barrier
; #define PG8_STAGE(bufoff, gbase, voff) do { _Pragma("unroll") for (int _i = 0; _i < 2; ++_i) \
;         __builtin_amdgcn_global_load_lds((const unsigned*)((const char*)(gbase) + (voff)[_i]), (PG8_LAS unsigned*)(lds + (bufoff) + ldsw + _i * 8192), 16, 0, 0); } while (0)
; #define PG8_LDA(dst, b, h) do { _Pragma("unroll") for (int m = 0; m < 4; ++m) _Pragma("unroll") for (int k = 0; k < 2; ++k) dst[m][k] = *(const PG8_LAS bf16x8*)(lds + PG8_SA(b, h) + aoff + m * 2048 + k * 1024); } while (0)
; #define PG8_LDB(dst, b, h) do { _Pragma("unroll") for (int n = 0; n < 2; ++n) _Pragma("unroll") for (int k = 0; k < 2; ++k) dst[n][k] = *(const PG8_LAS bf16x8*)(lds + PG8_SB(b, h) + boff + n * 2048 + k * 1024); } while (0)
; #define PG8_MMA(ai, bj, At, Bt) do { __builtin_amdgcn_s_setprio(1); _Pragma("unroll") for (int m = 0; m < 4; ++m) _Pragma("unroll") for (int n = 0; n < 2; ++n) _Pragma("unroll") for (int k = 0; k < 2; ++k) \
;         acc[ai][bj][m][n] = __builtin_amdgcn_mfma_f32_16x16x32_bf16(Bt[n][k], At[m][k], acc[ai][bj][m][n], 0, 0, 0); __builtin_amdgcn_s_setprio(0); } while (0)
; #define PG8_WAIT_V(n) asm volatile("s_waitcnt vmcnt(" #n ")" ::: "memory")
; #define PG8_WAIT_L(n) asm volatile("s_waitcnt lgkmcnt(" #n ")" ::: "memory")
; #define PG8_BAR __builtin_amdgcn_s_barrier()
; #define PG8_SCHED __builtin_amdgcn_sched_barrier(0)
; template <class Epi, class Sched, bool ALIGN_EPI = false, bool SP2 = false>
; __device__ __forceinline__ void gemm_phase(PG8_LAS unsigned char* lds, const Gemm g, const Sched& S, const Epi& E) {
;     ...
;             PG8_WAIT_V(8); PG8_WAIT_L(0); PG8_BAR; PG8_MMA(1, 0, At, B0); PG8_MMA(1, 1, At, B1); PG8_BAR; PG8_SCHED;
;             PG8_LDB(B0, 1, 0); PG8_LDB(B1, 1, 1); PG8_SCHED; PG8_LDA(At, 1, 0); PG8_STAGE(PG8_SA(0, 1), a2 + hstep, voffA);
;             PG8_WAIT_V(8); PG8_WAIT_L(0); PG8_BAR; PG8_MMA(0, 0, At, B0); PG8_MMA(0, 1, At, B1); PG8_BAR; PG8_SCHED;
	s_setprio 1
	s_waitcnt lgkmcnt(0)
	v_mfma_f32_16x16x32_bf16 v[60:63], v[128:131], v[188:191], v[60:63]
	v_mfma_f32_16x16x32_bf16 v[56:59], v[136:139], v[188:191], v[56:59]
	v_mfma_f32_16x16x32_bf16 v[44:47], v[136:139], v[196:199], v[44:47]
	v_mfma_f32_16x16x32_bf16 v[48:51], v[128:131], v[196:199], v[48:51]
	v_mfma_f32_16x16x32_bf16 v[36:39], v[128:131], v[204:207], v[36:39]
	v_mfma_f32_16x16x32_bf16 v[28:31], v[136:139], v[204:207], v[28:31]
	v_mfma_f32_16x16x32_bf16 v[12:15], v[136:139], v[212:215], v[12:15]
	v_mfma_f32_16x16x32_bf16 v[20:23], v[128:131], v[212:215], v[20:23]
	v_mfma_f32_16x16x32_bf16 v[60:63], v[132:135], v[192:195], v[60:63]
	v_mfma_f32_16x16x32_bf16 v[56:59], v[140:143], v[192:195], v[56:59]
	v_mfma_f32_16x16x32_bf16 v[44:47], v[140:143], v[200:203], v[44:47]
	v_mfma_f32_16x16x32_bf16 v[48:51], v[132:135], v[200:203], v[48:51]
	v_mfma_f32_16x16x32_bf16 v[36:39], v[132:135], v[208:211], v[36:39]
	v_mfma_f32_16x16x32_bf16 v[28:31], v[140:143], v[208:211], v[28:31]
	v_mfma_f32_16x16x32_bf16 v[12:15], v[140:143], v[216:219], v[12:15]
	v_mfma_f32_16x16x32_bf16 v[20:23], v[132:135], v[216:219], v[20:23]
	s_setprio 0
	s_setprio 1
	v_mfma_f32_16x16x32_bf16 v[52:55], v[162:165], v[188:191], v[52:55]
	v_mfma_f32_16x16x32_bf16 v[40:43], v[176:179], v[188:191], v[40:43]
	v_mfma_f32_16x16x32_bf16 v[24:27], v[176:179], v[196:199], v[24:27]
	v_mfma_f32_16x16x32_bf16 v[32:35], v[162:165], v[196:199], v[32:35]
	v_mfma_f32_16x16x32_bf16 v[16:19], v[162:165], v[204:207], v[16:19]
	v_mfma_f32_16x16x32_bf16 v[8:11], v[176:179], v[204:207], v[8:11]
	v_mfma_f32_16x16x32_bf16 v[0:3], v[176:179], v[212:215], v[0:3]
	v_mfma_f32_16x16x32_bf16 v[4:7], v[162:165], v[212:215], v[4:7]
	v_mfma_f32_16x16x32_bf16 v[52:55], v[172:175], v[192:195], v[52:55]
	v_mfma_f32_16x16x32_bf16 v[40:43], v[184:187], v[192:195], v[40:43]
	v_mfma_f32_16x16x32_bf16 v[24:27], v[184:187], v[200:203], v[24:27]
	v_mfma_f32_16x16x32_bf16 v[32:35], v[172:175], v[200:203], v[32:35]
	v_mfma_f32_16x16x32_bf16 v[16:19], v[172:175], v[208:211], v[16:19]
	v_mfma_f32_16x16x32_bf16 v[8:11], v[184:187], v[208:211], v[8:11]
	v_mfma_f32_16x16x32_bf16 v[0:3], v[184:187], v[216:219], v[0:3]
	v_mfma_f32_16x16x32_bf16 v[4:7], v[172:175], v[216:219], v[4:7]
	s_setprio 0
	s_barrier
	s_add_i32 s14, 0, 0x18000
	s_add_i32 s15, 0, 0x1c000
	v_add_u32_e32 v140, s14, v167
	v_add_u32_e32 v183, s15, v167
	ds_read_b128 v[128:131], v140
	ds_read_b128 v[132:135], v140 offset:1024
	ds_read_b128 v[136:139], v140 offset:2048
	ds_read_b128 v[140:143], v140 offset:3072
	ds_read_b128 v[162:165], v183
	ds_read_b128 v[172:175], v183 offset:1024
	ds_read_b128 v[176:179], v183 offset:2048
	ds_read_b128 v[184:187], v183 offset:3072
	s_add_u32 s34, s58, 0x40000
	s_addc_u32 s35, s59, 0
	s_mov_b32 m0, s66
	v_lshl_add_u64 v[226:227], s[34:35], 0, v[144:145]
	ds_read_b128 v[188:191], v171 offset:32768
	ds_read_b128 v[192:195], v171 offset:33792
	ds_read_b128 v[196:199], v171 offset:34816
	ds_read_b128 v[200:203], v171 offset:35840
	ds_read_b128 v[204:207], v171 offset:36864
	ds_read_b128 v[208:211], v171 offset:37888
	ds_read_b128 v[212:215], v171 offset:38912
	ds_read_b128 v[216:219], v171 offset:39936
	global_load_lds_dwordx4 v[226:227], off
	v_lshl_add_u64 v[226:227], s[34:35], 0, v[148:149]
	s_mov_b32 m0, s67
	s_nop 0
	global_load_lds_dwordx4 v[226:227], off
	s_waitcnt vmcnt(8)
	s_waitcnt lgkmcnt(0)
	s_barrier
	s_setprio 1
	s_waitcnt lgkmcnt(0)
	v_mfma_f32_16x16x32_bf16 v[124:127], v[128:131], v[188:191], v[124:127]
	v_mfma_f32_16x16x32_bf16 v[120:123], v[136:139], v[188:191], v[120:123]
	v_mfma_f32_16x16x32_bf16 v[108:111], v[136:139], v[196:199], v[108:111]
	v_mfma_f32_16x16x32_bf16 v[116:119], v[128:131], v[196:199], v[116:119]
	v_mfma_f32_16x16x32_bf16 v[100:103], v[128:131], v[204:207], v[100:103]
	v_mfma_f32_16x16x32_bf16 v[92:95], v[136:139], v[204:207], v[92:95]
	v_mfma_f32_16x16x32_bf16 v[76:79], v[136:139], v[212:215], v[76:79]
	v_mfma_f32_16x16x32_bf16 v[84:87], v[128:131], v[212:215], v[84:87]
	v_mfma_f32_16x16x32_bf16 v[124:127], v[132:135], v[192:195], v[124:127]
	v_mfma_f32_16x16x32_bf16 v[120:123], v[140:143], v[192:195], v[120:123]
	v_mfma_f32_16x16x32_bf16 v[108:111], v[140:143], v[200:203], v[108:111]
	v_mfma_f32_16x16x32_bf16 v[116:119], v[132:135], v[200:203], v[116:119]
	v_mfma_f32_16x16x32_bf16 v[100:103], v[132:135], v[208:211], v[100:103]
	v_mfma_f32_16x16x32_bf16 v[92:95], v[140:143], v[208:211], v[92:95]
	v_mfma_f32_16x16x32_bf16 v[76:79], v[140:143], v[216:219], v[76:79]
	v_mfma_f32_16x16x32_bf16 v[84:87], v[132:135], v[216:219], v[84:87]
	s_setprio 0
	s_setprio 1
	v_mfma_f32_16x16x32_bf16 v[112:115], v[162:165], v[188:191], v[112:115]
	v_mfma_f32_16x16x32_bf16 v[104:107], v[176:179], v[188:191], v[104:107]
	v_mfma_f32_16x16x32_bf16 v[88:91], v[176:179], v[196:199], v[88:91]
	v_mfma_f32_16x16x32_bf16 v[96:99], v[162:165], v[196:199], v[96:99]
	v_mfma_f32_16x16x32_bf16 v[80:83], v[162:165], v[204:207], v[80:83]
	v_mfma_f32_16x16x32_bf16 v[72:75], v[176:179], v[204:207], v[72:75]
	v_mfma_f32_16x16x32_bf16 v[64:67], v[176:179], v[212:215], v[64:67]
	v_mfma_f32_16x16x32_bf16 v[68:71], v[162:165], v[212:215], v[68:71]
	v_mfma_f32_16x16x32_bf16 v[112:115], v[172:175], v[192:195], v[112:115]
	v_mfma_f32_16x16x32_bf16 v[104:107], v[184:187], v[192:195], v[104:107]
	v_mfma_f32_16x16x32_bf16 v[88:91], v[184:187], v[200:203], v[88:91]
	v_mfma_f32_16x16x32_bf16 v[96:99], v[172:175], v[200:203], v[96:99]
	v_mfma_f32_16x16x32_bf16 v[80:83], v[172:175], v[208:211], v[80:83]
	v_mfma_f32_16x16x32_bf16 v[72:75], v[184:187], v[208:211], v[72:75]
	v_mfma_f32_16x16x32_bf16 v[64:67], v[184:187], v[216:219], v[64:67]
	v_mfma_f32_16x16x32_bf16 v[68:71], v[172:175], v[216:219], v[68:71]
	s_setprio 0
	s_barrier
; #define PG8_STAGE(bufoff, gbase, voff) do { _Pragma("unroll") for (int _i = 0; _i < 2; ++_i) \
;         __builtin_amdgcn_global_load_lds((const unsigned*)((const char*)(gbase) + (voff)[_i]), (PG8_LAS unsigned*)(lds + (bufoff) + ldsw + _i * 8192), 16, 0, 0); } while (0)
; #define PG8_LDA(dst, b, h) do { _Pragma("unroll") for (int m = 0; m < 4; ++m) _Pragma("unroll") for (int k = 0; k < 2; ++k) dst[m][k] = *(const PG8_LAS bf16x8*)(lds + PG8_SA(b, h) + aoff + m * 2048 + k * 1024); } while (0)
; #define PG8_MMA(ai, bj, At, Bt) do { __builtin_amdgcn_s_setprio(1); _Pragma("unroll") for (int m = 0; m < 4; ++m) _Pragma("unroll") for (int n = 0; n < 2; ++n) _Pragma("unroll") for (int k = 0; k < 2; ++k) \
;         acc[ai][bj][m][n] = __builtin_amdgcn_mfma_f32_16x16x32_bf16(Bt[n][k], At[m][k], acc[ai][bj][m][n], 0, 0, 0); __builtin_amdgcn_s_setprio(0); } while (0)
; #define PG8_WAIT_V(n) asm volatile("s_waitcnt vmcnt(" #n ")" ::: "memory")
; #define PG8_WAIT_L(n) asm volatile("s_waitcnt lgkmcnt(" #n ")" ::: "memory")
; #define PG8_BAR __builtin_amdgcn_s_barrier()
; #define PG8_SCHED __builtin_amdgcn_sched_barrier(0)
; template <class Epi, class Sched, bool ALIGN_EPI = false, bool SP2 = false>
; __device__ __forceinline__ void gemm_phase(PG8_LAS unsigned char* lds, const Gemm g, const Sched& S, const Epi& E) {
;     ...
;         for (int t = 0; t < nt; t += 2) {
;             const bool last = (t == nt - 2);
;             const char* a1 = cA + (size_t)(t + 1) * kstep;
;             const char* a2 = last ? nA : cA + (size_t)(t + 2) * kstep; const char* b2 = last ? nB : cB + (size_t)(t + 2) * kstep;
;             const char* a3 = a2 + kstep; const char* b3 = b2 + kstep;
;     ...
;             PG8_LDA(At, 1, 1); PG8_STAGE(PG8_SB(1, 0), b3, voffB); PG8_STAGE(PG8_SB(1, 1), b3 + hstep, voffB); PG8_STAGE(PG8_SA(1, 0), a3, voffA);
;             PG8_WAIT_V(8); PG8_WAIT_L(0); PG8_BAR; PG8_MMA(1, 0, At, B0); PG8_MMA(1, 1, At, B1); PG8_BAR; PG8_SCHED;
	s_add_i32 s14, s14, s63
	v_lshl_add_u64 v[180:181], v[180:181], 0, s[36:37]
	s_mov_b32 m0, s14
	ds_read_b128 v[188:191], v171 offset:49152
	ds_read_b128 v[192:195], v171 offset:50176
	ds_read_b128 v[196:199], v171 offset:51200
	ds_read_b128 v[200:203], v171 offset:52224
	ds_read_b128 v[204:207], v171 offset:53248
	ds_read_b128 v[208:211], v171 offset:54272
	ds_read_b128 v[212:215], v171 offset:55296
	ds_read_b128 v[216:219], v171 offset:56320
	global_load_lds_dwordx4 v[180:181], off
	s_add_i32 m0, s14, 0x2000
	s_add_u32 s34, s56, 0x40080
	v_lshl_add_u64 v[180:181], v[220:221], 0, s[36:37]
	s_addc_u32 s35, s57, 0
	s_add_i32 s14, s15, s63
	global_load_lds_dwordx4 v[180:181], off
	v_lshl_add_u64 v[180:181], s[34:35], 0, v[146:147]
	s_mov_b32 m0, s14
	s_nop 0
	global_load_lds_dwordx4 v[180:181], off
	v_lshl_add_u64 v[180:181], s[34:35], 0, v[150:151]
	s_add_i32 m0, s14, 0x2000
	s_nop 0
	global_load_lds_dwordx4 v[180:181], off
	v_lshl_add_u64 v[180:181], v[222:223], 0, s[36:37]
	s_mov_b32 m0, s74
	s_nop 0
	global_load_lds_dwordx4 v[180:181], off
	v_lshl_add_u64 v[180:181], v[224:225], 0, s[36:37]
	s_mov_b32 m0, s75
	s_nop 0
	global_load_lds_dwordx4 v[180:181], off
	s_waitcnt vmcnt(8)
	s_waitcnt lgkmcnt(0)
	s_barrier
	s_setprio 1
	s_waitcnt lgkmcnt(0)
	v_mfma_f32_16x16x32_bf16 v[60:63], v[128:131], v[188:191], v[60:63]
	v_mfma_f32_16x16x32_bf16 v[56:59], v[136:139], v[188:191], v[56:59]
	v_mfma_f32_16x16x32_bf16 v[44:47], v[136:139], v[196:199], v[44:47]
	v_mfma_f32_16x16x32_bf16 v[48:51], v[128:131], v[196:199], v[48:51]
	v_mfma_f32_16x16x32_bf16 v[36:39], v[128:131], v[204:207], v[36:39]
	v_mfma_f32_16x16x32_bf16 v[28:31], v[136:139], v[204:207], v[28:31]
	v_mfma_f32_16x16x32_bf16 v[12:15], v[136:139], v[212:215], v[12:15]
	v_mfma_f32_16x16x32_bf16 v[20:23], v[128:131], v[212:215], v[20:23]
	v_mfma_f32_16x16x32_bf16 v[60:63], v[132:135], v[192:195], v[60:63]
	v_mfma_f32_16x16x32_bf16 v[56:59], v[140:143], v[192:195], v[56:59]
	v_mfma_f32_16x16x32_bf16 v[44:47], v[140:143], v[200:203], v[44:47]
	v_mfma_f32_16x16x32_bf16 v[48:51], v[132:135], v[200:203], v[48:51]
	v_mfma_f32_16x16x32_bf16 v[36:39], v[132:135], v[208:211], v[36:39]
	v_mfma_f32_16x16x32_bf16 v[28:31], v[140:143], v[208:211], v[28:31]
	v_mfma_f32_16x16x32_bf16 v[12:15], v[140:143], v[216:219], v[12:15]
	v_mfma_f32_16x16x32_bf16 v[20:23], v[132:135], v[216:219], v[20:23]
	s_setprio 0
	s_setprio 1
	v_mfma_f32_16x16x32_bf16 v[52:55], v[162:165], v[188:191], v[52:55]
	v_mfma_f32_16x16x32_bf16 v[40:43], v[176:179], v[188:191], v[40:43]
	v_mfma_f32_16x16x32_bf16 v[24:27], v[176:179], v[196:199], v[24:27]
	v_mfma_f32_16x16x32_bf16 v[32:35], v[162:165], v[196:199], v[32:35]
	v_mfma_f32_16x16x32_bf16 v[16:19], v[162:165], v[204:207], v[16:19]
	v_mfma_f32_16x16x32_bf16 v[8:11], v[176:179], v[204:207], v[8:11]
	v_mfma_f32_16x16x32_bf16 v[0:3], v[176:179], v[212:215], v[0:3]
	v_mfma_f32_16x16x32_bf16 v[4:7], v[162:165], v[212:215], v[4:7]
	v_mfma_f32_16x16x32_bf16 v[52:55], v[172:175], v[192:195], v[52:55]
	v_mfma_f32_16x16x32_bf16 v[40:43], v[184:187], v[192:195], v[40:43]
	v_mfma_f32_16x16x32_bf16 v[24:27], v[184:187], v[200:203], v[24:27]
	v_mfma_f32_16x16x32_bf16 v[32:35], v[172:175], v[200:203], v[32:35]
	v_mfma_f32_16x16x32_bf16 v[16:19], v[172:175], v[208:211], v[16:19]
	v_mfma_f32_16x16x32_bf16 v[8:11], v[184:187], v[208:211], v[8:11]
	v_mfma_f32_16x16x32_bf16 v[0:3], v[184:187], v[216:219], v[0:3]
	v_mfma_f32_16x16x32_bf16 v[4:7], v[172:175], v[216:219], v[4:7]
	s_setprio 0
	s_barrier
	s_add_i32 s84, s84, 2
	s_add_u32 s82, s82, 0x100
	s_addc_u32 s83, s83, 0
	s_add_u32 s54, s54, 0x100
	s_addc_u32 s55, s55, 0
	s_cmp_gt_u32 s84, 13
	s_cbranch_scc0 .LBB0_710
	s_and_b64 vcc, exec, s[40:41]
	s_cbranch_vccz .LBB0_713
	s_barrier

; #define PG8_STAGE(bufoff, gbase, voff) do { _Pragma("unroll") for (int _i = 0; _i < 2; ++_i) \
;         __builtin_amdgcn_global_load_lds((const unsigned*)((const char*)(gbase) + (voff)[_i]), (PG8_LAS unsigned*)(lds + (bufoff) + ldsw + _i * 8192), 16, 0, 0); } while (0)
; #define PG8_LDA(dst, b, h) do { _Pragma("unroll") for (int m = 0; m < 4; ++m) _Pragma("unroll") for (int k = 0; k < 2; ++k) dst[m][k] = *(const PG8_LAS bf16x8*)(lds + PG8_SA(b, h) + aoff + m * 2048 + k * 1024); } while (0)
; #define PG8_LDB(dst, b, h) do { _Pragma("unroll") for (int n = 0; n < 2; ++n) _Pragma("unroll") for (int k = 0; k < 2; ++k) dst[n][k] = *(const PG8_LAS bf16x8*)(lds + PG8_SB(b, h) + boff + n * 2048 + k * 1024); } while (0)
; #define PG8_MMA(ai, bj, At, Bt) do { __builtin_amdgcn_s_setprio(1); _Pragma("unroll") for (int m = 0; m < 4; ++m) _Pragma("unroll") for (int n = 0; n < 2; ++n) _Pragma("unroll") for (int k = 0; k < 2; ++k) \
;         acc[ai][bj][m][n] = __builtin_amdgcn_mfma_f32_16x16x32_bf16(Bt[n][k], At[m][k], acc[ai][bj][m][n], 0, 0, 0); __builtin_amdgcn_s_setprio(0); } while (0)
; #define PG8_WAIT_V(n) asm volatile("s_waitcnt vmcnt(" #n ")" ::: "memory")
; #define PG8_WAIT_L(n) asm volatile("s_waitcnt lgkmcnt(" #n ")" ::: "memory")
; #define PG8_BAR __builtin_amdgcn_s_barrier()
; #define PG8_SCHED __builtin_amdgcn_sched_barrier(0)
; template <class Epi, class Sched, bool ALIGN_EPI = false, bool SP2 = false>
; __device__ __forceinline__ void gemm_phase(PG8_LAS unsigned char* lds, const Gemm g, const Sched& S, const Epi& E) {
;     ...
;             PG8_LDB(B0, 0, 0); PG8_LDB(B1, 0, 1); PG8_SCHED; PG8_LDA(At, 0, 0); PG8_STAGE(PG8_SA(1, 1), a1 + hstep, voffA);
;             PG8_WAIT_V(8); PG8_WAIT_L(0); PG8_BAR; PG8_MMA(0, 0, At, B0); PG8_MMA(0, 1, At, B1); PG8_BAR; PG8_SCHED;
;             PG8_LDA(At, 0, 1); PG8_STAGE(PG8_SB(0, 0), b2, voffB); PG8_STAGE(PG8_SB(0, 1), b2 + hstep, voffB); PG8_STAGE(PG8_SA(0, 0), a2, voffA);
.LBB0_796:
	v_add_u32_e32 v130, s76, v165
	ds_read_b128 v[118:121], v130
	ds_read_b128 v[122:125], v130 offset:1024
	ds_read_b128 v[126:129], v130 offset:2048
	ds_read_b128 v[172:175], v130 offset:3072
	v_add_u32_e32 v130, s77, v165
	ds_read_b128 v[176:179], v130
	ds_read_b128 v[184:187], v130 offset:1024
	ds_read_b128 v[188:191], v130 offset:2048
	ds_read_b128 v[192:195], v130 offset:3072
	s_add_u32 s12, s52, 0xfffc0080
	s_addc_u32 s13, s53, -1
	s_and_b64 s[34:35], s[54:55], exec
	s_cselect_b32 s57, s43, s13
	s_cselect_b32 s56, s78, s12
	s_cselect_b32 s55, s41, s51
	s_cselect_b32 s54, s79, s49
	v_lshl_add_u64 v[130:131], s[52:53], 0, v[154:155]
	s_add_i32 m0, s62, 0xc000
	ds_read_b128 v[196:199], v170
	ds_read_b128 v[200:203], v170 offset:1024
	ds_read_b128 v[204:207], v170 offset:2048
	ds_read_b128 v[208:211], v170 offset:3072
	ds_read_b128 v[212:215], v170 offset:4096
	ds_read_b128 v[216:219], v170 offset:5120
	ds_read_b128 v[220:223], v170 offset:6144
	ds_read_b128 v[224:227], v170 offset:7168
	global_load_lds_dwordx4 v[130:131], off
	v_lshl_add_u64 v[130:131], s[52:53], 0, v[152:153]
	s_add_i32 m0, s62, 0xe000
	s_nop 0
	global_load_lds_dwordx4 v[130:131], off
	s_waitcnt vmcnt(8)
	s_waitcnt lgkmcnt(0)
	s_barrier
	s_setprio 1
	s_waitcnt lgkmcnt(0)
	v_mfma_f32_16x16x32_bf16 v[140:143], v[118:121], v[196:199], v[140:143]
	v_mfma_f32_16x16x32_bf16 v[136:139], v[126:129], v[196:199], v[136:139]
	v_mfma_f32_16x16x32_bf16 v[104:107], v[126:129], v[204:207], v[104:107]
	v_mfma_f32_16x16x32_bf16 v[108:111], v[118:121], v[204:207], v[108:111]
	v_mfma_f32_16x16x32_bf16 v[92:95], v[118:121], v[212:215], v[92:95]
	v_mfma_f32_16x16x32_bf16 v[88:91], v[126:129], v[212:215], v[88:91]
	v_mfma_f32_16x16x32_bf16 v[72:75], v[126:129], v[220:223], v[72:75]
	v_mfma_f32_16x16x32_bf16 v[76:79], v[118:121], v[220:223], v[76:79]
	v_mfma_f32_16x16x32_bf16 v[140:143], v[122:125], v[200:203], v[140:143]
	v_mfma_f32_16x16x32_bf16 v[136:139], v[172:175], v[200:203], v[136:139]
	v_mfma_f32_16x16x32_bf16 v[104:107], v[172:175], v[208:211], v[104:107]
	v_mfma_f32_16x16x32_bf16 v[108:111], v[122:125], v[208:211], v[108:111]
	v_mfma_f32_16x16x32_bf16 v[92:95], v[122:125], v[216:219], v[92:95]
	v_mfma_f32_16x16x32_bf16 v[88:91], v[172:175], v[216:219], v[88:91]
	v_mfma_f32_16x16x32_bf16 v[72:75], v[172:175], v[224:227], v[72:75]
	v_mfma_f32_16x16x32_bf16 v[76:79], v[122:125], v[224:227], v[76:79]
	s_setprio 0
	s_setprio 1
	v_mfma_f32_16x16x32_bf16 v[130:133], v[176:179], v[196:199], v[132:135]
	v_mfma_f32_16x16x32_bf16 v[112:115], v[188:191], v[196:199], v[112:115]
	v_mfma_f32_16x16x32_bf16 v[96:99], v[188:191], v[204:207], v[96:99]
	v_mfma_f32_16x16x32_bf16 v[100:103], v[176:179], v[204:207], v[100:103]
	v_mfma_f32_16x16x32_bf16 v[84:87], v[176:179], v[212:215], v[84:87]
	v_mfma_f32_16x16x32_bf16 v[80:83], v[188:191], v[212:215], v[80:83]
	v_mfma_f32_16x16x32_bf16 v[64:67], v[188:191], v[220:223], v[64:67]
	v_mfma_f32_16x16x32_bf16 v[68:71], v[176:179], v[220:223], v[68:71]
	v_mfma_f32_16x16x32_bf16 v[130:133], v[184:187], v[200:203], v[130:133]
	v_mfma_f32_16x16x32_bf16 v[112:115], v[192:195], v[200:203], v[112:115]
	v_mfma_f32_16x16x32_bf16 v[96:99], v[192:195], v[208:211], v[96:99]
	v_mfma_f32_16x16x32_bf16 v[100:103], v[184:187], v[208:211], v[100:103]
	v_mfma_f32_16x16x32_bf16 v[84:87], v[184:187], v[216:219], v[84:87]
	v_mfma_f32_16x16x32_bf16 v[80:83], v[192:195], v[216:219], v[80:83]
	v_mfma_f32_16x16x32_bf16 v[64:67], v[192:195], v[224:227], v[64:67]
	v_mfma_f32_16x16x32_bf16 v[68:71], v[184:187], v[224:227], v[68:71]
	s_setprio 0
	s_barrier
	s_add_i32 s12, s76, s59
	v_lshl_add_u64 v[180:181], s[54:55], 0, v[148:149]
	s_mov_b32 m0, s12
	ds_read_b128 v[196:199], v170 offset:16384
	ds_read_b128 v[200:203], v170 offset:17408
	ds_read_b128 v[204:207], v170 offset:18432
	ds_read_b128 v[208:211], v170 offset:19456
	ds_read_b128 v[212:215], v170 offset:20480
	ds_read_b128 v[216:219], v170 offset:21504
	ds_read_b128 v[220:223], v170 offset:22528
	ds_read_b128 v[224:227], v170 offset:23552
	global_load_lds_dwordx4 v[180:181], off
	s_add_i32 m0, s12, 0x2000
	s_add_u32 s34, s54, 0x40000
	v_lshl_add_u64 v[228:229], s[54:55], 0, v[144:145]
	s_addc_u32 s35, s55, 0
	s_add_i32 s12, s77, s59
	global_load_lds_dwordx4 v[228:229], off
	v_lshl_add_u64 v[134:135], s[34:35], 0, v[148:149]
	s_mov_b32 m0, s12
	v_lshl_add_u64 v[230:231], s[56:57], 0, v[150:151]
	global_load_lds_dwordx4 v[134:135], off
	v_lshl_add_u64 v[134:135], s[34:35], 0, v[144:145]
	s_add_i32 m0, s12, 0x2000
	v_lshl_add_u64 v[232:233], s[56:57], 0, v[146:147]
	global_load_lds_dwordx4 v[134:135], off
	s_mov_b32 m0, s62
	s_nop 0
	global_load_lds_dwordx4 v[230:231], off
	s_mov_b32 m0, s63
	s_nop 0
	global_load_lds_dwordx4 v[232:233], off
	s_waitcnt vmcnt(8)
	s_waitcnt lgkmcnt(0)
	s_barrier
; #define PG8_STAGE(bufoff, gbase, voff) do { _Pragma("unroll") for (int _i = 0; _i < 2; ++_i) \
;         __builtin_amdgcn_global_load_lds((const unsigned*)((const char*)(gbase) + (voff)[_i]), (PG8_LAS unsigned*)(lds + (bufoff) + ldsw + _i * 8192), 16, 0, 0); } while (0)
; #define PG8_LDA(dst, b, h) do { _Pragma("unroll") for (int m = 0; m < 4; ++m) _Pragma("unroll") for (int k = 0; k < 2; ++k) dst[m][k] = *(const PG8_LAS bf16x8*)(lds + PG8_SA(b, h) + aoff + m * 2048 + k * 1024); } while (0)
; #define PG8_LDB(dst, b, h) do { _Pragma("unroll") for (int n = 0; n < 2; ++n) _Pragma("unroll") for (int k = 0; k < 2; ++k) dst[n][k] = *(const PG8_LAS bf16x8*)(lds + PG8_SB(b, h) + boff + n * 2048 + k * 1024); } while (0)
; #define PG8_MMA(ai, bj, At, Bt) do { __builtin_amdgcn_s_setprio(1); _Pragma("unroll") for (int m = 0; m < 4; ++m) _Pragma("unroll") for (int n = 0; n < 2; ++n) _Pragma("unroll") for (int k = 0; k < 2; ++k) \
;         acc[ai][bj][m][n] = __builtin_amdgcn_mfma_f32_16x16x32_bf16(Bt[n][k], At[m][k], acc[ai][bj][m][n], 0, 0, 0); __builtin_amdgcn_s_setprio(0); } while (0)
; #define PG8_WAIT_V(n) asm volatile("s_waitcnt vmcnt(" #n ")" ::: "memory")
; #define PG8_WAIT_L(n) asm volatile("s_waitcnt lgkmcnt(" #n ")" ::: "memory")
; #define PG8_BAR __builtin_amdgcn_s_barrier()
; #define PG8_SCHED __builtin_amdgcn_sched_barrier(0)
; template <class Epi, class Sched, bool ALIGN_EPI = false, bool SP2 = false>
; __device__ __forceinline__ void gemm_phase(PG8_LAS unsigned char* lds, const Gemm g, const Sched& S, const Epi& E) {
;     ...
;             PG8_WAIT_V(8); PG8_WAIT_L(0); PG8_BAR; PG8_MMA(1, 0, At, B0); PG8_MMA(1, 1, At, B1); PG8_BAR; PG8_SCHED;
;             PG8_LDB(B0, 1, 0); PG8_LDB(B1, 1, 1); PG8_SCHED; PG8_LDA(At, 1, 0); PG8_STAGE(PG8_SA(0, 1), a2 + hstep, voffA);
;             PG8_WAIT_V(8); PG8_WAIT_L(0); PG8_BAR; PG8_MMA(0, 0, At, B0); PG8_MMA(0, 1, At, B1); PG8_BAR; PG8_SCHED;
	s_setprio 1
	s_waitcnt lgkmcnt(0)
	v_mfma_f32_16x16x32_bf16 v[60:63], v[118:121], v[196:199], v[60:63]
	v_mfma_f32_16x16x32_bf16 v[56:59], v[126:129], v[196:199], v[56:59]
	v_mfma_f32_16x16x32_bf16 v[40:43], v[126:129], v[204:207], v[40:43]
	v_mfma_f32_16x16x32_bf16 v[44:47], v[118:121], v[204:207], v[44:47]
	v_mfma_f32_16x16x32_bf16 v[28:31], v[118:121], v[212:215], v[28:31]
	v_mfma_f32_16x16x32_bf16 v[24:27], v[126:129], v[212:215], v[24:27]
	v_mfma_f32_16x16x32_bf16 v[8:11], v[126:129], v[220:223], v[8:11]
	v_mfma_f32_16x16x32_bf16 v[12:15], v[118:121], v[220:223], v[12:15]
	v_mfma_f32_16x16x32_bf16 v[60:63], v[122:125], v[200:203], v[60:63]
	v_mfma_f32_16x16x32_bf16 v[56:59], v[172:175], v[200:203], v[56:59]
	v_mfma_f32_16x16x32_bf16 v[40:43], v[172:175], v[208:211], v[40:43]
	v_mfma_f32_16x16x32_bf16 v[44:47], v[122:125], v[208:211], v[44:47]
	v_mfma_f32_16x16x32_bf16 v[28:31], v[122:125], v[216:219], v[28:31]
	v_mfma_f32_16x16x32_bf16 v[24:27], v[172:175], v[216:219], v[24:27]
	v_mfma_f32_16x16x32_bf16 v[8:11], v[172:175], v[224:227], v[8:11]
	v_mfma_f32_16x16x32_bf16 v[12:15], v[122:125], v[224:227], v[12:15]
	s_setprio 0
	s_setprio 1
	v_mfma_f32_16x16x32_bf16 v[52:55], v[176:179], v[196:199], v[52:55]
	v_mfma_f32_16x16x32_bf16 v[48:51], v[188:191], v[196:199], v[48:51]
	v_mfma_f32_16x16x32_bf16 v[32:35], v[188:191], v[204:207], v[32:35]
	v_mfma_f32_16x16x32_bf16 v[36:39], v[176:179], v[204:207], v[36:39]
	v_mfma_f32_16x16x32_bf16 v[20:23], v[176:179], v[212:215], v[20:23]
	v_mfma_f32_16x16x32_bf16 v[16:19], v[188:191], v[212:215], v[16:19]
	v_mfma_f32_16x16x32_bf16 v[0:3], v[188:191], v[220:223], v[0:3]
	v_mfma_f32_16x16x32_bf16 v[4:7], v[176:179], v[220:223], v[4:7]
	v_mfma_f32_16x16x32_bf16 v[52:55], v[184:187], v[200:203], v[52:55]
	v_mfma_f32_16x16x32_bf16 v[48:51], v[192:195], v[200:203], v[48:51]
	v_mfma_f32_16x16x32_bf16 v[32:35], v[192:195], v[208:211], v[32:35]
	v_mfma_f32_16x16x32_bf16 v[36:39], v[184:187], v[208:211], v[36:39]
	v_mfma_f32_16x16x32_bf16 v[20:23], v[184:187], v[216:219], v[20:23]
	v_mfma_f32_16x16x32_bf16 v[16:19], v[192:195], v[216:219], v[16:19]
	v_mfma_f32_16x16x32_bf16 v[0:3], v[192:195], v[224:227], v[0:3]
	v_mfma_f32_16x16x32_bf16 v[4:7], v[184:187], v[224:227], v[4:7]
	s_setprio 0
	s_barrier
	s_add_i32 s12, 0, 0x18000
	v_add_u32_e32 v134, s12, v165
	s_add_i32 s13, 0, 0x1c000
	ds_read_b128 v[118:121], v134
	ds_read_b128 v[122:125], v134 offset:1024
	ds_read_b128 v[126:129], v134 offset:2048
	ds_read_b128 v[172:175], v134 offset:3072
	v_add_u32_e32 v134, s13, v165
	ds_read_b128 v[176:179], v134
	ds_read_b128 v[184:187], v134 offset:1024
	ds_read_b128 v[188:191], v134 offset:2048
	ds_read_b128 v[192:195], v134 offset:3072
	s_add_u32 s34, s56, 0x40000
	s_addc_u32 s35, s57, 0
	s_mov_b32 m0, s64
	v_lshl_add_u64 v[134:135], s[34:35], 0, v[150:151]
	ds_read_b128 v[196:199], v170 offset:32768
	ds_read_b128 v[200:203], v170 offset:33792
	ds_read_b128 v[204:207], v170 offset:34816
	ds_read_b128 v[208:211], v170 offset:35840
	ds_read_b128 v[212:215], v170 offset:36864
	ds_read_b128 v[216:219], v170 offset:37888
	ds_read_b128 v[220:223], v170 offset:38912
	ds_read_b128 v[224:227], v170 offset:39936
	global_load_lds_dwordx4 v[134:135], off
	v_lshl_add_u64 v[134:135], s[34:35], 0, v[146:147]
	s_mov_b32 m0, s65
	s_nop 0
	global_load_lds_dwordx4 v[134:135], off
	s_waitcnt vmcnt(8)
	s_waitcnt lgkmcnt(0)
	s_barrier
	s_setprio 1
	s_waitcnt lgkmcnt(0)
	v_mfma_f32_16x16x32_bf16 v[140:143], v[118:121], v[196:199], v[140:143]
	v_mfma_f32_16x16x32_bf16 v[134:137], v[126:129], v[196:199], v[136:139]
	v_mfma_f32_16x16x32_bf16 v[104:107], v[126:129], v[204:207], v[104:107]
	v_mfma_f32_16x16x32_bf16 v[108:111], v[118:121], v[204:207], v[108:111]
	v_mfma_f32_16x16x32_bf16 v[92:95], v[118:121], v[212:215], v[92:95]
	v_mfma_f32_16x16x32_bf16 v[88:91], v[126:129], v[212:215], v[88:91]
	v_mfma_f32_16x16x32_bf16 v[72:75], v[126:129], v[220:223], v[72:75]
	v_mfma_f32_16x16x32_bf16 v[76:79], v[118:121], v[220:223], v[76:79]
	v_mfma_f32_16x16x32_bf16 v[140:143], v[122:125], v[200:203], v[140:143]
	v_mfma_f32_16x16x32_bf16 v[136:139], v[172:175], v[200:203], v[134:137]
	v_mfma_f32_16x16x32_bf16 v[104:107], v[172:175], v[208:211], v[104:107]
	v_mfma_f32_16x16x32_bf16 v[108:111], v[122:125], v[208:211], v[108:111]
	v_mfma_f32_16x16x32_bf16 v[92:95], v[122:125], v[216:219], v[92:95]
	v_mfma_f32_16x16x32_bf16 v[88:91], v[172:175], v[216:219], v[88:91]
	v_mfma_f32_16x16x32_bf16 v[72:75], v[172:175], v[224:227], v[72:75]
	v_mfma_f32_16x16x32_bf16 v[76:79], v[122:125], v[224:227], v[76:79]
	s_setprio 0
	s_setprio 1
	v_mfma_f32_16x16x32_bf16 v[130:133], v[176:179], v[196:199], v[130:133]
	v_mfma_f32_16x16x32_bf16 v[112:115], v[188:191], v[196:199], v[112:115]
	v_mfma_f32_16x16x32_bf16 v[96:99], v[188:191], v[204:207], v[96:99]
	v_mfma_f32_16x16x32_bf16 v[100:103], v[176:179], v[204:207], v[100:103]
	v_mfma_f32_16x16x32_bf16 v[84:87], v[176:179], v[212:215], v[84:87]
	v_mfma_f32_16x16x32_bf16 v[80:83], v[188:191], v[212:215], v[80:83]
	v_mfma_f32_16x16x32_bf16 v[64:67], v[188:191], v[220:223], v[64:67]
	v_mfma_f32_16x16x32_bf16 v[68:71], v[176:179], v[220:223], v[68:71]
	v_mfma_f32_16x16x32_bf16 v[132:135], v[184:187], v[200:203], v[130:133]
	v_mfma_f32_16x16x32_bf16 v[112:115], v[192:195], v[200:203], v[112:115]
	v_mfma_f32_16x16x32_bf16 v[96:99], v[192:195], v[208:211], v[96:99]
	v_mfma_f32_16x16x32_bf16 v[100:103], v[184:187], v[208:211], v[100:103]
	v_mfma_f32_16x16x32_bf16 v[84:87], v[184:187], v[216:219], v[84:87]
	v_mfma_f32_16x16x32_bf16 v[80:83], v[192:195], v[216:219], v[80:83]
	v_mfma_f32_16x16x32_bf16 v[64:67], v[192:195], v[224:227], v[64:67]
	v_mfma_f32_16x16x32_bf16 v[68:71], v[184:187], v[224:227], v[68:71]
	s_setprio 0
	s_barrier
; #define PG8_STAGE(bufoff, gbase, voff) do { _Pragma("unroll") for (int _i = 0; _i < 2; ++_i) \
;         __builtin_amdgcn_global_load_lds((const unsigned*)((const char*)(gbase) + (voff)[_i]), (PG8_LAS unsigned*)(lds + (bufoff) + ldsw + _i * 8192), 16, 0, 0); } while (0)
; #define PG8_LDA(dst, b, h) do { _Pragma("unroll") for (int m = 0; m < 4; ++m) _Pragma("unroll") for (int k = 0; k < 2; ++k) dst[m][k] = *(const PG8_LAS bf16x8*)(lds + PG8_SA(b, h) + aoff + m * 2048 + k * 1024); } while (0)
; #define PG8_MMA(ai, bj, At, Bt) do { __builtin_amdgcn_s_setprio(1); _Pragma("unroll") for (int m = 0; m < 4; ++m) _Pragma("unroll") for (int n = 0; n < 2; ++n) _Pragma("unroll") for (int k = 0; k < 2; ++k) \
;         acc[ai][bj][m][n] = __builtin_amdgcn_mfma_f32_16x16x32_bf16(Bt[n][k], At[m][k], acc[ai][bj][m][n], 0, 0, 0); __builtin_amdgcn_s_setprio(0); } while (0)
; #define PG8_WAIT_V(n) asm volatile("s_waitcnt vmcnt(" #n ")" ::: "memory")
; #define PG8_WAIT_L(n) asm volatile("s_waitcnt lgkmcnt(" #n ")" ::: "memory")
; #define PG8_BAR __builtin_amdgcn_s_barrier()
; #define PG8_SCHED __builtin_amdgcn_sched_barrier(0)
; template <class Epi, class Sched, bool ALIGN_EPI = false, bool SP2 = false>
; __device__ __forceinline__ void gemm_phase(PG8_LAS unsigned char* lds, const Gemm g, const Sched& S, const Epi& E) {
;     ...
;         for (int t = 0; t < nt; t += 2) {
;             const bool last = (t == nt - 2);
;             const char* a1 = cA + (size_t)(t + 1) * kstep;
;             const char* a2 = last ? nA : cA + (size_t)(t + 2) * kstep; const char* b2 = last ? nB : cB + (size_t)(t + 2) * kstep;
;             const char* a3 = a2 + kstep; const char* b3 = b2 + kstep;
;     ...
;             PG8_LDA(At, 1, 1); PG8_STAGE(PG8_SB(1, 0), b3, voffB); PG8_STAGE(PG8_SB(1, 1), b3 + hstep, voffB); PG8_STAGE(PG8_SA(1, 0), a3, voffA);
;             PG8_WAIT_V(8); PG8_WAIT_L(0); PG8_BAR; PG8_MMA(1, 0, At, B0); PG8_MMA(1, 1, At, B1); PG8_BAR; PG8_SCHED;
	s_add_i32 s12, s12, s59
	v_lshl_add_u64 v[130:131], v[180:181], 0, s[18:19]
	s_mov_b32 m0, s12
	ds_read_b128 v[196:199], v170 offset:49152
	ds_read_b128 v[200:203], v170 offset:50176
	ds_read_b128 v[204:207], v170 offset:51200
	ds_read_b128 v[208:211], v170 offset:52224
	ds_read_b128 v[212:215], v170 offset:53248
	ds_read_b128 v[216:219], v170 offset:54272
	ds_read_b128 v[220:223], v170 offset:55296
	ds_read_b128 v[224:227], v170 offset:56320
	global_load_lds_dwordx4 v[130:131], off
	s_add_i32 m0, s12, 0x2000
	s_add_u32 s34, s54, 0x40080
	v_lshl_add_u64 v[130:131], v[228:229], 0, s[18:19]
	s_addc_u32 s35, s55, 0
	s_add_i32 s12, s13, s59
	global_load_lds_dwordx4 v[130:131], off
	v_lshl_add_u64 v[130:131], s[34:35], 0, v[148:149]
	s_mov_b32 m0, s12
	s_nop 0
	global_load_lds_dwordx4 v[130:131], off
	v_lshl_add_u64 v[130:131], s[34:35], 0, v[144:145]
	s_add_i32 m0, s12, 0x2000
	s_nop 0
	global_load_lds_dwordx4 v[130:131], off
	v_lshl_add_u64 v[130:131], v[230:231], 0, s[18:19]
	s_mov_b32 m0, s68
	s_nop 0
	global_load_lds_dwordx4 v[130:131], off
	v_lshl_add_u64 v[130:131], v[232:233], 0, s[18:19]
	s_mov_b32 m0, s69
	s_nop 0
	global_load_lds_dwordx4 v[130:131], off
	s_waitcnt vmcnt(8)
	s_waitcnt lgkmcnt(0)
	s_barrier
	s_setprio 1
	s_waitcnt lgkmcnt(0)
	v_mfma_f32_16x16x32_bf16 v[60:63], v[118:121], v[196:199], v[60:63]
	v_mfma_f32_16x16x32_bf16 v[56:59], v[126:129], v[196:199], v[56:59]
	v_mfma_f32_16x16x32_bf16 v[40:43], v[126:129], v[204:207], v[40:43]
	v_mfma_f32_16x16x32_bf16 v[44:47], v[118:121], v[204:207], v[44:47]
	v_mfma_f32_16x16x32_bf16 v[28:31], v[118:121], v[212:215], v[28:31]
	v_mfma_f32_16x16x32_bf16 v[24:27], v[126:129], v[212:215], v[24:27]
	v_mfma_f32_16x16x32_bf16 v[8:11], v[126:129], v[220:223], v[8:11]
	v_mfma_f32_16x16x32_bf16 v[12:15], v[118:121], v[220:223], v[12:15]
	v_mfma_f32_16x16x32_bf16 v[60:63], v[122:125], v[200:203], v[60:63]
	v_mfma_f32_16x16x32_bf16 v[56:59], v[172:175], v[200:203], v[56:59]
	v_mfma_f32_16x16x32_bf16 v[40:43], v[172:175], v[208:211], v[40:43]
	v_mfma_f32_16x16x32_bf16 v[44:47], v[122:125], v[208:211], v[44:47]
	v_mfma_f32_16x16x32_bf16 v[28:31], v[122:125], v[216:219], v[28:31]
	v_mfma_f32_16x16x32_bf16 v[24:27], v[172:175], v[216:219], v[24:27]
	v_mfma_f32_16x16x32_bf16 v[8:11], v[172:175], v[224:227], v[8:11]
	v_mfma_f32_16x16x32_bf16 v[12:15], v[122:125], v[224:227], v[12:15]
	s_setprio 0
	s_setprio 1
	v_mfma_f32_16x16x32_bf16 v[52:55], v[176:179], v[196:199], v[52:55]
	v_mfma_f32_16x16x32_bf16 v[48:51], v[188:191], v[196:199], v[48:51]
	v_mfma_f32_16x16x32_bf16 v[32:35], v[188:191], v[204:207], v[32:35]
	v_mfma_f32_16x16x32_bf16 v[36:39], v[176:179], v[204:207], v[36:39]
	v_mfma_f32_16x16x32_bf16 v[20:23], v[176:179], v[212:215], v[20:23]
	v_mfma_f32_16x16x32_bf16 v[16:19], v[188:191], v[212:215], v[16:19]
	v_mfma_f32_16x16x32_bf16 v[0:3], v[188:191], v[220:223], v[0:3]
	v_mfma_f32_16x16x32_bf16 v[4:7], v[176:179], v[220:223], v[4:7]
	v_mfma_f32_16x16x32_bf16 v[52:55], v[184:187], v[200:203], v[52:55]
	v_mfma_f32_16x16x32_bf16 v[48:51], v[192:195], v[200:203], v[48:51]
	v_mfma_f32_16x16x32_bf16 v[32:35], v[192:195], v[208:211], v[32:35]
	v_mfma_f32_16x16x32_bf16 v[36:39], v[184:187], v[208:211], v[36:39]
	v_mfma_f32_16x16x32_bf16 v[20:23], v[184:187], v[216:219], v[20:23]
	v_mfma_f32_16x16x32_bf16 v[16:19], v[192:195], v[216:219], v[16:19]
	v_mfma_f32_16x16x32_bf16 v[0:3], v[192:195], v[224:227], v[0:3]
	v_mfma_f32_16x16x32_bf16 v[4:7], v[184:187], v[224:227], v[4:7]
	s_setprio 0
	s_barrier
	s_add_i32 s80, s80, 2
	s_add_u32 s49, s49, 0x100
	s_addc_u32 s51, s51, 0
	s_add_u32 s52, s52, 0x100
	s_addc_u32 s53, s53, 0
	s_cmp_gt_u32 s80, 13
	s_cbranch_scc1 .LBB0_799

; #define PG8_STAGE(bufoff, gbase, voff) do { _Pragma("unroll") for (int _i = 0; _i < 2; ++_i) \
;         __builtin_amdgcn_global_load_lds((const unsigned*)((const char*)(gbase) + (voff)[_i]), (PG8_LAS unsigned*)(lds + (bufoff) + ldsw + _i * 8192), 16, 0, 0); } while (0)
; #define PG8_LDA(dst, b, h) do { _Pragma("unroll") for (int m = 0; m < 4; ++m) _Pragma("unroll") for (int k = 0; k < 2; ++k) dst[m][k] = *(const PG8_LAS bf16x8*)(lds + PG8_SA(b, h) + aoff + m * 2048 + k * 1024); } while (0)
; #define PG8_LDB(dst, b, h) do { _Pragma("unroll") for (int n = 0; n < 2; ++n) _Pragma("unroll") for (int k = 0; k < 2; ++k) dst[n][k] = *(const PG8_LAS bf16x8*)(lds + PG8_SB(b, h) + boff + n * 2048 + k * 1024); } while (0)
; #define PG8_MMA(ai, bj, At, Bt) do { __builtin_amdgcn_s_setprio(1); _Pragma("unroll") for (int m = 0; m < 4; ++m) _Pragma("unroll") for (int n = 0; n < 2; ++n) _Pragma("unroll") for (int k = 0; k < 2; ++k) \
;         acc[ai][bj][m][n] = __builtin_amdgcn_mfma_f32_16x16x32_bf16(Bt[n][k], At[m][k], acc[ai][bj][m][n], 0, 0, 0); __builtin_amdgcn_s_setprio(0); } while (0)
; #define PG8_WAIT_V(n) asm volatile("s_waitcnt vmcnt(" #n ")" ::: "memory")
; #define PG8_WAIT_L(n) asm volatile("s_waitcnt lgkmcnt(" #n ")" ::: "memory")
; #define PG8_BAR __builtin_amdgcn_s_barrier()
; #define PG8_SCHED __builtin_amdgcn_sched_barrier(0)
; template <class Epi, class Sched, bool ALIGN_EPI = false, bool SP2 = false>
; __device__ __forceinline__ void gemm_phase(PG8_LAS unsigned char* lds, const Gemm g, const Sched& S, const Epi& E) {
;     ...
;             PG8_LDB(B0, 0, 0); PG8_LDB(B1, 0, 1); PG8_SCHED; PG8_LDA(At, 0, 0); PG8_STAGE(PG8_SA(1, 1), a1 + hstep, voffA);
;             PG8_WAIT_V(8); PG8_WAIT_L(0); PG8_BAR; PG8_MMA(0, 0, At, B0); PG8_MMA(0, 1, At, B1); PG8_BAR; PG8_SCHED;
;             PG8_LDA(At, 0, 1); PG8_STAGE(PG8_SB(0, 0), b2, voffB); PG8_STAGE(PG8_SB(0, 1), b2 + hstep, voffB); PG8_STAGE(PG8_SA(0, 0), a2, voffA);
.LBB0_872:
	ds_read_b128 v[128:131], v169
	ds_read_b128 v[132:135], v169 offset:1024
	ds_read_b128 v[136:139], v169 offset:2048
	ds_read_b128 v[140:143], v169 offset:3072
	ds_read_b128 v[162:165], v170
	ds_read_b128 v[172:175], v170 offset:1024
	ds_read_b128 v[176:179], v170 offset:2048
	ds_read_b128 v[184:187], v170 offset:3072
	s_add_u32 s42, s40, 0x100
	s_addc_u32 s43, s41, 0
	s_cmp_eq_u32 s74, 40
	s_cselect_b32 s47, s11, s43
	s_cselect_b32 s46, s10, s42
	s_cselect_b32 s45, s37, s73
	s_cselect_b32 s44, s36, s71
	v_lshl_add_u64 v[180:181], s[40:41], 0, v[154:155]
	s_add_i32 m0, s50, 0xc000
	ds_read_b128 v[188:191], v171
	ds_read_b128 v[192:195], v171 offset:1024
	ds_read_b128 v[196:199], v171 offset:2048
	ds_read_b128 v[200:203], v171 offset:3072
	ds_read_b128 v[204:207], v171 offset:4096
	ds_read_b128 v[208:211], v171 offset:5120
	ds_read_b128 v[212:215], v171 offset:6144
	ds_read_b128 v[216:219], v171 offset:7168
	global_load_lds_dwordx4 v[180:181], off
	v_lshl_add_u64 v[180:181], s[40:41], 0, v[152:153]
	s_add_i32 m0, s50, 0xe000
	s_nop 0
	global_load_lds_dwordx4 v[180:181], off
	s_waitcnt vmcnt(8)
	s_waitcnt lgkmcnt(0)
	s_barrier
	s_setprio 1
	s_waitcnt lgkmcnt(0)
	v_mfma_f32_16x16x32_bf16 v[124:127], v[128:131], v[188:191], v[124:127]
	v_mfma_f32_16x16x32_bf16 v[120:123], v[136:139], v[188:191], v[120:123]
	v_mfma_f32_16x16x32_bf16 v[108:111], v[136:139], v[196:199], v[108:111]
	v_mfma_f32_16x16x32_bf16 v[116:119], v[128:131], v[196:199], v[116:119]
	v_mfma_f32_16x16x32_bf16 v[100:103], v[128:131], v[204:207], v[100:103]
	v_mfma_f32_16x16x32_bf16 v[92:95], v[136:139], v[204:207], v[92:95]
	v_mfma_f32_16x16x32_bf16 v[76:79], v[136:139], v[212:215], v[76:79]
	v_mfma_f32_16x16x32_bf16 v[84:87], v[128:131], v[212:215], v[84:87]
	v_mfma_f32_16x16x32_bf16 v[124:127], v[132:135], v[192:195], v[124:127]
	v_mfma_f32_16x16x32_bf16 v[120:123], v[140:143], v[192:195], v[120:123]
	v_mfma_f32_16x16x32_bf16 v[108:111], v[140:143], v[200:203], v[108:111]
	v_mfma_f32_16x16x32_bf16 v[116:119], v[132:135], v[200:203], v[116:119]
	v_mfma_f32_16x16x32_bf16 v[100:103], v[132:135], v[208:211], v[100:103]
	v_mfma_f32_16x16x32_bf16 v[92:95], v[140:143], v[208:211], v[92:95]
	v_mfma_f32_16x16x32_bf16 v[76:79], v[140:143], v[216:219], v[76:79]
	v_mfma_f32_16x16x32_bf16 v[84:87], v[132:135], v[216:219], v[84:87]
	s_setprio 0
	s_setprio 1
	v_mfma_f32_16x16x32_bf16 v[112:115], v[162:165], v[188:191], v[112:115]
	v_mfma_f32_16x16x32_bf16 v[104:107], v[176:179], v[188:191], v[104:107]
	v_mfma_f32_16x16x32_bf16 v[88:91], v[176:179], v[196:199], v[88:91]
	v_mfma_f32_16x16x32_bf16 v[96:99], v[162:165], v[196:199], v[96:99]
	v_mfma_f32_16x16x32_bf16 v[80:83], v[162:165], v[204:207], v[80:83]
	v_mfma_f32_16x16x32_bf16 v[72:75], v[176:179], v[204:207], v[72:75]
	v_mfma_f32_16x16x32_bf16 v[64:67], v[176:179], v[212:215], v[64:67]
	v_mfma_f32_16x16x32_bf16 v[68:71], v[162:165], v[212:215], v[68:71]
	v_mfma_f32_16x16x32_bf16 v[112:115], v[172:175], v[192:195], v[112:115]
	v_mfma_f32_16x16x32_bf16 v[104:107], v[184:187], v[192:195], v[104:107]
	v_mfma_f32_16x16x32_bf16 v[88:91], v[184:187], v[200:203], v[88:91]
	v_mfma_f32_16x16x32_bf16 v[96:99], v[172:175], v[200:203], v[96:99]
	v_mfma_f32_16x16x32_bf16 v[80:83], v[172:175], v[208:211], v[80:83]
	v_mfma_f32_16x16x32_bf16 v[72:75], v[184:187], v[208:211], v[72:75]
	v_mfma_f32_16x16x32_bf16 v[64:67], v[184:187], v[216:219], v[64:67]
	v_mfma_f32_16x16x32_bf16 v[68:71], v[172:175], v[216:219], v[68:71]
	s_setprio 0
	s_barrier
	s_add_i32 s12, s65, s49
	v_lshl_add_u64 v[180:181], s[44:45], 0, v[146:147]
	s_mov_b32 m0, s12
	ds_read_b128 v[188:191], v171 offset:16384
	ds_read_b128 v[192:195], v171 offset:17408
	ds_read_b128 v[196:199], v171 offset:18432
	ds_read_b128 v[200:203], v171 offset:19456
	ds_read_b128 v[204:207], v171 offset:20480
	ds_read_b128 v[208:211], v171 offset:21504
	ds_read_b128 v[212:215], v171 offset:22528
	ds_read_b128 v[216:219], v171 offset:23552
	global_load_lds_dwordx4 v[180:181], off
	s_add_i32 m0, s12, 0x2000
	s_add_u32 s40, s44, 0xb0000
	v_lshl_add_u64 v[220:221], s[44:45], 0, v[150:151]
	s_addc_u32 s41, s45, 0
	s_add_i32 s12, s66, s49
	global_load_lds_dwordx4 v[220:221], off
	v_lshl_add_u64 v[222:223], s[40:41], 0, v[146:147]
	s_mov_b32 m0, s12
	v_lshl_add_u64 v[224:225], s[46:47], 0, v[148:149]
	global_load_lds_dwordx4 v[222:223], off
	v_lshl_add_u64 v[222:223], s[40:41], 0, v[150:151]
	s_add_i32 m0, s12, 0x2000
	s_nop 0
	global_load_lds_dwordx4 v[222:223], off
	v_lshl_add_u64 v[222:223], s[46:47], 0, v[144:145]
	s_mov_b32 m0, s50
	s_nop 0
	global_load_lds_dwordx4 v[222:223], off
	s_mov_b32 m0, s51
	s_nop 0
	global_load_lds_dwordx4 v[224:225], off
	s_waitcnt vmcnt(8)
	s_waitcnt lgkmcnt(0)
	s_barrier
; #define PG8_STAGE(bufoff, gbase, voff) do { _Pragma("unroll") for (int _i = 0; _i < 2; ++_i) \
;         __builtin_amdgcn_global_load_lds((const unsigned*)((const char*)(gbase) + (voff)[_i]), (PG8_LAS unsigned*)(lds + (bufoff) + ldsw + _i * 8192), 16, 0, 0); } while (0)
; #define PG8_LDA(dst, b, h) do { _Pragma("unroll") for (int m = 0; m < 4; ++m) _Pragma("unroll") for (int k = 0; k < 2; ++k) dst[m][k] = *(const PG8_LAS bf16x8*)(lds + PG8_SA(b, h) + aoff + m * 2048 + k * 1024); } while (0)
; #define PG8_LDB(dst, b, h) do { _Pragma("unroll") for (int n = 0; n < 2; ++n) _Pragma("unroll") for (int k = 0; k < 2; ++k) dst[n][k] = *(const PG8_LAS bf16x8*)(lds + PG8_SB(b, h) + boff + n * 2048 + k * 1024); } while (0)
; #define PG8_MMA(ai, bj, At, Bt) do { __builtin_amdgcn_s_setprio(1); _Pragma("unroll") for (int m = 0; m < 4; ++m) _Pragma("unroll") for (int n = 0; n < 2; ++n) _Pragma("unroll") for (int k = 0; k < 2; ++k) \
;         acc[ai][bj][m][n] = __builtin_amdgcn_mfma_f32_16x16x32_bf16(Bt[n][k], At[m][k], acc[ai][bj][m][n], 0, 0, 0); __builtin_amdgcn_s_setprio(0); } while (0)
; #define PG8_WAIT_V(n) asm volatile("s_waitcnt vmcnt(" #n ")" ::: "memory")
; #define PG8_WAIT_L(n) asm volatile("s_waitcnt lgkmcnt(" #n ")" ::: "memory")
; #define PG8_BAR __builtin_amdgcn_s_barrier()
; #define PG8_SCHED __builtin_amdgcn_sched_barrier(0)
; template <class Epi, class Sched, bool ALIGN_EPI = false, bool SP2 = false>
; __device__ __forceinline__ void gemm_phase(PG8_LAS unsigned char* lds, const Gemm g, const Sched& S, const Epi& E) {
;     ...
;             PG8_WAIT_V(8); PG8_WAIT_L(0); PG8_BAR; PG8_MMA(1, 0, At, B0); PG8_MMA(1, 1, At, B1); PG8_BAR; PG8_SCHED;
;             PG8_LDB(B0, 1, 0); PG8_LDB(B1, 1, 1); PG8_SCHED; PG8_LDA(At, 1, 0); PG8_STAGE(PG8_SA(0, 1), a2 + hstep, voffA);
;             PG8_WAIT_V(8); PG8_WAIT_L(0); PG8_BAR; PG8_MMA(0, 0, At, B0); PG8_MMA(0, 1, At, B1); PG8_BAR; PG8_SCHED;
	s_setprio 1
	s_waitcnt lgkmcnt(0)
	v_mfma_f32_16x16x32_bf16 v[60:63], v[128:131], v[188:191], v[60:63]
	v_mfma_f32_16x16x32_bf16 v[56:59], v[136:139], v[188:191], v[56:59]
	v_mfma_f32_16x16x32_bf16 v[44:47], v[136:139], v[196:199], v[44:47]
	v_mfma_f32_16x16x32_bf16 v[48:51], v[128:131], v[196:199], v[48:51]
	v_mfma_f32_16x16x32_bf16 v[36:39], v[128:131], v[204:207], v[36:39]
	v_mfma_f32_16x16x32_bf16 v[28:31], v[136:139], v[204:207], v[28:31]
	v_mfma_f32_16x16x32_bf16 v[12:15], v[136:139], v[212:215], v[12:15]
	v_mfma_f32_16x16x32_bf16 v[20:23], v[128:131], v[212:215], v[20:23]
	v_mfma_f32_16x16x32_bf16 v[60:63], v[132:135], v[192:195], v[60:63]
	v_mfma_f32_16x16x32_bf16 v[56:59], v[140:143], v[192:195], v[56:59]
	v_mfma_f32_16x16x32_bf16 v[44:47], v[140:143], v[200:203], v[44:47]
	v_mfma_f32_16x16x32_bf16 v[48:51], v[132:135], v[200:203], v[48:51]
	v_mfma_f32_16x16x32_bf16 v[36:39], v[132:135], v[208:211], v[36:39]
	v_mfma_f32_16x16x32_bf16 v[28:31], v[140:143], v[208:211], v[28:31]
	v_mfma_f32_16x16x32_bf16 v[12:15], v[140:143], v[216:219], v[12:15]
	v_mfma_f32_16x16x32_bf16 v[20:23], v[132:135], v[216:219], v[20:23]
	s_setprio 0
	s_setprio 1
	v_mfma_f32_16x16x32_bf16 v[52:55], v[162:165], v[188:191], v[52:55]
	v_mfma_f32_16x16x32_bf16 v[40:43], v[176:179], v[188:191], v[40:43]
	v_mfma_f32_16x16x32_bf16 v[24:27], v[176:179], v[196:199], v[24:27]
	v_mfma_f32_16x16x32_bf16 v[32:35], v[162:165], v[196:199], v[32:35]
	v_mfma_f32_16x16x32_bf16 v[16:19], v[162:165], v[204:207], v[16:19]
	v_mfma_f32_16x16x32_bf16 v[8:11], v[176:179], v[204:207], v[8:11]
	v_mfma_f32_16x16x32_bf16 v[0:3], v[176:179], v[212:215], v[0:3]
	v_mfma_f32_16x16x32_bf16 v[4:7], v[162:165], v[212:215], v[4:7]
	v_mfma_f32_16x16x32_bf16 v[52:55], v[172:175], v[192:195], v[52:55]
	v_mfma_f32_16x16x32_bf16 v[40:43], v[184:187], v[192:195], v[40:43]
	v_mfma_f32_16x16x32_bf16 v[24:27], v[184:187], v[200:203], v[24:27]
	v_mfma_f32_16x16x32_bf16 v[32:35], v[172:175], v[200:203], v[32:35]
	v_mfma_f32_16x16x32_bf16 v[16:19], v[172:175], v[208:211], v[16:19]
	v_mfma_f32_16x16x32_bf16 v[8:11], v[184:187], v[208:211], v[8:11]
	v_mfma_f32_16x16x32_bf16 v[0:3], v[184:187], v[216:219], v[0:3]
	v_mfma_f32_16x16x32_bf16 v[4:7], v[172:175], v[216:219], v[4:7]
	s_setprio 0
	s_barrier
	s_add_i32 s12, 0, 0x18000
	s_add_i32 s13, 0, 0x1c000
	v_add_u32_e32 v140, s12, v167
	v_add_u32_e32 v183, s13, v167
	ds_read_b128 v[128:131], v140
	ds_read_b128 v[132:135], v140 offset:1024
	ds_read_b128 v[136:139], v140 offset:2048
	ds_read_b128 v[140:143], v140 offset:3072
	ds_read_b128 v[162:165], v183
	ds_read_b128 v[172:175], v183 offset:1024
	ds_read_b128 v[176:179], v183 offset:2048
	ds_read_b128 v[184:187], v183 offset:3072
	s_add_u32 s40, s46, 0xb0000
	s_addc_u32 s41, s47, 0
	s_mov_b32 m0, s52
	v_lshl_add_u64 v[226:227], s[40:41], 0, v[144:145]
	ds_read_b128 v[188:191], v171 offset:32768
	ds_read_b128 v[192:195], v171 offset:33792
	ds_read_b128 v[196:199], v171 offset:34816
	ds_read_b128 v[200:203], v171 offset:35840
	ds_read_b128 v[204:207], v171 offset:36864
	ds_read_b128 v[208:211], v171 offset:37888
	ds_read_b128 v[212:215], v171 offset:38912
	ds_read_b128 v[216:219], v171 offset:39936
	global_load_lds_dwordx4 v[226:227], off
	v_lshl_add_u64 v[226:227], s[40:41], 0, v[148:149]
	s_mov_b32 m0, s53
	s_nop 0
	global_load_lds_dwordx4 v[226:227], off
	s_waitcnt vmcnt(8)
	s_waitcnt lgkmcnt(0)
	s_barrier
	s_setprio 1
	s_waitcnt lgkmcnt(0)
	v_mfma_f32_16x16x32_bf16 v[124:127], v[128:131], v[188:191], v[124:127]
	v_mfma_f32_16x16x32_bf16 v[120:123], v[136:139], v[188:191], v[120:123]
	v_mfma_f32_16x16x32_bf16 v[108:111], v[136:139], v[196:199], v[108:111]
	v_mfma_f32_16x16x32_bf16 v[116:119], v[128:131], v[196:199], v[116:119]
	v_mfma_f32_16x16x32_bf16 v[100:103], v[128:131], v[204:207], v[100:103]
	v_mfma_f32_16x16x32_bf16 v[92:95], v[136:139], v[204:207], v[92:95]
	v_mfma_f32_16x16x32_bf16 v[76:79], v[136:139], v[212:215], v[76:79]
	v_mfma_f32_16x16x32_bf16 v[84:87], v[128:131], v[212:215], v[84:87]
	v_mfma_f32_16x16x32_bf16 v[124:127], v[132:135], v[192:195], v[124:127]
	v_mfma_f32_16x16x32_bf16 v[120:123], v[140:143], v[192:195], v[120:123]
	v_mfma_f32_16x16x32_bf16 v[108:111], v[140:143], v[200:203], v[108:111]
	v_mfma_f32_16x16x32_bf16 v[116:119], v[132:135], v[200:203], v[116:119]
	v_mfma_f32_16x16x32_bf16 v[100:103], v[132:135], v[208:211], v[100:103]
	v_mfma_f32_16x16x32_bf16 v[92:95], v[140:143], v[208:211], v[92:95]
	v_mfma_f32_16x16x32_bf16 v[76:79], v[140:143], v[216:219], v[76:79]
	v_mfma_f32_16x16x32_bf16 v[84:87], v[132:135], v[216:219], v[84:87]
	s_setprio 0
	s_setprio 1
	v_mfma_f32_16x16x32_bf16 v[112:115], v[162:165], v[188:191], v[112:115]
	v_mfma_f32_16x16x32_bf16 v[104:107], v[176:179], v[188:191], v[104:107]
	v_mfma_f32_16x16x32_bf16 v[88:91], v[176:179], v[196:199], v[88:91]
	v_mfma_f32_16x16x32_bf16 v[96:99], v[162:165], v[196:199], v[96:99]
	v_mfma_f32_16x16x32_bf16 v[80:83], v[162:165], v[204:207], v[80:83]
	v_mfma_f32_16x16x32_bf16 v[72:75], v[176:179], v[204:207], v[72:75]
	v_mfma_f32_16x16x32_bf16 v[64:67], v[176:179], v[212:215], v[64:67]
	v_mfma_f32_16x16x32_bf16 v[68:71], v[162:165], v[212:215], v[68:71]
	v_mfma_f32_16x16x32_bf16 v[112:115], v[172:175], v[192:195], v[112:115]
	v_mfma_f32_16x16x32_bf16 v[104:107], v[184:187], v[192:195], v[104:107]
	v_mfma_f32_16x16x32_bf16 v[88:91], v[184:187], v[200:203], v[88:91]
	v_mfma_f32_16x16x32_bf16 v[96:99], v[172:175], v[200:203], v[96:99]
	v_mfma_f32_16x16x32_bf16 v[80:83], v[172:175], v[208:211], v[80:83]
	v_mfma_f32_16x16x32_bf16 v[72:75], v[184:187], v[208:211], v[72:75]
	v_mfma_f32_16x16x32_bf16 v[64:67], v[184:187], v[216:219], v[64:67]
	v_mfma_f32_16x16x32_bf16 v[68:71], v[172:175], v[216:219], v[68:71]
	s_setprio 0
	s_barrier
; #define PG8_STAGE(bufoff, gbase, voff) do { _Pragma("unroll") for (int _i = 0; _i < 2; ++_i) \
;         __builtin_amdgcn_global_load_lds((const unsigned*)((const char*)(gbase) + (voff)[_i]), (PG8_LAS unsigned*)(lds + (bufoff) + ldsw + _i * 8192), 16, 0, 0); } while (0)
; #define PG8_LDA(dst, b, h) do { _Pragma("unroll") for (int m = 0; m < 4; ++m) _Pragma("unroll") for (int k = 0; k < 2; ++k) dst[m][k] = *(const PG8_LAS bf16x8*)(lds + PG8_SA(b, h) + aoff + m * 2048 + k * 1024); } while (0)
; #define PG8_MMA(ai, bj, At, Bt) do { __builtin_amdgcn_s_setprio(1); _Pragma("unroll") for (int m = 0; m < 4; ++m) _Pragma("unroll") for (int n = 0; n < 2; ++n) _Pragma("unroll") for (int k = 0; k < 2; ++k) \
;         acc[ai][bj][m][n] = __builtin_amdgcn_mfma_f32_16x16x32_bf16(Bt[n][k], At[m][k], acc[ai][bj][m][n], 0, 0, 0); __builtin_amdgcn_s_setprio(0); } while (0)
; #define PG8_WAIT_V(n) asm volatile("s_waitcnt vmcnt(" #n ")" ::: "memory")
; #define PG8_WAIT_L(n) asm volatile("s_waitcnt lgkmcnt(" #n ")" ::: "memory")
; #define PG8_BAR __builtin_amdgcn_s_barrier()
; #define PG8_SCHED __builtin_amdgcn_sched_barrier(0)
; template <class Epi, class Sched, bool ALIGN_EPI = false, bool SP2 = false>
; __device__ __forceinline__ void gemm_phase(PG8_LAS unsigned char* lds, const Gemm g, const Sched& S, const Epi& E) {
;     ...
;         for (int t = 0; t < nt; t += 2) {
;             const bool last = (t == nt - 2);
;             const char* a1 = cA + (size_t)(t + 1) * kstep;
;             const char* a2 = last ? nA : cA + (size_t)(t + 2) * kstep; const char* b2 = last ? nB : cB + (size_t)(t + 2) * kstep;
;             const char* a3 = a2 + kstep; const char* b3 = b2 + kstep;
;     ...
;             PG8_LDA(At, 1, 1); PG8_STAGE(PG8_SB(1, 0), b3, voffB); PG8_STAGE(PG8_SB(1, 1), b3 + hstep, voffB); PG8_STAGE(PG8_SA(1, 0), a3, voffA);
;             PG8_WAIT_V(8); PG8_WAIT_L(0); PG8_BAR; PG8_MMA(1, 0, At, B0); PG8_MMA(1, 1, At, B1); PG8_BAR; PG8_SCHED;
	s_add_i32 s12, s12, s49
	v_lshl_add_u64 v[180:181], v[180:181], 0, s[30:31]
	s_mov_b32 m0, s12
	ds_read_b128 v[188:191], v171 offset:49152
	ds_read_b128 v[192:195], v171 offset:50176
	ds_read_b128 v[196:199], v171 offset:51200
	ds_read_b128 v[200:203], v171 offset:52224
	ds_read_b128 v[204:207], v171 offset:53248
	ds_read_b128 v[208:211], v171 offset:54272
	ds_read_b128 v[212:215], v171 offset:55296
	ds_read_b128 v[216:219], v171 offset:56320
	global_load_lds_dwordx4 v[180:181], off
	s_add_i32 m0, s12, 0x2000
	s_add_u32 s40, s44, 0xb0080
	v_lshl_add_u64 v[180:181], v[220:221], 0, s[30:31]
	s_addc_u32 s41, s45, 0
	s_add_i32 s12, s13, s49
	global_load_lds_dwordx4 v[180:181], off
	v_lshl_add_u64 v[180:181], s[40:41], 0, v[146:147]
	s_mov_b32 m0, s12
	s_nop 0
	global_load_lds_dwordx4 v[180:181], off
	v_lshl_add_u64 v[180:181], s[40:41], 0, v[150:151]
	s_add_i32 m0, s12, 0x2000
	s_nop 0
	global_load_lds_dwordx4 v[180:181], off
	v_lshl_add_u64 v[180:181], v[222:223], 0, s[30:31]
	s_mov_b32 m0, s59
	s_nop 0
	global_load_lds_dwordx4 v[180:181], off
	v_lshl_add_u64 v[180:181], v[224:225], 0, s[30:31]
	s_mov_b32 m0, s60
	s_nop 0
	global_load_lds_dwordx4 v[180:181], off
	s_waitcnt vmcnt(8)
	s_waitcnt lgkmcnt(0)
	s_barrier
	s_setprio 1
	s_waitcnt lgkmcnt(0)
	v_mfma_f32_16x16x32_bf16 v[60:63], v[128:131], v[188:191], v[60:63]
	v_mfma_f32_16x16x32_bf16 v[56:59], v[136:139], v[188:191], v[56:59]
	v_mfma_f32_16x16x32_bf16 v[44:47], v[136:139], v[196:199], v[44:47]
	v_mfma_f32_16x16x32_bf16 v[48:51], v[128:131], v[196:199], v[48:51]
	v_mfma_f32_16x16x32_bf16 v[36:39], v[128:131], v[204:207], v[36:39]
	v_mfma_f32_16x16x32_bf16 v[28:31], v[136:139], v[204:207], v[28:31]
	v_mfma_f32_16x16x32_bf16 v[12:15], v[136:139], v[212:215], v[12:15]
	v_mfma_f32_16x16x32_bf16 v[20:23], v[128:131], v[212:215], v[20:23]
	v_mfma_f32_16x16x32_bf16 v[60:63], v[132:135], v[192:195], v[60:63]
	v_mfma_f32_16x16x32_bf16 v[56:59], v[140:143], v[192:195], v[56:59]
	v_mfma_f32_16x16x32_bf16 v[44:47], v[140:143], v[200:203], v[44:47]
	v_mfma_f32_16x16x32_bf16 v[48:51], v[132:135], v[200:203], v[48:51]
	v_mfma_f32_16x16x32_bf16 v[36:39], v[132:135], v[208:211], v[36:39]
	v_mfma_f32_16x16x32_bf16 v[28:31], v[140:143], v[208:211], v[28:31]
	v_mfma_f32_16x16x32_bf16 v[12:15], v[140:143], v[216:219], v[12:15]
	v_mfma_f32_16x16x32_bf16 v[20:23], v[132:135], v[216:219], v[20:23]
	s_setprio 0
	s_setprio 1
	v_mfma_f32_16x16x32_bf16 v[52:55], v[162:165], v[188:191], v[52:55]
	v_mfma_f32_16x16x32_bf16 v[40:43], v[176:179], v[188:191], v[40:43]
	v_mfma_f32_16x16x32_bf16 v[24:27], v[176:179], v[196:199], v[24:27]
	v_mfma_f32_16x16x32_bf16 v[32:35], v[162:165], v[196:199], v[32:35]
	v_mfma_f32_16x16x32_bf16 v[16:19], v[162:165], v[204:207], v[16:19]
	v_mfma_f32_16x16x32_bf16 v[8:11], v[176:179], v[204:207], v[8:11]
	v_mfma_f32_16x16x32_bf16 v[0:3], v[176:179], v[212:215], v[0:3]
	v_mfma_f32_16x16x32_bf16 v[4:7], v[162:165], v[212:215], v[4:7]
	v_mfma_f32_16x16x32_bf16 v[52:55], v[172:175], v[192:195], v[52:55]
	v_mfma_f32_16x16x32_bf16 v[40:43], v[184:187], v[192:195], v[40:43]
	v_mfma_f32_16x16x32_bf16 v[24:27], v[184:187], v[200:203], v[24:27]
	v_mfma_f32_16x16x32_bf16 v[32:35], v[172:175], v[200:203], v[32:35]
	v_mfma_f32_16x16x32_bf16 v[16:19], v[172:175], v[208:211], v[16:19]
	v_mfma_f32_16x16x32_bf16 v[8:11], v[184:187], v[208:211], v[8:11]
	v_mfma_f32_16x16x32_bf16 v[0:3], v[184:187], v[216:219], v[0:3]
	v_mfma_f32_16x16x32_bf16 v[4:7], v[172:175], v[216:219], v[4:7]
	s_setprio 0
	s_barrier
	s_add_i32 s74, s74, 2
	s_add_u32 s71, s71, 0x100
	s_addc_u32 s73, s73, 0
	s_cmp_gt_u32 s74, 41
	s_mov_b64 s[40:41], s[42:43]
	s_cbranch_scc0 .LBB0_872
	s_and_b64 vcc, exec, s[34:35]
	s_cbranch_vccz .LBB0_875
	s_barrier

; #define PG8_STAGE(bufoff, gbase, voff) do { _Pragma("unroll") for (int _i = 0; _i < 2; ++_i) \
;         __builtin_amdgcn_global_load_lds((const unsigned*)((const char*)(gbase) + (voff)[_i]), (PG8_LAS unsigned*)(lds + (bufoff) + ldsw + _i * 8192), 16, 0, 0); } while (0)
; #define PG8_LDA(dst, b, h) do { _Pragma("unroll") for (int m = 0; m < 4; ++m) _Pragma("unroll") for (int k = 0; k < 2; ++k) dst[m][k] = *(const PG8_LAS bf16x8*)(lds + PG8_SA(b, h) + aoff + m * 2048 + k * 1024); } while (0)
; #define PG8_LDB(dst, b, h) do { _Pragma("unroll") for (int n = 0; n < 2; ++n) _Pragma("unroll") for (int k = 0; k < 2; ++k) dst[n][k] = *(const PG8_LAS bf16x8*)(lds + PG8_SB(b, h) + boff + n * 2048 + k * 1024); } while (0)
; #define PG8_MMA(ai, bj, At, Bt) do { __builtin_amdgcn_s_setprio(1); _Pragma("unroll") for (int m = 0; m < 4; ++m) _Pragma("unroll") for (int n = 0; n < 2; ++n) _Pragma("unroll") for (int k = 0; k < 2; ++k) \
;         acc[ai][bj][m][n] = __builtin_amdgcn_mfma_f32_16x16x32_bf16(Bt[n][k], At[m][k], acc[ai][bj][m][n], 0, 0, 0); __builtin_amdgcn_s_setprio(0); } while (0)
; #define PG8_WAIT_V(n) asm volatile("s_waitcnt vmcnt(" #n ")" ::: "memory")
; #define PG8_WAIT_L(n) asm volatile("s_waitcnt lgkmcnt(" #n ")" ::: "memory")
; #define PG8_BAR __builtin_amdgcn_s_barrier()
; #define PG8_SCHED __builtin_amdgcn_sched_barrier(0)
; template <class Epi, class Sched, bool ALIGN_EPI = false, bool SP2 = false>
; __device__ __forceinline__ void gemm_phase(PG8_LAS unsigned char* lds, const Gemm g, const Sched& S, const Epi& E) {
;     ...
;             PG8_LDB(B0, 0, 0); PG8_LDB(B1, 0, 1); PG8_SCHED; PG8_LDA(At, 0, 0); PG8_STAGE(PG8_SA(1, 1), a1 + hstep, voffA);
;             PG8_WAIT_V(8); PG8_WAIT_L(0); PG8_BAR; PG8_MMA(0, 0, At, B0); PG8_MMA(0, 1, At, B1); PG8_BAR; PG8_SCHED;
;             PG8_LDA(At, 0, 1); PG8_STAGE(PG8_SB(0, 0), b2, voffB); PG8_STAGE(PG8_SB(0, 1), b2 + hstep, voffB); PG8_STAGE(PG8_SA(0, 0), a2, voffA);
.LBB0_960:
	v_add_u32_e32 v130, s89, v169
	ds_read_b128 v[150:153], v130
	ds_read_b128 v[158:161], v130 offset:1024
	ds_read_b128 v[162:165], v130 offset:2048
	ds_read_b128 v[196:199], v130 offset:3072
	v_add_u32_e32 v130, s90, v169
	ds_read_b128 v[200:203], v130
	ds_read_b128 v[204:207], v130 offset:1024
	ds_read_b128 v[208:211], v130 offset:2048
	ds_read_b128 v[212:215], v130 offset:3072
	s_add_u32 s12, s10, 0xfffc0080
	s_addc_u32 s13, s11, -1
	s_and_b64 s[66:67], s[66:67], exec
	s_cselect_b32 s69, s57, s13
	s_cselect_b32 s68, s63, s12
	s_cselect_b32 s67, s55, s71
	s_cselect_b32 s66, s70, s65
	v_lshl_add_u64 v[130:131], s[10:11], 0, v[142:143]
	s_add_i32 m0, s75, 0xc000
	ds_read_b128 v[216:219], v191
	ds_read_b128 v[220:223], v191 offset:1024
	ds_read_b128 v[224:227], v191 offset:2048
	ds_read_b128 v[228:231], v191 offset:3072
	ds_read_b128 v[232:235], v191 offset:4096
	ds_read_b128 v[236:239], v191 offset:5120
	ds_read_b128 v[240:243], v191 offset:6144
	ds_read_b128 v[244:247], v191 offset:7168
	global_load_lds_dwordx4 v[130:131], off
	v_lshl_add_u64 v[130:131], s[10:11], 0, v[140:141]
	s_add_i32 m0, s75, 0xe000
	s_nop 0
	global_load_lds_dwordx4 v[130:131], off
	s_waitcnt vmcnt(8)
	s_waitcnt lgkmcnt(0)
	s_barrier
	s_setprio 1
	s_waitcnt lgkmcnt(0)
	v_mfma_f32_16x16x32_bf16 v[124:127], v[150:153], v[216:219], v[124:127]
	v_mfma_f32_16x16x32_bf16 v[120:123], v[162:165], v[216:219], v[120:123]
	v_mfma_f32_16x16x32_bf16 v[104:107], v[162:165], v[224:227], v[104:107]
	v_mfma_f32_16x16x32_bf16 v[112:115], v[150:153], v[224:227], v[112:115]
	v_mfma_f32_16x16x32_bf16 v[100:103], v[150:153], v[232:235], v[100:103]
	v_mfma_f32_16x16x32_bf16 v[96:99], v[162:165], v[232:235], v[96:99]
	v_mfma_f32_16x16x32_bf16 v[72:75], v[162:165], v[240:243], v[72:75]
	v_mfma_f32_16x16x32_bf16 v[80:83], v[150:153], v[240:243], v[80:83]
	v_mfma_f32_16x16x32_bf16 v[124:127], v[158:161], v[220:223], v[124:127]
	v_mfma_f32_16x16x32_bf16 v[120:123], v[196:199], v[220:223], v[120:123]
	v_mfma_f32_16x16x32_bf16 v[104:107], v[196:199], v[228:231], v[104:107]
	v_mfma_f32_16x16x32_bf16 v[112:115], v[158:161], v[228:231], v[112:115]
	v_mfma_f32_16x16x32_bf16 v[100:103], v[158:161], v[236:239], v[100:103]
	v_mfma_f32_16x16x32_bf16 v[96:99], v[196:199], v[236:239], v[96:99]
	v_mfma_f32_16x16x32_bf16 v[72:75], v[196:199], v[244:247], v[72:75]
	v_mfma_f32_16x16x32_bf16 v[80:83], v[158:161], v[244:247], v[80:83]
	s_setprio 0
	s_setprio 1
	v_mfma_f32_16x16x32_bf16 v[116:119], v[200:203], v[216:219], v[116:119]
	v_mfma_f32_16x16x32_bf16 v[108:111], v[208:211], v[216:219], v[108:111]
	v_mfma_f32_16x16x32_bf16 v[88:91], v[208:211], v[224:227], v[88:91]
	v_mfma_f32_16x16x32_bf16 v[92:95], v[200:203], v[224:227], v[92:95]
	v_mfma_f32_16x16x32_bf16 v[84:87], v[200:203], v[232:235], v[84:87]
	v_mfma_f32_16x16x32_bf16 v[76:79], v[208:211], v[232:235], v[76:79]
	v_mfma_f32_16x16x32_bf16 v[64:67], v[208:211], v[240:243], v[64:67]
	v_mfma_f32_16x16x32_bf16 v[68:71], v[200:203], v[240:243], v[68:71]
	v_mfma_f32_16x16x32_bf16 v[116:119], v[204:207], v[220:223], v[116:119]
	v_mfma_f32_16x16x32_bf16 v[108:111], v[212:215], v[220:223], v[108:111]
	v_mfma_f32_16x16x32_bf16 v[88:91], v[212:215], v[228:231], v[88:91]
	v_mfma_f32_16x16x32_bf16 v[92:95], v[204:207], v[228:231], v[92:95]
	v_mfma_f32_16x16x32_bf16 v[84:87], v[204:207], v[236:239], v[84:87]
	v_mfma_f32_16x16x32_bf16 v[76:79], v[212:215], v[236:239], v[76:79]
	v_mfma_f32_16x16x32_bf16 v[64:67], v[212:215], v[244:247], v[64:67]
	v_mfma_f32_16x16x32_bf16 v[68:71], v[204:207], v[244:247], v[68:71]
	s_setprio 0
	s_barrier
	s_add_i32 s12, s89, s74
	v_lshl_add_u64 v[130:131], s[66:67], 0, v[134:135]
	s_mov_b32 m0, s12
	ds_read_b128 v[216:219], v191 offset:16384
	ds_read_b128 v[220:223], v191 offset:17408
	ds_read_b128 v[224:227], v191 offset:18432
	ds_read_b128 v[228:231], v191 offset:19456
	ds_read_b128 v[232:235], v191 offset:20480
	ds_read_b128 v[236:239], v191 offset:21504
	ds_read_b128 v[240:243], v191 offset:22528
	ds_read_b128 v[244:247], v191 offset:23552
	global_load_lds_dwordx4 v[130:131], off
	s_add_i32 m0, s12, 0x2000
	s_add_u32 vcc_lo, s66, 0x40000
	v_lshl_add_u64 v[154:155], s[66:67], 0, v[138:139]
	s_addc_u32 vcc_hi, s67, 0
	s_add_i32 s12, s90, s74
	global_load_lds_dwordx4 v[154:155], off
	v_lshl_add_u64 v[166:167], vcc, 0, v[134:135]
	s_mov_b32 m0, s12
	v_lshl_add_u64 v[248:249], s[68:69], 0, v[136:137]
	global_load_lds_dwordx4 v[166:167], off
	v_lshl_add_u64 v[166:167], vcc, 0, v[138:139]
	s_add_i32 m0, s12, 0x2000
	s_nop 0
	global_load_lds_dwordx4 v[166:167], off
	v_lshl_add_u64 v[166:167], s[68:69], 0, v[132:133]
	s_mov_b32 m0, s75
	s_nop 0
	global_load_lds_dwordx4 v[166:167], off
	s_mov_b32 m0, s76
	s_nop 0
	global_load_lds_dwordx4 v[248:249], off
	s_waitcnt vmcnt(8)
	s_waitcnt lgkmcnt(0)
	s_barrier
; #define PG8_STAGE(bufoff, gbase, voff) do { _Pragma("unroll") for (int _i = 0; _i < 2; ++_i) \
;         __builtin_amdgcn_global_load_lds((const unsigned*)((const char*)(gbase) + (voff)[_i]), (PG8_LAS unsigned*)(lds + (bufoff) + ldsw + _i * 8192), 16, 0, 0); } while (0)
; #define PG8_LDA(dst, b, h) do { _Pragma("unroll") for (int m = 0; m < 4; ++m) _Pragma("unroll") for (int k = 0; k < 2; ++k) dst[m][k] = *(const PG8_LAS bf16x8*)(lds + PG8_SA(b, h) + aoff + m * 2048 + k * 1024); } while (0)
; #define PG8_LDB(dst, b, h) do { _Pragma("unroll") for (int n = 0; n < 2; ++n) _Pragma("unroll") for (int k = 0; k < 2; ++k) dst[n][k] = *(const PG8_LAS bf16x8*)(lds + PG8_SB(b, h) + boff + n * 2048 + k * 1024); } while (0)
; #define PG8_MMA(ai, bj, At, Bt) do { __builtin_amdgcn_s_setprio(1); _Pragma("unroll") for (int m = 0; m < 4; ++m) _Pragma("unroll") for (int n = 0; n < 2; ++n) _Pragma("unroll") for (int k = 0; k < 2; ++k) \
;         acc[ai][bj][m][n] = __builtin_amdgcn_mfma_f32_16x16x32_bf16(Bt[n][k], At[m][k], acc[ai][bj][m][n], 0, 0, 0); __builtin_amdgcn_s_setprio(0); } while (0)
; #define PG8_WAIT_V(n) asm volatile("s_waitcnt vmcnt(" #n ")" ::: "memory")
; #define PG8_WAIT_L(n) asm volatile("s_waitcnt lgkmcnt(" #n ")" ::: "memory")
; #define PG8_BAR __builtin_amdgcn_s_barrier()
; #define PG8_SCHED __builtin_amdgcn_sched_barrier(0)
; template <class Epi, class Sched, bool ALIGN_EPI = false, bool SP2 = false>
; __device__ __forceinline__ void gemm_phase(PG8_LAS unsigned char* lds, const Gemm g, const Sched& S, const Epi& E) {
;     ...
;             PG8_WAIT_V(8); PG8_WAIT_L(0); PG8_BAR; PG8_MMA(1, 0, At, B0); PG8_MMA(1, 1, At, B1); PG8_BAR; PG8_SCHED;
;             PG8_LDB(B0, 1, 0); PG8_LDB(B1, 1, 1); PG8_SCHED; PG8_LDA(At, 1, 0); PG8_STAGE(PG8_SA(0, 1), a2 + hstep, voffA);
;             PG8_WAIT_V(8); PG8_WAIT_L(0); PG8_BAR; PG8_MMA(0, 0, At, B0); PG8_MMA(0, 1, At, B1); PG8_BAR; PG8_SCHED;
	s_setprio 1
	s_waitcnt lgkmcnt(0)
	v_mfma_f32_16x16x32_bf16 v[60:63], v[150:153], v[216:219], v[60:63]
	v_mfma_f32_16x16x32_bf16 v[56:59], v[162:165], v[216:219], v[56:59]
	v_mfma_f32_16x16x32_bf16 v[40:43], v[162:165], v[224:227], v[40:43]
	v_mfma_f32_16x16x32_bf16 v[48:51], v[150:153], v[224:227], v[48:51]
	v_mfma_f32_16x16x32_bf16 v[36:39], v[150:153], v[232:235], v[36:39]
	v_mfma_f32_16x16x32_bf16 v[32:35], v[162:165], v[232:235], v[32:35]
	v_mfma_f32_16x16x32_bf16 v[16:19], v[162:165], v[240:243], v[16:19]
	v_mfma_f32_16x16x32_bf16 v[20:23], v[150:153], v[240:243], v[20:23]
	v_mfma_f32_16x16x32_bf16 v[60:63], v[158:161], v[220:223], v[60:63]
	v_mfma_f32_16x16x32_bf16 v[56:59], v[196:199], v[220:223], v[56:59]
	v_mfma_f32_16x16x32_bf16 v[40:43], v[196:199], v[228:231], v[40:43]
	v_mfma_f32_16x16x32_bf16 v[48:51], v[158:161], v[228:231], v[48:51]
	v_mfma_f32_16x16x32_bf16 v[36:39], v[158:161], v[236:239], v[36:39]
	v_mfma_f32_16x16x32_bf16 v[32:35], v[196:199], v[236:239], v[32:35]
	v_mfma_f32_16x16x32_bf16 v[16:19], v[196:199], v[244:247], v[16:19]
	v_mfma_f32_16x16x32_bf16 v[20:23], v[158:161], v[244:247], v[20:23]
	s_setprio 0
	s_setprio 1
	v_mfma_f32_16x16x32_bf16 v[52:55], v[200:203], v[216:219], v[52:55]
	v_mfma_f32_16x16x32_bf16 v[44:47], v[208:211], v[216:219], v[44:47]
	v_mfma_f32_16x16x32_bf16 v[24:27], v[208:211], v[224:227], v[24:27]
	v_mfma_f32_16x16x32_bf16 v[28:31], v[200:203], v[224:227], v[28:31]
	v_mfma_f32_16x16x32_bf16 v[12:15], v[200:203], v[232:235], v[12:15]
	v_mfma_f32_16x16x32_bf16 v[8:11], v[208:211], v[232:235], v[8:11]
	v_mfma_f32_16x16x32_bf16 v[0:3], v[208:211], v[240:243], v[0:3]
	v_mfma_f32_16x16x32_bf16 v[4:7], v[200:203], v[240:243], v[4:7]
	v_mfma_f32_16x16x32_bf16 v[52:55], v[204:207], v[220:223], v[52:55]
	v_mfma_f32_16x16x32_bf16 v[44:47], v[212:215], v[220:223], v[44:47]
	v_mfma_f32_16x16x32_bf16 v[24:27], v[212:215], v[228:231], v[24:27]
	v_mfma_f32_16x16x32_bf16 v[28:31], v[204:207], v[228:231], v[28:31]
	v_mfma_f32_16x16x32_bf16 v[12:15], v[204:207], v[236:239], v[12:15]
	v_mfma_f32_16x16x32_bf16 v[8:11], v[212:215], v[236:239], v[8:11]
	v_mfma_f32_16x16x32_bf16 v[0:3], v[212:215], v[244:247], v[0:3]
	v_mfma_f32_16x16x32_bf16 v[4:7], v[204:207], v[244:247], v[4:7]
	s_setprio 0
	s_barrier
	s_add_i32 s12, 0, 0x18000
	v_add_u32_e32 v195, s12, v169
	s_add_i32 s13, 0, 0x1c000
	ds_read_b128 v[150:153], v195
	ds_read_b128 v[158:161], v195 offset:1024
	ds_read_b128 v[162:165], v195 offset:2048
	ds_read_b128 v[196:199], v195 offset:3072
	v_add_u32_e32 v195, s13, v169
	ds_read_b128 v[200:203], v195
	ds_read_b128 v[204:207], v195 offset:1024
	ds_read_b128 v[208:211], v195 offset:2048
	ds_read_b128 v[212:215], v195 offset:3072
	s_add_u32 s68, s68, 0x40000
	s_addc_u32 s69, s69, 0
	s_mov_b32 m0, s77
	v_lshl_add_u64 v[250:251], s[68:69], 0, v[132:133]
	ds_read_b128 v[216:219], v191 offset:32768
	ds_read_b128 v[220:223], v191 offset:33792
	ds_read_b128 v[224:227], v191 offset:34816
	ds_read_b128 v[228:231], v191 offset:35840
	ds_read_b128 v[232:235], v191 offset:36864
	ds_read_b128 v[236:239], v191 offset:37888
	ds_read_b128 v[240:243], v191 offset:38912
	ds_read_b128 v[244:247], v191 offset:39936
	global_load_lds_dwordx4 v[250:251], off
	v_lshl_add_u64 v[250:251], s[68:69], 0, v[136:137]
	s_mov_b32 m0, s78
	s_nop 0
	global_load_lds_dwordx4 v[250:251], off
	s_waitcnt vmcnt(8)
	s_waitcnt lgkmcnt(0)
	s_barrier
	s_setprio 1
	s_waitcnt lgkmcnt(0)
	v_mfma_f32_16x16x32_bf16 v[124:127], v[150:153], v[216:219], v[124:127]
	v_mfma_f32_16x16x32_bf16 v[120:123], v[162:165], v[216:219], v[120:123]
	v_mfma_f32_16x16x32_bf16 v[104:107], v[162:165], v[224:227], v[104:107]
	v_mfma_f32_16x16x32_bf16 v[112:115], v[150:153], v[224:227], v[112:115]
	v_mfma_f32_16x16x32_bf16 v[100:103], v[150:153], v[232:235], v[100:103]
	v_mfma_f32_16x16x32_bf16 v[96:99], v[162:165], v[232:235], v[96:99]
	v_mfma_f32_16x16x32_bf16 v[72:75], v[162:165], v[240:243], v[72:75]
	v_mfma_f32_16x16x32_bf16 v[80:83], v[150:153], v[240:243], v[80:83]
	v_mfma_f32_16x16x32_bf16 v[124:127], v[158:161], v[220:223], v[124:127]
	v_mfma_f32_16x16x32_bf16 v[120:123], v[196:199], v[220:223], v[120:123]
	v_mfma_f32_16x16x32_bf16 v[104:107], v[196:199], v[228:231], v[104:107]
	v_mfma_f32_16x16x32_bf16 v[112:115], v[158:161], v[228:231], v[112:115]
	v_mfma_f32_16x16x32_bf16 v[100:103], v[158:161], v[236:239], v[100:103]
	v_mfma_f32_16x16x32_bf16 v[96:99], v[196:199], v[236:239], v[96:99]
	v_mfma_f32_16x16x32_bf16 v[72:75], v[196:199], v[244:247], v[72:75]
	v_mfma_f32_16x16x32_bf16 v[80:83], v[158:161], v[244:247], v[80:83]
	s_setprio 0
	s_setprio 1
	v_mfma_f32_16x16x32_bf16 v[116:119], v[200:203], v[216:219], v[116:119]
	v_mfma_f32_16x16x32_bf16 v[108:111], v[208:211], v[216:219], v[108:111]
	v_mfma_f32_16x16x32_bf16 v[88:91], v[208:211], v[224:227], v[88:91]
	v_mfma_f32_16x16x32_bf16 v[92:95], v[200:203], v[224:227], v[92:95]
	v_mfma_f32_16x16x32_bf16 v[84:87], v[200:203], v[232:235], v[84:87]
	v_mfma_f32_16x16x32_bf16 v[76:79], v[208:211], v[232:235], v[76:79]
	v_mfma_f32_16x16x32_bf16 v[64:67], v[208:211], v[240:243], v[64:67]
	v_mfma_f32_16x16x32_bf16 v[68:71], v[200:203], v[240:243], v[68:71]
	v_mfma_f32_16x16x32_bf16 v[116:119], v[204:207], v[220:223], v[116:119]
	v_mfma_f32_16x16x32_bf16 v[108:111], v[212:215], v[220:223], v[108:111]
	v_mfma_f32_16x16x32_bf16 v[88:91], v[212:215], v[228:231], v[88:91]
	v_mfma_f32_16x16x32_bf16 v[92:95], v[204:207], v[228:231], v[92:95]
	v_mfma_f32_16x16x32_bf16 v[84:87], v[204:207], v[236:239], v[84:87]
	v_mfma_f32_16x16x32_bf16 v[76:79], v[212:215], v[236:239], v[76:79]
	v_mfma_f32_16x16x32_bf16 v[64:67], v[212:215], v[244:247], v[64:67]
	v_mfma_f32_16x16x32_bf16 v[68:71], v[204:207], v[244:247], v[68:71]
	s_setprio 0
	s_barrier
; #define PG8_STAGE(bufoff, gbase, voff) do { _Pragma("unroll") for (int _i = 0; _i < 2; ++_i) \
;         __builtin_amdgcn_global_load_lds((const unsigned*)((const char*)(gbase) + (voff)[_i]), (PG8_LAS unsigned*)(lds + (bufoff) + ldsw + _i * 8192), 16, 0, 0); } while (0)
; #define PG8_LDA(dst, b, h) do { _Pragma("unroll") for (int m = 0; m < 4; ++m) _Pragma("unroll") for (int k = 0; k < 2; ++k) dst[m][k] = *(const PG8_LAS bf16x8*)(lds + PG8_SA(b, h) + aoff + m * 2048 + k * 1024); } while (0)
; #define PG8_MMA(ai, bj, At, Bt) do { __builtin_amdgcn_s_setprio(1); _Pragma("unroll") for (int m = 0; m < 4; ++m) _Pragma("unroll") for (int n = 0; n < 2; ++n) _Pragma("unroll") for (int k = 0; k < 2; ++k) \
;         acc[ai][bj][m][n] = __builtin_amdgcn_mfma_f32_16x16x32_bf16(Bt[n][k], At[m][k], acc[ai][bj][m][n], 0, 0, 0); __builtin_amdgcn_s_setprio(0); } while (0)
; #define PG8_WAIT_V(n) asm volatile("s_waitcnt vmcnt(" #n ")" ::: "memory")
; #define PG8_WAIT_L(n) asm volatile("s_waitcnt lgkmcnt(" #n ")" ::: "memory")
; #define PG8_BAR __builtin_amdgcn_s_barrier()
; #define PG8_SCHED __builtin_amdgcn_sched_barrier(0)
; template <class Epi, class Sched, bool ALIGN_EPI = false, bool SP2 = false>
; __device__ __forceinline__ void gemm_phase(PG8_LAS unsigned char* lds, const Gemm g, const Sched& S, const Epi& E) {
;     ...
;         for (int t = 0; t < nt; t += 2) {
;             const bool last = (t == nt - 2);
;             const char* a1 = cA + (size_t)(t + 1) * kstep;
;             const char* a2 = last ? nA : cA + (size_t)(t + 2) * kstep; const char* b2 = last ? nB : cB + (size_t)(t + 2) * kstep;
;             const char* a3 = a2 + kstep; const char* b3 = b2 + kstep;
;     ...
;             PG8_LDA(At, 1, 1); PG8_STAGE(PG8_SB(1, 0), b3, voffB); PG8_STAGE(PG8_SB(1, 1), b3 + hstep, voffB); PG8_STAGE(PG8_SA(1, 0), a3, voffA);
;             PG8_WAIT_V(8); PG8_WAIT_L(0); PG8_BAR; PG8_MMA(1, 0, At, B0); PG8_MMA(1, 1, At, B1); PG8_BAR; PG8_SCHED;
	s_add_i32 s12, s12, s74
	v_lshl_add_u64 v[130:131], v[130:131], 0, s[42:43]
	s_mov_b32 m0, s12
	ds_read_b128 v[216:219], v191 offset:49152
	ds_read_b128 v[220:223], v191 offset:50176
	ds_read_b128 v[224:227], v191 offset:51200
	ds_read_b128 v[228:231], v191 offset:52224
	ds_read_b128 v[232:235], v191 offset:53248
	ds_read_b128 v[236:239], v191 offset:54272
	ds_read_b128 v[240:243], v191 offset:55296
	ds_read_b128 v[244:247], v191 offset:56320
	global_load_lds_dwordx4 v[130:131], off
	s_add_i32 m0, s12, 0x2000
	s_add_u32 s66, s66, 0x40080
	v_lshl_add_u64 v[130:131], v[154:155], 0, s[42:43]
	s_addc_u32 s67, s67, 0
	s_add_i32 s12, s13, s74
	global_load_lds_dwordx4 v[130:131], off
	v_lshl_add_u64 v[130:131], s[66:67], 0, v[134:135]
	s_mov_b32 m0, s12
	s_nop 0
	global_load_lds_dwordx4 v[130:131], off
	v_lshl_add_u64 v[130:131], s[66:67], 0, v[138:139]
	s_add_i32 m0, s12, 0x2000
	s_nop 0
	global_load_lds_dwordx4 v[130:131], off
	v_lshl_add_u64 v[130:131], v[166:167], 0, s[42:43]
	s_mov_b32 m0, s79
	s_nop 0
	global_load_lds_dwordx4 v[130:131], off
	v_lshl_add_u64 v[130:131], v[248:249], 0, s[42:43]
	s_mov_b32 m0, s80
	s_nop 0
	global_load_lds_dwordx4 v[130:131], off
	s_waitcnt vmcnt(8)
	s_waitcnt lgkmcnt(0)
	s_barrier
	s_setprio 1
	s_waitcnt lgkmcnt(0)
	v_mfma_f32_16x16x32_bf16 v[60:63], v[150:153], v[216:219], v[60:63]
	v_mfma_f32_16x16x32_bf16 v[56:59], v[162:165], v[216:219], v[56:59]
	v_mfma_f32_16x16x32_bf16 v[40:43], v[162:165], v[224:227], v[40:43]
	v_mfma_f32_16x16x32_bf16 v[48:51], v[150:153], v[224:227], v[48:51]
	v_mfma_f32_16x16x32_bf16 v[36:39], v[150:153], v[232:235], v[36:39]
	v_mfma_f32_16x16x32_bf16 v[32:35], v[162:165], v[232:235], v[32:35]
	v_mfma_f32_16x16x32_bf16 v[16:19], v[162:165], v[240:243], v[16:19]
	v_mfma_f32_16x16x32_bf16 v[20:23], v[150:153], v[240:243], v[20:23]
	v_mfma_f32_16x16x32_bf16 v[60:63], v[158:161], v[220:223], v[60:63]
	v_mfma_f32_16x16x32_bf16 v[56:59], v[196:199], v[220:223], v[56:59]
	v_mfma_f32_16x16x32_bf16 v[40:43], v[196:199], v[228:231], v[40:43]
	v_mfma_f32_16x16x32_bf16 v[48:51], v[158:161], v[228:231], v[48:51]
	v_mfma_f32_16x16x32_bf16 v[36:39], v[158:161], v[236:239], v[36:39]
	v_mfma_f32_16x16x32_bf16 v[32:35], v[196:199], v[236:239], v[32:35]
	v_mfma_f32_16x16x32_bf16 v[16:19], v[196:199], v[244:247], v[16:19]
	v_mfma_f32_16x16x32_bf16 v[20:23], v[158:161], v[244:247], v[20:23]
	s_setprio 0
	s_setprio 1
	v_mfma_f32_16x16x32_bf16 v[52:55], v[200:203], v[216:219], v[52:55]
	v_mfma_f32_16x16x32_bf16 v[44:47], v[208:211], v[216:219], v[44:47]
	v_mfma_f32_16x16x32_bf16 v[24:27], v[208:211], v[224:227], v[24:27]
	v_mfma_f32_16x16x32_bf16 v[28:31], v[200:203], v[224:227], v[28:31]
	v_mfma_f32_16x16x32_bf16 v[12:15], v[200:203], v[232:235], v[12:15]
	v_mfma_f32_16x16x32_bf16 v[8:11], v[208:211], v[232:235], v[8:11]
	v_mfma_f32_16x16x32_bf16 v[0:3], v[208:211], v[240:243], v[0:3]
	v_mfma_f32_16x16x32_bf16 v[4:7], v[200:203], v[240:243], v[4:7]
	v_mfma_f32_16x16x32_bf16 v[52:55], v[204:207], v[220:223], v[52:55]
	v_mfma_f32_16x16x32_bf16 v[44:47], v[212:215], v[220:223], v[44:47]
	v_mfma_f32_16x16x32_bf16 v[24:27], v[212:215], v[228:231], v[24:27]
	v_mfma_f32_16x16x32_bf16 v[28:31], v[204:207], v[228:231], v[28:31]
	v_mfma_f32_16x16x32_bf16 v[12:15], v[204:207], v[236:239], v[12:15]
	v_mfma_f32_16x16x32_bf16 v[8:11], v[212:215], v[236:239], v[8:11]
	v_mfma_f32_16x16x32_bf16 v[0:3], v[212:215], v[244:247], v[0:3]
	v_mfma_f32_16x16x32_bf16 v[4:7], v[204:207], v[244:247], v[4:7]
	s_setprio 0
	s_barrier
	s_add_i32 s96, s96, 2
	s_add_u32 s65, s65, 0x100
	s_addc_u32 s71, s71, 0
	s_add_u32 s10, s10, 0x100
	s_addc_u32 s11, s11, 0
	s_cmp_gt_u32 s96, 13
	s_cbranch_scc1 .LBB0_963

; #define PG8_STAGE(bufoff, gbase, voff) do { _Pragma("unroll") for (int _i = 0; _i < 2; ++_i) \
;         __builtin_amdgcn_global_load_lds((const unsigned*)((const char*)(gbase) + (voff)[_i]), (PG8_LAS unsigned*)(lds + (bufoff) + ldsw + _i * 8192), 16, 0, 0); } while (0)
; #define PG8_LDA(dst, b, h) do { _Pragma("unroll") for (int m = 0; m < 4; ++m) _Pragma("unroll") for (int k = 0; k < 2; ++k) dst[m][k] = *(const PG8_LAS bf16x8*)(lds + PG8_SA(b, h) + aoff + m * 2048 + k * 1024); } while (0)
; #define PG8_LDB(dst, b, h) do { _Pragma("unroll") for (int n = 0; n < 2; ++n) _Pragma("unroll") for (int k = 0; k < 2; ++k) dst[n][k] = *(const PG8_LAS bf16x8*)(lds + PG8_SB(b, h) + boff + n * 2048 + k * 1024); } while (0)
; #define PG8_MMA(ai, bj, At, Bt) do { __builtin_amdgcn_s_setprio(1); _Pragma("unroll") for (int m = 0; m < 4; ++m) _Pragma("unroll") for (int n = 0; n < 2; ++n) _Pragma("unroll") for (int k = 0; k < 2; ++k) \
;         acc[ai][bj][m][n] = __builtin_amdgcn_mfma_f32_16x16x32_bf16(Bt[n][k], At[m][k], acc[ai][bj][m][n], 0, 0, 0); __builtin_amdgcn_s_setprio(0); } while (0)
; #define PG8_WAIT_V(n) asm volatile("s_waitcnt vmcnt(" #n ")" ::: "memory")
; #define PG8_WAIT_L(n) asm volatile("s_waitcnt lgkmcnt(" #n ")" ::: "memory")
; #define PG8_BAR __builtin_amdgcn_s_barrier()
; #define PG8_SCHED __builtin_amdgcn_sched_barrier(0)
; template <class Epi, class Sched, bool ALIGN_EPI = false, bool SP2 = false>
; __device__ __forceinline__ void gemm_phase(PG8_LAS unsigned char* lds, const Gemm g, const Sched& S, const Epi& E) {
;     ...
;             PG8_LDB(B0, 0, 0); PG8_LDB(B1, 0, 1); PG8_SCHED; PG8_LDA(At, 0, 0); PG8_STAGE(PG8_SA(1, 1), a1 + hstep, voffA);
;             PG8_WAIT_V(8); PG8_WAIT_L(0); PG8_BAR; PG8_MMA(0, 0, At, B0); PG8_MMA(0, 1, At, B1); PG8_BAR; PG8_SCHED;
;             PG8_LDA(At, 0, 1); PG8_STAGE(PG8_SB(0, 0), b2, voffB); PG8_STAGE(PG8_SB(0, 1), b2 + hstep, voffB); PG8_STAGE(PG8_SA(0, 0), a2, voffA);
.LBB0_1272:
	ds_read_b128 v[128:131], v167
	ds_read_b128 v[132:135], v167 offset:1024
	ds_read_b128 v[136:139], v167 offset:2048
	ds_read_b128 v[140:143], v167 offset:3072
	ds_read_b128 v[160:163], v168
	ds_read_b128 v[170:173], v168 offset:1024
	ds_read_b128 v[174:177], v168 offset:2048
	ds_read_b128 v[178:181], v168 offset:3072
	s_add_u32 s12, s50, 0xfffc0080
	s_addc_u32 s13, s51, -1
	s_cmp_eq_u32 s79, 12
	s_cselect_b32 s55, s41, s13
	s_cselect_b32 s54, s47, s12
	s_cselect_b32 s53, s39, s78
	s_cselect_b32 s52, s49, s77
	v_lshl_add_u64 v[184:185], s[50:51], 0, v[154:155]
	s_add_i32 m0, s60, 0xc000
	ds_read_b128 v[188:191], v169
	ds_read_b128 v[192:195], v169 offset:1024
	ds_read_b128 v[196:199], v169 offset:2048
	ds_read_b128 v[200:203], v169 offset:3072
	ds_read_b128 v[204:207], v169 offset:4096
	ds_read_b128 v[208:211], v169 offset:5120
	ds_read_b128 v[212:215], v169 offset:6144
	ds_read_b128 v[216:219], v169 offset:7168
	global_load_lds_dwordx4 v[184:185], off
	v_lshl_add_u64 v[184:185], s[50:51], 0, v[152:153]
	s_add_i32 m0, s60, 0xe000
	s_nop 0
	global_load_lds_dwordx4 v[184:185], off
	s_waitcnt vmcnt(8)
	s_waitcnt lgkmcnt(0)
	s_barrier
	s_setprio 1
	s_waitcnt lgkmcnt(0)
	v_mfma_f32_16x16x32_bf16 v[124:127], v[128:131], v[188:191], v[124:127]
	v_mfma_f32_16x16x32_bf16 v[120:123], v[136:139], v[188:191], v[120:123]
	v_mfma_f32_16x16x32_bf16 v[108:111], v[136:139], v[196:199], v[108:111]
	v_mfma_f32_16x16x32_bf16 v[116:119], v[128:131], v[196:199], v[116:119]
	v_mfma_f32_16x16x32_bf16 v[100:103], v[128:131], v[204:207], v[100:103]
	v_mfma_f32_16x16x32_bf16 v[92:95], v[136:139], v[204:207], v[92:95]
	v_mfma_f32_16x16x32_bf16 v[76:79], v[136:139], v[212:215], v[76:79]
	v_mfma_f32_16x16x32_bf16 v[84:87], v[128:131], v[212:215], v[84:87]
	v_mfma_f32_16x16x32_bf16 v[124:127], v[132:135], v[192:195], v[124:127]
	v_mfma_f32_16x16x32_bf16 v[120:123], v[140:143], v[192:195], v[120:123]
	v_mfma_f32_16x16x32_bf16 v[108:111], v[140:143], v[200:203], v[108:111]
	v_mfma_f32_16x16x32_bf16 v[116:119], v[132:135], v[200:203], v[116:119]
	v_mfma_f32_16x16x32_bf16 v[100:103], v[132:135], v[208:211], v[100:103]
	v_mfma_f32_16x16x32_bf16 v[92:95], v[140:143], v[208:211], v[92:95]
	v_mfma_f32_16x16x32_bf16 v[76:79], v[140:143], v[216:219], v[76:79]
	v_mfma_f32_16x16x32_bf16 v[84:87], v[132:135], v[216:219], v[84:87]
	s_setprio 0
	s_setprio 1
	v_mfma_f32_16x16x32_bf16 v[112:115], v[160:163], v[188:191], v[112:115]
	v_mfma_f32_16x16x32_bf16 v[104:107], v[174:177], v[188:191], v[104:107]
	v_mfma_f32_16x16x32_bf16 v[88:91], v[174:177], v[196:199], v[88:91]
	v_mfma_f32_16x16x32_bf16 v[96:99], v[160:163], v[196:199], v[96:99]
	v_mfma_f32_16x16x32_bf16 v[80:83], v[160:163], v[204:207], v[80:83]
	v_mfma_f32_16x16x32_bf16 v[72:75], v[174:177], v[204:207], v[72:75]
	v_mfma_f32_16x16x32_bf16 v[64:67], v[174:177], v[212:215], v[64:67]
	v_mfma_f32_16x16x32_bf16 v[68:71], v[160:163], v[212:215], v[68:71]
	v_mfma_f32_16x16x32_bf16 v[112:115], v[170:173], v[192:195], v[112:115]
	v_mfma_f32_16x16x32_bf16 v[104:107], v[178:181], v[192:195], v[104:107]
	v_mfma_f32_16x16x32_bf16 v[88:91], v[178:181], v[200:203], v[88:91]
	v_mfma_f32_16x16x32_bf16 v[96:99], v[170:173], v[200:203], v[96:99]
	v_mfma_f32_16x16x32_bf16 v[80:83], v[170:173], v[208:211], v[80:83]
	v_mfma_f32_16x16x32_bf16 v[72:75], v[178:181], v[208:211], v[72:75]
	v_mfma_f32_16x16x32_bf16 v[64:67], v[178:181], v[216:219], v[64:67]
	v_mfma_f32_16x16x32_bf16 v[68:71], v[170:173], v[216:219], v[68:71]
	s_setprio 0
	s_barrier
	s_add_i32 s12, s75, s59
	v_lshl_add_u64 v[184:185], s[52:53], 0, v[146:147]
	s_mov_b32 m0, s12
	ds_read_b128 v[188:191], v169 offset:16384
	ds_read_b128 v[192:195], v169 offset:17408
	ds_read_b128 v[196:199], v169 offset:18432
	ds_read_b128 v[200:203], v169 offset:19456
	ds_read_b128 v[204:207], v169 offset:20480
	ds_read_b128 v[208:211], v169 offset:21504
	ds_read_b128 v[212:215], v169 offset:22528
	ds_read_b128 v[216:219], v169 offset:23552
	global_load_lds_dwordx4 v[184:185], off
	s_add_i32 m0, s12, 0x2000
	s_add_u32 s80, s52, 0x40000
	v_lshl_add_u64 v[220:221], s[52:53], 0, v[150:151]
	s_addc_u32 s81, s53, 0
	s_add_i32 s12, s76, s59
	global_load_lds_dwordx4 v[220:221], off
	v_lshl_add_u64 v[222:223], s[80:81], 0, v[146:147]
	s_mov_b32 m0, s12
	v_lshl_add_u64 v[224:225], s[54:55], 0, v[148:149]
	global_load_lds_dwordx4 v[222:223], off
	v_lshl_add_u64 v[222:223], s[80:81], 0, v[150:151]
	s_add_i32 m0, s12, 0x2000
	s_nop 0
	global_load_lds_dwordx4 v[222:223], off
	v_lshl_add_u64 v[222:223], s[54:55], 0, v[144:145]
	s_mov_b32 m0, s60
	s_nop 0
	global_load_lds_dwordx4 v[222:223], off
	s_mov_b32 m0, s61
	s_nop 0
	global_load_lds_dwordx4 v[224:225], off
	s_waitcnt vmcnt(8)
	s_waitcnt lgkmcnt(0)
	s_barrier
; #define PG8_STAGE(bufoff, gbase, voff) do { _Pragma("unroll") for (int _i = 0; _i < 2; ++_i) \
;         __builtin_amdgcn_global_load_lds((const unsigned*)((const char*)(gbase) + (voff)[_i]), (PG8_LAS unsigned*)(lds + (bufoff) + ldsw + _i * 8192), 16, 0, 0); } while (0)
; #define PG8_LDA(dst, b, h) do { _Pragma("unroll") for (int m = 0; m < 4; ++m) _Pragma("unroll") for (int k = 0; k < 2; ++k) dst[m][k] = *(const PG8_LAS bf16x8*)(lds + PG8_SA(b, h) + aoff + m * 2048 + k * 1024); } while (0)
; #define PG8_LDB(dst, b, h) do { _Pragma("unroll") for (int n = 0; n < 2; ++n) _Pragma("unroll") for (int k = 0; k < 2; ++k) dst[n][k] = *(const PG8_LAS bf16x8*)(lds + PG8_SB(b, h) + boff + n * 2048 + k * 1024); } while (0)
; #define PG8_MMA(ai, bj, At, Bt) do { __builtin_amdgcn_s_setprio(1); _Pragma("unroll") for (int m = 0; m < 4; ++m) _Pragma("unroll") for (int n = 0; n < 2; ++n) _Pragma("unroll") for (int k = 0; k < 2; ++k) \
;         acc[ai][bj][m][n] = __builtin_amdgcn_mfma_f32_16x16x32_bf16(Bt[n][k], At[m][k], acc[ai][bj][m][n], 0, 0, 0); __builtin_amdgcn_s_setprio(0); } while (0)
; #define PG8_WAIT_V(n) asm volatile("s_waitcnt vmcnt(" #n ")" ::: "memory")
; #define PG8_WAIT_L(n) asm volatile("s_waitcnt lgkmcnt(" #n ")" ::: "memory")
; #define PG8_BAR __builtin_amdgcn_s_barrier()
; #define PG8_SCHED __builtin_amdgcn_sched_barrier(0)
; template <class Epi, class Sched, bool ALIGN_EPI = false, bool SP2 = false>
; __device__ __forceinline__ void gemm_phase(PG8_LAS unsigned char* lds, const Gemm g, const Sched& S, const Epi& E) {
;     ...
;             PG8_WAIT_V(8); PG8_WAIT_L(0); PG8_BAR; PG8_MMA(1, 0, At, B0); PG8_MMA(1, 1, At, B1); PG8_BAR; PG8_SCHED;
;             PG8_LDB(B0, 1, 0); PG8_LDB(B1, 1, 1); PG8_SCHED; PG8_LDA(At, 1, 0); PG8_STAGE(PG8_SA(0, 1), a2 + hstep, voffA);
;             PG8_WAIT_V(8); PG8_WAIT_L(0); PG8_BAR; PG8_MMA(0, 0, At, B0); PG8_MMA(0, 1, At, B1); PG8_BAR; PG8_SCHED;
	s_setprio 1
	s_waitcnt lgkmcnt(0)
	v_mfma_f32_16x16x32_bf16 v[60:63], v[128:131], v[188:191], v[60:63]
	v_mfma_f32_16x16x32_bf16 v[56:59], v[136:139], v[188:191], v[56:59]
	v_mfma_f32_16x16x32_bf16 v[44:47], v[136:139], v[196:199], v[44:47]
	v_mfma_f32_16x16x32_bf16 v[48:51], v[128:131], v[196:199], v[48:51]
	v_mfma_f32_16x16x32_bf16 v[36:39], v[128:131], v[204:207], v[36:39]
	v_mfma_f32_16x16x32_bf16 v[28:31], v[136:139], v[204:207], v[28:31]
	v_mfma_f32_16x16x32_bf16 v[12:15], v[136:139], v[212:215], v[12:15]
	v_mfma_f32_16x16x32_bf16 v[20:23], v[128:131], v[212:215], v[20:23]
	v_mfma_f32_16x16x32_bf16 v[60:63], v[132:135], v[192:195], v[60:63]
	v_mfma_f32_16x16x32_bf16 v[56:59], v[140:143], v[192:195], v[56:59]
	v_mfma_f32_16x16x32_bf16 v[44:47], v[140:143], v[200:203], v[44:47]
	v_mfma_f32_16x16x32_bf16 v[48:51], v[132:135], v[200:203], v[48:51]
	v_mfma_f32_16x16x32_bf16 v[36:39], v[132:135], v[208:211], v[36:39]
	v_mfma_f32_16x16x32_bf16 v[28:31], v[140:143], v[208:211], v[28:31]
	v_mfma_f32_16x16x32_bf16 v[12:15], v[140:143], v[216:219], v[12:15]
	v_mfma_f32_16x16x32_bf16 v[20:23], v[132:135], v[216:219], v[20:23]
	s_setprio 0
	s_setprio 1
	v_mfma_f32_16x16x32_bf16 v[52:55], v[160:163], v[188:191], v[52:55]
	v_mfma_f32_16x16x32_bf16 v[40:43], v[174:177], v[188:191], v[40:43]
	v_mfma_f32_16x16x32_bf16 v[24:27], v[174:177], v[196:199], v[24:27]
	v_mfma_f32_16x16x32_bf16 v[32:35], v[160:163], v[196:199], v[32:35]
	v_mfma_f32_16x16x32_bf16 v[16:19], v[160:163], v[204:207], v[16:19]
	v_mfma_f32_16x16x32_bf16 v[8:11], v[174:177], v[204:207], v[8:11]
	v_mfma_f32_16x16x32_bf16 v[0:3], v[174:177], v[212:215], v[0:3]
	v_mfma_f32_16x16x32_bf16 v[4:7], v[160:163], v[212:215], v[4:7]
	v_mfma_f32_16x16x32_bf16 v[52:55], v[170:173], v[192:195], v[52:55]
	v_mfma_f32_16x16x32_bf16 v[40:43], v[178:181], v[192:195], v[40:43]
	v_mfma_f32_16x16x32_bf16 v[24:27], v[178:181], v[200:203], v[24:27]
	v_mfma_f32_16x16x32_bf16 v[32:35], v[170:173], v[200:203], v[32:35]
	v_mfma_f32_16x16x32_bf16 v[16:19], v[170:173], v[208:211], v[16:19]
	v_mfma_f32_16x16x32_bf16 v[8:11], v[178:181], v[208:211], v[8:11]
	v_mfma_f32_16x16x32_bf16 v[0:3], v[178:181], v[216:219], v[0:3]
	v_mfma_f32_16x16x32_bf16 v[4:7], v[170:173], v[216:219], v[4:7]
	s_setprio 0
	s_barrier
	s_add_i32 s12, 0, 0x18000
	s_add_i32 s13, 0, 0x1c000
	v_add_u32_e32 v140, s12, v165
	v_add_u32_e32 v178, s13, v165
	ds_read_b128 v[128:131], v140
	ds_read_b128 v[132:135], v140 offset:1024
	ds_read_b128 v[136:139], v140 offset:2048
	ds_read_b128 v[140:143], v140 offset:3072
	ds_read_b128 v[160:163], v178
	ds_read_b128 v[170:173], v178 offset:1024
	ds_read_b128 v[174:177], v178 offset:2048
	ds_read_b128 v[178:181], v178 offset:3072
	s_add_u32 s54, s54, 0x40000
	s_addc_u32 s55, s55, 0
	s_mov_b32 m0, s62
	v_lshl_add_u64 v[226:227], s[54:55], 0, v[144:145]
	ds_read_b128 v[188:191], v169 offset:32768
	ds_read_b128 v[192:195], v169 offset:33792
	ds_read_b128 v[196:199], v169 offset:34816
	ds_read_b128 v[200:203], v169 offset:35840
	ds_read_b128 v[204:207], v169 offset:36864
	ds_read_b128 v[208:211], v169 offset:37888
	ds_read_b128 v[212:215], v169 offset:38912
	ds_read_b128 v[216:219], v169 offset:39936
	global_load_lds_dwordx4 v[226:227], off
	v_lshl_add_u64 v[226:227], s[54:55], 0, v[148:149]
	s_mov_b32 m0, s63
	s_nop 0
	global_load_lds_dwordx4 v[226:227], off
	s_waitcnt vmcnt(8)
	s_waitcnt lgkmcnt(0)
	s_barrier
	s_setprio 1
	s_waitcnt lgkmcnt(0)
	v_mfma_f32_16x16x32_bf16 v[124:127], v[128:131], v[188:191], v[124:127]
	v_mfma_f32_16x16x32_bf16 v[120:123], v[136:139], v[188:191], v[120:123]
	v_mfma_f32_16x16x32_bf16 v[108:111], v[136:139], v[196:199], v[108:111]
	v_mfma_f32_16x16x32_bf16 v[116:119], v[128:131], v[196:199], v[116:119]
	v_mfma_f32_16x16x32_bf16 v[100:103], v[128:131], v[204:207], v[100:103]
	v_mfma_f32_16x16x32_bf16 v[92:95], v[136:139], v[204:207], v[92:95]
	v_mfma_f32_16x16x32_bf16 v[76:79], v[136:139], v[212:215], v[76:79]
	v_mfma_f32_16x16x32_bf16 v[84:87], v[128:131], v[212:215], v[84:87]
	v_mfma_f32_16x16x32_bf16 v[124:127], v[132:135], v[192:195], v[124:127]
	v_mfma_f32_16x16x32_bf16 v[120:123], v[140:143], v[192:195], v[120:123]
	v_mfma_f32_16x16x32_bf16 v[108:111], v[140:143], v[200:203], v[108:111]
	v_mfma_f32_16x16x32_bf16 v[116:119], v[132:135], v[200:203], v[116:119]
	v_mfma_f32_16x16x32_bf16 v[100:103], v[132:135], v[208:211], v[100:103]
	v_mfma_f32_16x16x32_bf16 v[92:95], v[140:143], v[208:211], v[92:95]
	v_mfma_f32_16x16x32_bf16 v[76:79], v[140:143], v[216:219], v[76:79]
	v_mfma_f32_16x16x32_bf16 v[84:87], v[132:135], v[216:219], v[84:87]
	s_setprio 0
	s_setprio 1
	v_mfma_f32_16x16x32_bf16 v[112:115], v[160:163], v[188:191], v[112:115]
	v_mfma_f32_16x16x32_bf16 v[104:107], v[174:177], v[188:191], v[104:107]
	v_mfma_f32_16x16x32_bf16 v[88:91], v[174:177], v[196:199], v[88:91]
	v_mfma_f32_16x16x32_bf16 v[96:99], v[160:163], v[196:199], v[96:99]
	v_mfma_f32_16x16x32_bf16 v[80:83], v[160:163], v[204:207], v[80:83]
	v_mfma_f32_16x16x32_bf16 v[72:75], v[174:177], v[204:207], v[72:75]
	v_mfma_f32_16x16x32_bf16 v[64:67], v[174:177], v[212:215], v[64:67]
	v_mfma_f32_16x16x32_bf16 v[68:71], v[160:163], v[212:215], v[68:71]
	v_mfma_f32_16x16x32_bf16 v[112:115], v[170:173], v[192:195], v[112:115]
	v_mfma_f32_16x16x32_bf16 v[104:107], v[178:181], v[192:195], v[104:107]
	v_mfma_f32_16x16x32_bf16 v[88:91], v[178:181], v[200:203], v[88:91]
	v_mfma_f32_16x16x32_bf16 v[96:99], v[170:173], v[200:203], v[96:99]
	v_mfma_f32_16x16x32_bf16 v[80:83], v[170:173], v[208:211], v[80:83]
	v_mfma_f32_16x16x32_bf16 v[72:75], v[178:181], v[208:211], v[72:75]
	v_mfma_f32_16x16x32_bf16 v[64:67], v[178:181], v[216:219], v[64:67]
	v_mfma_f32_16x16x32_bf16 v[68:71], v[170:173], v[216:219], v[68:71]
	s_setprio 0
	s_barrier
; #define PG8_STAGE(bufoff, gbase, voff) do { _Pragma("unroll") for (int _i = 0; _i < 2; ++_i) \
;         __builtin_amdgcn_global_load_lds((const unsigned*)((const char*)(gbase) + (voff)[_i]), (PG8_LAS unsigned*)(lds + (bufoff) + ldsw + _i * 8192), 16, 0, 0); } while (0)
; #define PG8_LDA(dst, b, h) do { _Pragma("unroll") for (int m = 0; m < 4; ++m) _Pragma("unroll") for (int k = 0; k < 2; ++k) dst[m][k] = *(const PG8_LAS bf16x8*)(lds + PG8_SA(b, h) + aoff + m * 2048 + k * 1024); } while (0)
; #define PG8_MMA(ai, bj, At, Bt) do { __builtin_amdgcn_s_setprio(1); _Pragma("unroll") for (int m = 0; m < 4; ++m) _Pragma("unroll") for (int n = 0; n < 2; ++n) _Pragma("unroll") for (int k = 0; k < 2; ++k) \
;         acc[ai][bj][m][n] = __builtin_amdgcn_mfma_f32_16x16x32_bf16(Bt[n][k], At[m][k], acc[ai][bj][m][n], 0, 0, 0); __builtin_amdgcn_s_setprio(0); } while (0)
; #define PG8_WAIT_V(n) asm volatile("s_waitcnt vmcnt(" #n ")" ::: "memory")
; #define PG8_WAIT_L(n) asm volatile("s_waitcnt lgkmcnt(" #n ")" ::: "memory")
; #define PG8_BAR __builtin_amdgcn_s_barrier()
; #define PG8_SCHED __builtin_amdgcn_sched_barrier(0)
; template <class Epi, class Sched, bool ALIGN_EPI = false, bool SP2 = false>
; __device__ __forceinline__ void gemm_phase(PG8_LAS unsigned char* lds, const Gemm g, const Sched& S, const Epi& E) {
;     ...
;         for (int t = 0; t < nt; t += 2) {
;             const bool last = (t == nt - 2);
;             const char* a1 = cA + (size_t)(t + 1) * kstep;
;             const char* a2 = last ? nA : cA + (size_t)(t + 2) * kstep; const char* b2 = last ? nB : cB + (size_t)(t + 2) * kstep;
;             const char* a3 = a2 + kstep; const char* b3 = b2 + kstep;
;     ...
;             PG8_LDA(At, 1, 1); PG8_STAGE(PG8_SB(1, 0), b3, voffB); PG8_STAGE(PG8_SB(1, 1), b3 + hstep, voffB); PG8_STAGE(PG8_SA(1, 0), a3, voffA);
;             PG8_WAIT_V(8); PG8_WAIT_L(0); PG8_BAR; PG8_MMA(1, 0, At, B0); PG8_MMA(1, 1, At, B1); PG8_BAR; PG8_SCHED;
	s_add_i32 s12, s12, s59
	v_lshl_add_u64 v[184:185], v[184:185], 0, s[22:23]
	s_mov_b32 m0, s12
	ds_read_b128 v[188:191], v169 offset:49152
	ds_read_b128 v[192:195], v169 offset:50176
	ds_read_b128 v[196:199], v169 offset:51200
	ds_read_b128 v[200:203], v169 offset:52224
	ds_read_b128 v[204:207], v169 offset:53248
	ds_read_b128 v[208:211], v169 offset:54272
	ds_read_b128 v[212:215], v169 offset:55296
	ds_read_b128 v[216:219], v169 offset:56320
	global_load_lds_dwordx4 v[184:185], off
	s_add_i32 m0, s12, 0x2000
	s_add_u32 s52, s52, 0x40080
	v_lshl_add_u64 v[184:185], v[220:221], 0, s[22:23]
	s_addc_u32 s53, s53, 0
	s_add_i32 s12, s13, s59
	global_load_lds_dwordx4 v[184:185], off
	v_lshl_add_u64 v[184:185], s[52:53], 0, v[146:147]
	s_mov_b32 m0, s12
	s_nop 0
	global_load_lds_dwordx4 v[184:185], off
	v_lshl_add_u64 v[184:185], s[52:53], 0, v[150:151]
	s_add_i32 m0, s12, 0x2000
	s_nop 0
	global_load_lds_dwordx4 v[184:185], off
	v_lshl_add_u64 v[184:185], v[222:223], 0, s[22:23]
	s_mov_b32 m0, s69
	s_nop 0
	global_load_lds_dwordx4 v[184:185], off
	v_lshl_add_u64 v[184:185], v[224:225], 0, s[22:23]
	s_mov_b32 m0, s70
	s_nop 0
	global_load_lds_dwordx4 v[184:185], off
	s_waitcnt vmcnt(8)
	s_waitcnt lgkmcnt(0)
	s_barrier
	s_setprio 1
	s_waitcnt lgkmcnt(0)
	v_mfma_f32_16x16x32_bf16 v[60:63], v[128:131], v[188:191], v[60:63]
	v_mfma_f32_16x16x32_bf16 v[56:59], v[136:139], v[188:191], v[56:59]
	v_mfma_f32_16x16x32_bf16 v[44:47], v[136:139], v[196:199], v[44:47]
	v_mfma_f32_16x16x32_bf16 v[48:51], v[128:131], v[196:199], v[48:51]
	v_mfma_f32_16x16x32_bf16 v[36:39], v[128:131], v[204:207], v[36:39]
	v_mfma_f32_16x16x32_bf16 v[28:31], v[136:139], v[204:207], v[28:31]
	v_mfma_f32_16x16x32_bf16 v[12:15], v[136:139], v[212:215], v[12:15]
	v_mfma_f32_16x16x32_bf16 v[20:23], v[128:131], v[212:215], v[20:23]
	v_mfma_f32_16x16x32_bf16 v[60:63], v[132:135], v[192:195], v[60:63]
	v_mfma_f32_16x16x32_bf16 v[56:59], v[140:143], v[192:195], v[56:59]
	v_mfma_f32_16x16x32_bf16 v[44:47], v[140:143], v[200:203], v[44:47]
	v_mfma_f32_16x16x32_bf16 v[48:51], v[132:135], v[200:203], v[48:51]
	v_mfma_f32_16x16x32_bf16 v[36:39], v[132:135], v[208:211], v[36:39]
	v_mfma_f32_16x16x32_bf16 v[28:31], v[140:143], v[208:211], v[28:31]
	v_mfma_f32_16x16x32_bf16 v[12:15], v[140:143], v[216:219], v[12:15]
	v_mfma_f32_16x16x32_bf16 v[20:23], v[132:135], v[216:219], v[20:23]
	s_setprio 0
	s_setprio 1
	v_mfma_f32_16x16x32_bf16 v[52:55], v[160:163], v[188:191], v[52:55]
	v_mfma_f32_16x16x32_bf16 v[40:43], v[174:177], v[188:191], v[40:43]
	v_mfma_f32_16x16x32_bf16 v[24:27], v[174:177], v[196:199], v[24:27]
	v_mfma_f32_16x16x32_bf16 v[32:35], v[160:163], v[196:199], v[32:35]
	v_mfma_f32_16x16x32_bf16 v[16:19], v[160:163], v[204:207], v[16:19]
	v_mfma_f32_16x16x32_bf16 v[8:11], v[174:177], v[204:207], v[8:11]
	v_mfma_f32_16x16x32_bf16 v[0:3], v[174:177], v[212:215], v[0:3]
	v_mfma_f32_16x16x32_bf16 v[4:7], v[160:163], v[212:215], v[4:7]
	v_mfma_f32_16x16x32_bf16 v[52:55], v[170:173], v[192:195], v[52:55]
	v_mfma_f32_16x16x32_bf16 v[40:43], v[178:181], v[192:195], v[40:43]
	v_mfma_f32_16x16x32_bf16 v[24:27], v[178:181], v[200:203], v[24:27]
	v_mfma_f32_16x16x32_bf16 v[32:35], v[170:173], v[200:203], v[32:35]
	v_mfma_f32_16x16x32_bf16 v[16:19], v[170:173], v[208:211], v[16:19]
	v_mfma_f32_16x16x32_bf16 v[8:11], v[178:181], v[208:211], v[8:11]
	v_mfma_f32_16x16x32_bf16 v[0:3], v[178:181], v[216:219], v[0:3]
	v_mfma_f32_16x16x32_bf16 v[4:7], v[170:173], v[216:219], v[4:7]
	s_setprio 0
	s_barrier
	s_add_i32 s79, s79, 2
	s_add_u32 s77, s77, 0x100
	s_addc_u32 s78, s78, 0
	s_add_u32 s50, s50, 0x100
	s_addc_u32 s51, s51, 0
	s_cmp_gt_u32 s79, 13
	s_cbranch_scc0 .LBB0_1272
	s_and_b64 vcc, exec, s[36:37]
	s_cbranch_vccz .LBB0_1275
	s_barrier

; #define PG8_STAGE(bufoff, gbase, voff) do { _Pragma("unroll") for (int _i = 0; _i < 2; ++_i) \
;         __builtin_amdgcn_global_load_lds((const unsigned*)((const char*)(gbase) + (voff)[_i]), (PG8_LAS unsigned*)(lds + (bufoff) + ldsw + _i * 8192), 16, 0, 0); } while (0)
; #define PG8_LDA(dst, b, h) do { _Pragma("unroll") for (int m = 0; m < 4; ++m) _Pragma("unroll") for (int k = 0; k < 2; ++k) dst[m][k] = *(const PG8_LAS bf16x8*)(lds + PG8_SA(b, h) + aoff + m * 2048 + k * 1024); } while (0)
; #define PG8_LDB(dst, b, h) do { _Pragma("unroll") for (int n = 0; n < 2; ++n) _Pragma("unroll") for (int k = 0; k < 2; ++k) dst[n][k] = *(const PG8_LAS bf16x8*)(lds + PG8_SB(b, h) + boff + n * 2048 + k * 1024); } while (0)
; #define PG8_MMA(ai, bj, At, Bt) do { __builtin_amdgcn_s_setprio(1); _Pragma("unroll") for (int m = 0; m < 4; ++m) _Pragma("unroll") for (int n = 0; n < 2; ++n) _Pragma("unroll") for (int k = 0; k < 2; ++k) \
;         acc[ai][bj][m][n] = __builtin_amdgcn_mfma_f32_16x16x32_bf16(Bt[n][k], At[m][k], acc[ai][bj][m][n], 0, 0, 0); __builtin_amdgcn_s_setprio(0); } while (0)
; #define PG8_WAIT_V(n) asm volatile("s_waitcnt vmcnt(" #n ")" ::: "memory")
; #define PG8_WAIT_L(n) asm volatile("s_waitcnt lgkmcnt(" #n ")" ::: "memory")
; #define PG8_BAR __builtin_amdgcn_s_barrier()
; #define PG8_SCHED __builtin_amdgcn_sched_barrier(0)
; template <class Epi, class Sched, bool ALIGN_EPI = false, bool SP2 = false>
; __device__ __forceinline__ void gemm_phase(PG8_LAS unsigned char* lds, const Gemm g, const Sched& S, const Epi& E) {
;     ...
;             PG8_LDB(B0, 0, 0); PG8_LDB(B1, 0, 1); PG8_SCHED; PG8_LDA(At, 0, 0); PG8_STAGE(PG8_SA(1, 1), a1 + hstep, voffA);
;             PG8_WAIT_V(8); PG8_WAIT_L(0); PG8_BAR; PG8_MMA(0, 0, At, B0); PG8_MMA(0, 1, At, B1); PG8_BAR; PG8_SCHED;
;             PG8_LDA(At, 0, 1); PG8_STAGE(PG8_SB(0, 0), b2, voffB); PG8_STAGE(PG8_SB(0, 1), b2 + hstep, voffB); PG8_STAGE(PG8_SA(0, 0), a2, voffA);
.LBB0_1358:
	v_add_u32_e32 v130, s71, v163
	ds_read_b128 v[118:121], v130
	ds_read_b128 v[122:125], v130 offset:1024
	ds_read_b128 v[126:129], v130 offset:2048
	ds_read_b128 v[170:173], v130 offset:3072
	v_add_u32_e32 v130, s72, v163
	ds_read_b128 v[174:177], v130
	ds_read_b128 v[178:181], v130 offset:1024
	ds_read_b128 v[184:187], v130 offset:2048
	ds_read_b128 v[188:191], v130 offset:3072
	s_add_u32 s14, s48, 0xfffc0080
	s_addc_u32 s15, s49, -1
	s_and_b64 s[50:51], s[50:51], exec
	s_cselect_b32 s53, s39, s15
	s_cselect_b32 s52, s73, s14
	s_cselect_b32 s51, s37, s47
	s_cselect_b32 s50, s74, s45
	v_lshl_add_u64 v[130:131], s[48:49], 0, v[154:155]
	s_add_i32 m0, s58, 0xc000
	ds_read_b128 v[192:195], v168
	ds_read_b128 v[196:199], v168 offset:1024
	ds_read_b128 v[200:203], v168 offset:2048
	ds_read_b128 v[204:207], v168 offset:3072
	ds_read_b128 v[208:211], v168 offset:4096
	ds_read_b128 v[212:215], v168 offset:5120
	ds_read_b128 v[216:219], v168 offset:6144
	ds_read_b128 v[220:223], v168 offset:7168
	global_load_lds_dwordx4 v[130:131], off
	v_lshl_add_u64 v[130:131], s[48:49], 0, v[152:153]
	s_add_i32 m0, s58, 0xe000
	s_nop 0
	global_load_lds_dwordx4 v[130:131], off
	s_waitcnt vmcnt(8)
	s_waitcnt lgkmcnt(0)
	s_barrier
	s_setprio 1
	s_waitcnt lgkmcnt(0)
	v_mfma_f32_16x16x32_bf16 v[140:143], v[118:121], v[192:195], v[140:143]
	v_mfma_f32_16x16x32_bf16 v[136:139], v[126:129], v[192:195], v[136:139]
	v_mfma_f32_16x16x32_bf16 v[104:107], v[126:129], v[200:203], v[104:107]
	v_mfma_f32_16x16x32_bf16 v[108:111], v[118:121], v[200:203], v[108:111]
	v_mfma_f32_16x16x32_bf16 v[92:95], v[118:121], v[208:211], v[92:95]
	v_mfma_f32_16x16x32_bf16 v[88:91], v[126:129], v[208:211], v[88:91]
	v_mfma_f32_16x16x32_bf16 v[72:75], v[126:129], v[216:219], v[72:75]
	v_mfma_f32_16x16x32_bf16 v[76:79], v[118:121], v[216:219], v[76:79]
	v_mfma_f32_16x16x32_bf16 v[140:143], v[122:125], v[196:199], v[140:143]
	v_mfma_f32_16x16x32_bf16 v[136:139], v[170:173], v[196:199], v[136:139]
	v_mfma_f32_16x16x32_bf16 v[104:107], v[170:173], v[204:207], v[104:107]
	v_mfma_f32_16x16x32_bf16 v[108:111], v[122:125], v[204:207], v[108:111]
	v_mfma_f32_16x16x32_bf16 v[92:95], v[122:125], v[212:215], v[92:95]
	v_mfma_f32_16x16x32_bf16 v[88:91], v[170:173], v[212:215], v[88:91]
	v_mfma_f32_16x16x32_bf16 v[72:75], v[170:173], v[220:223], v[72:75]
	v_mfma_f32_16x16x32_bf16 v[76:79], v[122:125], v[220:223], v[76:79]
	s_setprio 0
	s_setprio 1
	v_mfma_f32_16x16x32_bf16 v[130:133], v[174:177], v[192:195], v[132:135]
	v_mfma_f32_16x16x32_bf16 v[112:115], v[184:187], v[192:195], v[112:115]
	v_mfma_f32_16x16x32_bf16 v[96:99], v[184:187], v[200:203], v[96:99]
	v_mfma_f32_16x16x32_bf16 v[100:103], v[174:177], v[200:203], v[100:103]
	v_mfma_f32_16x16x32_bf16 v[84:87], v[174:177], v[208:211], v[84:87]
	v_mfma_f32_16x16x32_bf16 v[80:83], v[184:187], v[208:211], v[80:83]
	v_mfma_f32_16x16x32_bf16 v[64:67], v[184:187], v[216:219], v[64:67]
	v_mfma_f32_16x16x32_bf16 v[68:71], v[174:177], v[216:219], v[68:71]
	v_mfma_f32_16x16x32_bf16 v[130:133], v[178:181], v[196:199], v[130:133]
	v_mfma_f32_16x16x32_bf16 v[112:115], v[188:191], v[196:199], v[112:115]
	v_mfma_f32_16x16x32_bf16 v[96:99], v[188:191], v[204:207], v[96:99]
	v_mfma_f32_16x16x32_bf16 v[100:103], v[178:181], v[204:207], v[100:103]
	v_mfma_f32_16x16x32_bf16 v[84:87], v[178:181], v[212:215], v[84:87]
	v_mfma_f32_16x16x32_bf16 v[80:83], v[188:191], v[212:215], v[80:83]
	v_mfma_f32_16x16x32_bf16 v[64:67], v[188:191], v[220:223], v[64:67]
	v_mfma_f32_16x16x32_bf16 v[68:71], v[178:181], v[220:223], v[68:71]
	s_setprio 0
	s_barrier
	s_add_i32 s14, s71, s55
	v_lshl_add_u64 v[224:225], s[50:51], 0, v[148:149]
	s_mov_b32 m0, s14
	ds_read_b128 v[192:195], v168 offset:16384
	ds_read_b128 v[196:199], v168 offset:17408
	ds_read_b128 v[200:203], v168 offset:18432
	ds_read_b128 v[204:207], v168 offset:19456
	ds_read_b128 v[208:211], v168 offset:20480
	ds_read_b128 v[212:215], v168 offset:21504
	ds_read_b128 v[216:219], v168 offset:22528
	ds_read_b128 v[220:223], v168 offset:23552
	global_load_lds_dwordx4 v[224:225], off
	s_add_i32 m0, s14, 0x2000
	s_add_u32 s76, s50, 0x40000
	v_lshl_add_u64 v[226:227], s[50:51], 0, v[144:145]
	s_addc_u32 s77, s51, 0
	s_add_i32 s14, s72, s55
	global_load_lds_dwordx4 v[226:227], off
	v_lshl_add_u64 v[134:135], s[76:77], 0, v[148:149]
	s_mov_b32 m0, s14
	v_lshl_add_u64 v[228:229], s[52:53], 0, v[150:151]
	global_load_lds_dwordx4 v[134:135], off
	v_lshl_add_u64 v[134:135], s[76:77], 0, v[144:145]
	s_add_i32 m0, s14, 0x2000
	v_lshl_add_u64 v[230:231], s[52:53], 0, v[146:147]
	global_load_lds_dwordx4 v[134:135], off
	s_mov_b32 m0, s58
	s_nop 0
	global_load_lds_dwordx4 v[228:229], off
	s_mov_b32 m0, s59
	s_nop 0
	global_load_lds_dwordx4 v[230:231], off
	s_waitcnt vmcnt(8)
	s_waitcnt lgkmcnt(0)
	s_barrier
; #define PG8_STAGE(bufoff, gbase, voff) do { _Pragma("unroll") for (int _i = 0; _i < 2; ++_i) \
;         __builtin_amdgcn_global_load_lds((const unsigned*)((const char*)(gbase) + (voff)[_i]), (PG8_LAS unsigned*)(lds + (bufoff) + ldsw + _i * 8192), 16, 0, 0); } while (0)
; #define PG8_LDA(dst, b, h) do { _Pragma("unroll") for (int m = 0; m < 4; ++m) _Pragma("unroll") for (int k = 0; k < 2; ++k) dst[m][k] = *(const PG8_LAS bf16x8*)(lds + PG8_SA(b, h) + aoff + m * 2048 + k * 1024); } while (0)
; #define PG8_LDB(dst, b, h) do { _Pragma("unroll") for (int n = 0; n < 2; ++n) _Pragma("unroll") for (int k = 0; k < 2; ++k) dst[n][k] = *(const PG8_LAS bf16x8*)(lds + PG8_SB(b, h) + boff + n * 2048 + k * 1024); } while (0)
; #define PG8_MMA(ai, bj, At, Bt) do { __builtin_amdgcn_s_setprio(1); _Pragma("unroll") for (int m = 0; m < 4; ++m) _Pragma("unroll") for (int n = 0; n < 2; ++n) _Pragma("unroll") for (int k = 0; k < 2; ++k) \
;         acc[ai][bj][m][n] = __builtin_amdgcn_mfma_f32_16x16x32_bf16(Bt[n][k], At[m][k], acc[ai][bj][m][n], 0, 0, 0); __builtin_amdgcn_s_setprio(0); } while (0)
; #define PG8_WAIT_V(n) asm volatile("s_waitcnt vmcnt(" #n ")" ::: "memory")
; #define PG8_WAIT_L(n) asm volatile("s_waitcnt lgkmcnt(" #n ")" ::: "memory")
; #define PG8_BAR __builtin_amdgcn_s_barrier()
; #define PG8_SCHED __builtin_amdgcn_sched_barrier(0)
; template <class Epi, class Sched, bool ALIGN_EPI = false, bool SP2 = false>
; __device__ __forceinline__ void gemm_phase(PG8_LAS unsigned char* lds, const Gemm g, const Sched& S, const Epi& E) {
;     ...
;             PG8_WAIT_V(8); PG8_WAIT_L(0); PG8_BAR; PG8_MMA(1, 0, At, B0); PG8_MMA(1, 1, At, B1); PG8_BAR; PG8_SCHED;
;             PG8_LDB(B0, 1, 0); PG8_LDB(B1, 1, 1); PG8_SCHED; PG8_LDA(At, 1, 0); PG8_STAGE(PG8_SA(0, 1), a2 + hstep, voffA);
;             PG8_WAIT_V(8); PG8_WAIT_L(0); PG8_BAR; PG8_MMA(0, 0, At, B0); PG8_MMA(0, 1, At, B1); PG8_BAR; PG8_SCHED;
	s_setprio 1
	s_waitcnt lgkmcnt(0)
	v_mfma_f32_16x16x32_bf16 v[60:63], v[118:121], v[192:195], v[60:63]
	v_mfma_f32_16x16x32_bf16 v[56:59], v[126:129], v[192:195], v[56:59]
	v_mfma_f32_16x16x32_bf16 v[40:43], v[126:129], v[200:203], v[40:43]
	v_mfma_f32_16x16x32_bf16 v[44:47], v[118:121], v[200:203], v[44:47]
	v_mfma_f32_16x16x32_bf16 v[28:31], v[118:121], v[208:211], v[28:31]
	v_mfma_f32_16x16x32_bf16 v[24:27], v[126:129], v[208:211], v[24:27]
	v_mfma_f32_16x16x32_bf16 v[8:11], v[126:129], v[216:219], v[8:11]
	v_mfma_f32_16x16x32_bf16 v[12:15], v[118:121], v[216:219], v[12:15]
	v_mfma_f32_16x16x32_bf16 v[60:63], v[122:125], v[196:199], v[60:63]
	v_mfma_f32_16x16x32_bf16 v[56:59], v[170:173], v[196:199], v[56:59]
	v_mfma_f32_16x16x32_bf16 v[40:43], v[170:173], v[204:207], v[40:43]
	v_mfma_f32_16x16x32_bf16 v[44:47], v[122:125], v[204:207], v[44:47]
	v_mfma_f32_16x16x32_bf16 v[28:31], v[122:125], v[212:215], v[28:31]
	v_mfma_f32_16x16x32_bf16 v[24:27], v[170:173], v[212:215], v[24:27]
	v_mfma_f32_16x16x32_bf16 v[8:11], v[170:173], v[220:223], v[8:11]
	v_mfma_f32_16x16x32_bf16 v[12:15], v[122:125], v[220:223], v[12:15]
	s_setprio 0
	s_setprio 1
	v_mfma_f32_16x16x32_bf16 v[52:55], v[174:177], v[192:195], v[52:55]
	v_mfma_f32_16x16x32_bf16 v[48:51], v[184:187], v[192:195], v[48:51]
	v_mfma_f32_16x16x32_bf16 v[32:35], v[184:187], v[200:203], v[32:35]
	v_mfma_f32_16x16x32_bf16 v[36:39], v[174:177], v[200:203], v[36:39]
	v_mfma_f32_16x16x32_bf16 v[20:23], v[174:177], v[208:211], v[20:23]
	v_mfma_f32_16x16x32_bf16 v[16:19], v[184:187], v[208:211], v[16:19]
	v_mfma_f32_16x16x32_bf16 v[0:3], v[184:187], v[216:219], v[0:3]
	v_mfma_f32_16x16x32_bf16 v[4:7], v[174:177], v[216:219], v[4:7]
	v_mfma_f32_16x16x32_bf16 v[52:55], v[178:181], v[196:199], v[52:55]
	v_mfma_f32_16x16x32_bf16 v[48:51], v[188:191], v[196:199], v[48:51]
	v_mfma_f32_16x16x32_bf16 v[32:35], v[188:191], v[204:207], v[32:35]
	v_mfma_f32_16x16x32_bf16 v[36:39], v[178:181], v[204:207], v[36:39]
	v_mfma_f32_16x16x32_bf16 v[20:23], v[178:181], v[212:215], v[20:23]
	v_mfma_f32_16x16x32_bf16 v[16:19], v[188:191], v[212:215], v[16:19]
	v_mfma_f32_16x16x32_bf16 v[0:3], v[188:191], v[220:223], v[0:3]
	v_mfma_f32_16x16x32_bf16 v[4:7], v[178:181], v[220:223], v[4:7]
	s_setprio 0
	s_barrier
	s_add_i32 s14, 0, 0x18000
	v_add_u32_e32 v134, s14, v163
	s_add_i32 s15, 0, 0x1c000
	ds_read_b128 v[118:121], v134
	ds_read_b128 v[122:125], v134 offset:1024
	ds_read_b128 v[126:129], v134 offset:2048
	ds_read_b128 v[170:173], v134 offset:3072
	v_add_u32_e32 v134, s15, v163
	ds_read_b128 v[174:177], v134
	ds_read_b128 v[178:181], v134 offset:1024
	ds_read_b128 v[184:187], v134 offset:2048
	ds_read_b128 v[188:191], v134 offset:3072
	s_add_u32 s52, s52, 0x40000
	s_addc_u32 s53, s53, 0
	s_mov_b32 m0, s60
	v_lshl_add_u64 v[134:135], s[52:53], 0, v[150:151]
	ds_read_b128 v[192:195], v168 offset:32768
	ds_read_b128 v[196:199], v168 offset:33792
	ds_read_b128 v[200:203], v168 offset:34816
	ds_read_b128 v[204:207], v168 offset:35840
	ds_read_b128 v[208:211], v168 offset:36864
	ds_read_b128 v[212:215], v168 offset:37888
	ds_read_b128 v[216:219], v168 offset:38912
	ds_read_b128 v[220:223], v168 offset:39936
	global_load_lds_dwordx4 v[134:135], off
	v_lshl_add_u64 v[134:135], s[52:53], 0, v[146:147]
	s_mov_b32 m0, s61
	s_nop 0
	global_load_lds_dwordx4 v[134:135], off
	s_waitcnt vmcnt(8)
	s_waitcnt lgkmcnt(0)
	s_barrier
	s_setprio 1
	s_waitcnt lgkmcnt(0)
	v_mfma_f32_16x16x32_bf16 v[140:143], v[118:121], v[192:195], v[140:143]
	v_mfma_f32_16x16x32_bf16 v[134:137], v[126:129], v[192:195], v[136:139]
	v_mfma_f32_16x16x32_bf16 v[104:107], v[126:129], v[200:203], v[104:107]
	v_mfma_f32_16x16x32_bf16 v[108:111], v[118:121], v[200:203], v[108:111]
	v_mfma_f32_16x16x32_bf16 v[92:95], v[118:121], v[208:211], v[92:95]
	v_mfma_f32_16x16x32_bf16 v[88:91], v[126:129], v[208:211], v[88:91]
	v_mfma_f32_16x16x32_bf16 v[72:75], v[126:129], v[216:219], v[72:75]
	v_mfma_f32_16x16x32_bf16 v[76:79], v[118:121], v[216:219], v[76:79]
	v_mfma_f32_16x16x32_bf16 v[140:143], v[122:125], v[196:199], v[140:143]
	v_mfma_f32_16x16x32_bf16 v[136:139], v[170:173], v[196:199], v[134:137]
	v_mfma_f32_16x16x32_bf16 v[104:107], v[170:173], v[204:207], v[104:107]
	v_mfma_f32_16x16x32_bf16 v[108:111], v[122:125], v[204:207], v[108:111]
	v_mfma_f32_16x16x32_bf16 v[92:95], v[122:125], v[212:215], v[92:95]
	v_mfma_f32_16x16x32_bf16 v[88:91], v[170:173], v[212:215], v[88:91]
	v_mfma_f32_16x16x32_bf16 v[72:75], v[170:173], v[220:223], v[72:75]
	v_mfma_f32_16x16x32_bf16 v[76:79], v[122:125], v[220:223], v[76:79]
	s_setprio 0
	s_setprio 1
	v_mfma_f32_16x16x32_bf16 v[130:133], v[174:177], v[192:195], v[130:133]
	v_mfma_f32_16x16x32_bf16 v[112:115], v[184:187], v[192:195], v[112:115]
	v_mfma_f32_16x16x32_bf16 v[96:99], v[184:187], v[200:203], v[96:99]
	v_mfma_f32_16x16x32_bf16 v[100:103], v[174:177], v[200:203], v[100:103]
	v_mfma_f32_16x16x32_bf16 v[84:87], v[174:177], v[208:211], v[84:87]
	v_mfma_f32_16x16x32_bf16 v[80:83], v[184:187], v[208:211], v[80:83]
	v_mfma_f32_16x16x32_bf16 v[64:67], v[184:187], v[216:219], v[64:67]
	v_mfma_f32_16x16x32_bf16 v[68:71], v[174:177], v[216:219], v[68:71]
	v_mfma_f32_16x16x32_bf16 v[132:135], v[178:181], v[196:199], v[130:133]
	v_mfma_f32_16x16x32_bf16 v[112:115], v[188:191], v[196:199], v[112:115]
	v_mfma_f32_16x16x32_bf16 v[96:99], v[188:191], v[204:207], v[96:99]
	v_mfma_f32_16x16x32_bf16 v[100:103], v[178:181], v[204:207], v[100:103]
	v_mfma_f32_16x16x32_bf16 v[84:87], v[178:181], v[212:215], v[84:87]
	v_mfma_f32_16x16x32_bf16 v[80:83], v[188:191], v[212:215], v[80:83]
	v_mfma_f32_16x16x32_bf16 v[64:67], v[188:191], v[220:223], v[64:67]
	v_mfma_f32_16x16x32_bf16 v[68:71], v[178:181], v[220:223], v[68:71]
	s_setprio 0
	s_barrier
; #define PG8_STAGE(bufoff, gbase, voff) do { _Pragma("unroll") for (int _i = 0; _i < 2; ++_i) \
;         __builtin_amdgcn_global_load_lds((const unsigned*)((const char*)(gbase) + (voff)[_i]), (PG8_LAS unsigned*)(lds + (bufoff) + ldsw + _i * 8192), 16, 0, 0); } while (0)
; #define PG8_LDA(dst, b, h) do { _Pragma("unroll") for (int m = 0; m < 4; ++m) _Pragma("unroll") for (int k = 0; k < 2; ++k) dst[m][k] = *(const PG8_LAS bf16x8*)(lds + PG8_SA(b, h) + aoff + m * 2048 + k * 1024); } while (0)
; #define PG8_MMA(ai, bj, At, Bt) do { __builtin_amdgcn_s_setprio(1); _Pragma("unroll") for (int m = 0; m < 4; ++m) _Pragma("unroll") for (int n = 0; n < 2; ++n) _Pragma("unroll") for (int k = 0; k < 2; ++k) \
;         acc[ai][bj][m][n] = __builtin_amdgcn_mfma_f32_16x16x32_bf16(Bt[n][k], At[m][k], acc[ai][bj][m][n], 0, 0, 0); __builtin_amdgcn_s_setprio(0); } while (0)
; #define PG8_WAIT_V(n) asm volatile("s_waitcnt vmcnt(" #n ")" ::: "memory")
; #define PG8_WAIT_L(n) asm volatile("s_waitcnt lgkmcnt(" #n ")" ::: "memory")
; #define PG8_BAR __builtin_amdgcn_s_barrier()
; #define PG8_SCHED __builtin_amdgcn_sched_barrier(0)
; template <class Epi, class Sched, bool ALIGN_EPI = false, bool SP2 = false>
; __device__ __forceinline__ void gemm_phase(PG8_LAS unsigned char* lds, const Gemm g, const Sched& S, const Epi& E) {
;     ...
;         for (int t = 0; t < nt; t += 2) {
;             const bool last = (t == nt - 2);
;             const char* a1 = cA + (size_t)(t + 1) * kstep;
;             const char* a2 = last ? nA : cA + (size_t)(t + 2) * kstep; const char* b2 = last ? nB : cB + (size_t)(t + 2) * kstep;
;             const char* a3 = a2 + kstep; const char* b3 = b2 + kstep;
;     ...
;             PG8_LDA(At, 1, 1); PG8_STAGE(PG8_SB(1, 0), b3, voffB); PG8_STAGE(PG8_SB(1, 1), b3 + hstep, voffB); PG8_STAGE(PG8_SA(1, 0), a3, voffA);
;             PG8_WAIT_V(8); PG8_WAIT_L(0); PG8_BAR; PG8_MMA(1, 0, At, B0); PG8_MMA(1, 1, At, B1); PG8_BAR; PG8_SCHED;
	s_add_i32 s14, s14, s55
	v_lshl_add_u64 v[130:131], v[224:225], 0, s[18:19]
	s_mov_b32 m0, s14
	ds_read_b128 v[192:195], v168 offset:49152
	ds_read_b128 v[196:199], v168 offset:50176
	ds_read_b128 v[200:203], v168 offset:51200
	ds_read_b128 v[204:207], v168 offset:52224
	ds_read_b128 v[208:211], v168 offset:53248
	ds_read_b128 v[212:215], v168 offset:54272
	ds_read_b128 v[216:219], v168 offset:55296
	ds_read_b128 v[220:223], v168 offset:56320
	global_load_lds_dwordx4 v[130:131], off
	s_add_i32 m0, s14, 0x2000
	s_add_u32 s50, s50, 0x40080
	v_lshl_add_u64 v[130:131], v[226:227], 0, s[18:19]
	s_addc_u32 s51, s51, 0
	s_add_i32 s14, s15, s55
	global_load_lds_dwordx4 v[130:131], off
	v_lshl_add_u64 v[130:131], s[50:51], 0, v[148:149]
	s_mov_b32 m0, s14
	s_nop 0
	global_load_lds_dwordx4 v[130:131], off
	v_lshl_add_u64 v[130:131], s[50:51], 0, v[144:145]
	s_add_i32 m0, s14, 0x2000
	s_nop 0
	global_load_lds_dwordx4 v[130:131], off
	v_lshl_add_u64 v[130:131], v[228:229], 0, s[18:19]
	s_mov_b32 m0, s64
	s_nop 0
	global_load_lds_dwordx4 v[130:131], off
	v_lshl_add_u64 v[130:131], v[230:231], 0, s[18:19]
	s_mov_b32 m0, s65
	s_nop 0
	global_load_lds_dwordx4 v[130:131], off
	s_waitcnt vmcnt(8)
	s_waitcnt lgkmcnt(0)
	s_barrier
	s_setprio 1
	s_waitcnt lgkmcnt(0)
	v_mfma_f32_16x16x32_bf16 v[60:63], v[118:121], v[192:195], v[60:63]
	v_mfma_f32_16x16x32_bf16 v[56:59], v[126:129], v[192:195], v[56:59]
	v_mfma_f32_16x16x32_bf16 v[40:43], v[126:129], v[200:203], v[40:43]
	v_mfma_f32_16x16x32_bf16 v[44:47], v[118:121], v[200:203], v[44:47]
	v_mfma_f32_16x16x32_bf16 v[28:31], v[118:121], v[208:211], v[28:31]
	v_mfma_f32_16x16x32_bf16 v[24:27], v[126:129], v[208:211], v[24:27]
	v_mfma_f32_16x16x32_bf16 v[8:11], v[126:129], v[216:219], v[8:11]
	v_mfma_f32_16x16x32_bf16 v[12:15], v[118:121], v[216:219], v[12:15]
	v_mfma_f32_16x16x32_bf16 v[60:63], v[122:125], v[196:199], v[60:63]
	v_mfma_f32_16x16x32_bf16 v[56:59], v[170:173], v[196:199], v[56:59]
	v_mfma_f32_16x16x32_bf16 v[40:43], v[170:173], v[204:207], v[40:43]
	v_mfma_f32_16x16x32_bf16 v[44:47], v[122:125], v[204:207], v[44:47]
	v_mfma_f32_16x16x32_bf16 v[28:31], v[122:125], v[212:215], v[28:31]
	v_mfma_f32_16x16x32_bf16 v[24:27], v[170:173], v[212:215], v[24:27]
	v_mfma_f32_16x16x32_bf16 v[8:11], v[170:173], v[220:223], v[8:11]
	v_mfma_f32_16x16x32_bf16 v[12:15], v[122:125], v[220:223], v[12:15]
	s_setprio 0
	s_setprio 1
	v_mfma_f32_16x16x32_bf16 v[52:55], v[174:177], v[192:195], v[52:55]
	v_mfma_f32_16x16x32_bf16 v[48:51], v[184:187], v[192:195], v[48:51]
	v_mfma_f32_16x16x32_bf16 v[32:35], v[184:187], v[200:203], v[32:35]
	v_mfma_f32_16x16x32_bf16 v[36:39], v[174:177], v[200:203], v[36:39]
	v_mfma_f32_16x16x32_bf16 v[20:23], v[174:177], v[208:211], v[20:23]
	v_mfma_f32_16x16x32_bf16 v[16:19], v[184:187], v[208:211], v[16:19]
	v_mfma_f32_16x16x32_bf16 v[0:3], v[184:187], v[216:219], v[0:3]
	v_mfma_f32_16x16x32_bf16 v[4:7], v[174:177], v[216:219], v[4:7]
	v_mfma_f32_16x16x32_bf16 v[52:55], v[178:181], v[196:199], v[52:55]
	v_mfma_f32_16x16x32_bf16 v[48:51], v[188:191], v[196:199], v[48:51]
	v_mfma_f32_16x16x32_bf16 v[32:35], v[188:191], v[204:207], v[32:35]
	v_mfma_f32_16x16x32_bf16 v[36:39], v[178:181], v[204:207], v[36:39]
	v_mfma_f32_16x16x32_bf16 v[20:23], v[178:181], v[212:215], v[20:23]
	v_mfma_f32_16x16x32_bf16 v[16:19], v[188:191], v[212:215], v[16:19]
	v_mfma_f32_16x16x32_bf16 v[0:3], v[188:191], v[220:223], v[0:3]
	v_mfma_f32_16x16x32_bf16 v[4:7], v[178:181], v[220:223], v[4:7]
	s_setprio 0
	s_barrier
	s_add_i32 s75, s75, 2
	s_add_u32 s45, s45, 0x100
	s_addc_u32 s47, s47, 0
	s_add_u32 s48, s48, 0x100
	s_addc_u32 s49, s49, 0
	s_cmp_gt_u32 s75, 13
	s_cbranch_scc1 .LBB0_1361

; #define PG8_STAGE(bufoff, gbase, voff) do { _Pragma("unroll") for (int _i = 0; _i < 2; ++_i) \
;         __builtin_amdgcn_global_load_lds((const unsigned*)((const char*)(gbase) + (voff)[_i]), (PG8_LAS unsigned*)(lds + (bufoff) + ldsw + _i * 8192), 16, 0, 0); } while (0)
; #define PG8_LDA(dst, b, h) do { _Pragma("unroll") for (int m = 0; m < 4; ++m) _Pragma("unroll") for (int k = 0; k < 2; ++k) dst[m][k] = *(const PG8_LAS bf16x8*)(lds + PG8_SA(b, h) + aoff + m * 2048 + k * 1024); } while (0)
; #define PG8_LDB(dst, b, h) do { _Pragma("unroll") for (int n = 0; n < 2; ++n) _Pragma("unroll") for (int k = 0; k < 2; ++k) dst[n][k] = *(const PG8_LAS bf16x8*)(lds + PG8_SB(b, h) + boff + n * 2048 + k * 1024); } while (0)
; #define PG8_MMA(ai, bj, At, Bt) do { __builtin_amdgcn_s_setprio(1); _Pragma("unroll") for (int m = 0; m < 4; ++m) _Pragma("unroll") for (int n = 0; n < 2; ++n) _Pragma("unroll") for (int k = 0; k < 2; ++k) \
;         acc[ai][bj][m][n] = __builtin_amdgcn_mfma_f32_16x16x32_bf16(Bt[n][k], At[m][k], acc[ai][bj][m][n], 0, 0, 0); __builtin_amdgcn_s_setprio(0); } while (0)
; #define PG8_WAIT_V(n) asm volatile("s_waitcnt vmcnt(" #n ")" ::: "memory")
; #define PG8_WAIT_L(n) asm volatile("s_waitcnt lgkmcnt(" #n ")" ::: "memory")
; #define PG8_BAR __builtin_amdgcn_s_barrier()
; #define PG8_SCHED __builtin_amdgcn_sched_barrier(0)
; template <class Epi, class Sched, bool ALIGN_EPI = false, bool SP2 = false>
; __device__ __forceinline__ void gemm_phase(PG8_LAS unsigned char* lds, const Gemm g, const Sched& S, const Epi& E) {
;     ...
;             PG8_LDB(B0, 0, 0); PG8_LDB(B1, 0, 1); PG8_SCHED; PG8_LDA(At, 0, 0); PG8_STAGE(PG8_SA(1, 1), a1 + hstep, voffA);
;             PG8_WAIT_V(8); PG8_WAIT_L(0); PG8_BAR; PG8_MMA(0, 0, At, B0); PG8_MMA(0, 1, At, B1); PG8_BAR; PG8_SCHED;
;             PG8_LDA(At, 0, 1); PG8_STAGE(PG8_SB(0, 0), b2, voffB); PG8_STAGE(PG8_SB(0, 1), b2 + hstep, voffB); PG8_STAGE(PG8_SA(0, 0), a2, voffA);
.LBB0_1432:
	ds_read_b128 v[128:131], v167
	ds_read_b128 v[132:135], v167 offset:1024
	ds_read_b128 v[136:139], v167 offset:2048
	ds_read_b128 v[140:143], v167 offset:3072
	ds_read_b128 v[160:163], v168
	ds_read_b128 v[170:173], v168 offset:1024
	ds_read_b128 v[174:177], v168 offset:2048
	ds_read_b128 v[178:181], v168 offset:3072
	s_add_u32 s20, s18, 0x100
	s_addc_u32 s21, s19, 0
	s_cmp_eq_u32 s52, 40
	s_cselect_b32 s27, s5, s21
	s_cselect_b32 s26, s4, s20
	s_cselect_b32 s23, s17, s51
	s_cselect_b32 s22, s16, s50
	v_lshl_add_u64 v[214:215], s[18:19], 0, v[154:155]
	s_add_i32 m0, s36, 0xc000
	ds_read_b128 v[182:185], v169
	ds_read_b128 v[186:189], v169 offset:1024
	ds_read_b128 v[190:193], v169 offset:2048
	ds_read_b128 v[194:197], v169 offset:3072
	ds_read_b128 v[198:201], v169 offset:4096
	ds_read_b128 v[202:205], v169 offset:5120
	ds_read_b128 v[206:209], v169 offset:6144
	ds_read_b128 v[210:213], v169 offset:7168
	global_load_lds_dwordx4 v[214:215], off
	v_lshl_add_u64 v[214:215], s[18:19], 0, v[152:153]
	s_add_i32 m0, s36, 0xe000
	s_nop 0
	global_load_lds_dwordx4 v[214:215], off
	s_waitcnt vmcnt(8)
	s_waitcnt lgkmcnt(0)
	s_barrier
	s_setprio 1
	s_waitcnt lgkmcnt(0)
	v_mfma_f32_16x16x32_bf16 v[124:127], v[128:131], v[182:185], v[124:127]
	v_mfma_f32_16x16x32_bf16 v[120:123], v[136:139], v[182:185], v[120:123]
	v_mfma_f32_16x16x32_bf16 v[108:111], v[136:139], v[190:193], v[108:111]
	v_mfma_f32_16x16x32_bf16 v[116:119], v[128:131], v[190:193], v[116:119]
	v_mfma_f32_16x16x32_bf16 v[100:103], v[128:131], v[198:201], v[100:103]
	v_mfma_f32_16x16x32_bf16 v[92:95], v[136:139], v[198:201], v[92:95]
	v_mfma_f32_16x16x32_bf16 v[76:79], v[136:139], v[206:209], v[76:79]
	v_mfma_f32_16x16x32_bf16 v[84:87], v[128:131], v[206:209], v[84:87]
	v_mfma_f32_16x16x32_bf16 v[124:127], v[132:135], v[186:189], v[124:127]
	v_mfma_f32_16x16x32_bf16 v[120:123], v[140:143], v[186:189], v[120:123]
	v_mfma_f32_16x16x32_bf16 v[108:111], v[140:143], v[194:197], v[108:111]
	v_mfma_f32_16x16x32_bf16 v[116:119], v[132:135], v[194:197], v[116:119]
	v_mfma_f32_16x16x32_bf16 v[100:103], v[132:135], v[202:205], v[100:103]
	v_mfma_f32_16x16x32_bf16 v[92:95], v[140:143], v[202:205], v[92:95]
	v_mfma_f32_16x16x32_bf16 v[76:79], v[140:143], v[210:213], v[76:79]
	v_mfma_f32_16x16x32_bf16 v[84:87], v[132:135], v[210:213], v[84:87]
	s_setprio 0
	s_setprio 1
	v_mfma_f32_16x16x32_bf16 v[112:115], v[160:163], v[182:185], v[112:115]
	v_mfma_f32_16x16x32_bf16 v[104:107], v[174:177], v[182:185], v[104:107]
	v_mfma_f32_16x16x32_bf16 v[88:91], v[174:177], v[190:193], v[88:91]
	v_mfma_f32_16x16x32_bf16 v[96:99], v[160:163], v[190:193], v[96:99]
	v_mfma_f32_16x16x32_bf16 v[80:83], v[160:163], v[198:201], v[80:83]
	v_mfma_f32_16x16x32_bf16 v[72:75], v[174:177], v[198:201], v[72:75]
	v_mfma_f32_16x16x32_bf16 v[64:67], v[174:177], v[206:209], v[64:67]
	v_mfma_f32_16x16x32_bf16 v[68:71], v[160:163], v[206:209], v[68:71]
	v_mfma_f32_16x16x32_bf16 v[112:115], v[170:173], v[186:189], v[112:115]
	v_mfma_f32_16x16x32_bf16 v[104:107], v[178:181], v[186:189], v[104:107]
	v_mfma_f32_16x16x32_bf16 v[88:91], v[178:181], v[194:197], v[88:91]
	v_mfma_f32_16x16x32_bf16 v[96:99], v[170:173], v[194:197], v[96:99]
	v_mfma_f32_16x16x32_bf16 v[80:83], v[170:173], v[202:205], v[80:83]
	v_mfma_f32_16x16x32_bf16 v[72:75], v[178:181], v[202:205], v[72:75]
	v_mfma_f32_16x16x32_bf16 v[64:67], v[178:181], v[210:213], v[64:67]
	v_mfma_f32_16x16x32_bf16 v[68:71], v[170:173], v[210:213], v[68:71]
	s_setprio 0
	s_barrier
	s_add_i32 s18, s44, s33
	v_lshl_add_u64 v[214:215], s[22:23], 0, v[148:149]
	s_mov_b32 m0, s18
	ds_read_b128 v[182:185], v169 offset:16384
	ds_read_b128 v[186:189], v169 offset:17408
	ds_read_b128 v[190:193], v169 offset:18432
	ds_read_b128 v[194:197], v169 offset:19456
	ds_read_b128 v[198:201], v169 offset:20480
	ds_read_b128 v[202:205], v169 offset:21504
	ds_read_b128 v[206:209], v169 offset:22528
	ds_read_b128 v[210:213], v169 offset:23552
	global_load_lds_dwordx4 v[214:215], off
	s_add_i32 m0, s18, 0x2000
	s_add_u32 s18, s22, 0xb0000
	v_lshl_add_u64 v[216:217], s[22:23], 0, v[144:145]
	s_addc_u32 s19, s23, 0
	s_add_i32 s53, s45, s33
	global_load_lds_dwordx4 v[216:217], off
	v_lshl_add_u64 v[218:219], s[18:19], 0, v[148:149]
	s_mov_b32 m0, s53
	v_lshl_add_u64 v[220:221], s[26:27], 0, v[146:147]
	global_load_lds_dwordx4 v[218:219], off
	v_lshl_add_u64 v[218:219], s[18:19], 0, v[144:145]
	s_add_i32 m0, s53, 0x2000
	s_nop 0
	global_load_lds_dwordx4 v[218:219], off
	v_lshl_add_u64 v[218:219], s[26:27], 0, v[150:151]
	s_mov_b32 m0, s36
	s_nop 0
	global_load_lds_dwordx4 v[218:219], off
	s_mov_b32 m0, s37
	s_nop 0
	global_load_lds_dwordx4 v[220:221], off
	s_waitcnt vmcnt(8)
	s_waitcnt lgkmcnt(0)
	s_barrier
; #define PG8_STAGE(bufoff, gbase, voff) do { _Pragma("unroll") for (int _i = 0; _i < 2; ++_i) \
;         __builtin_amdgcn_global_load_lds((const unsigned*)((const char*)(gbase) + (voff)[_i]), (PG8_LAS unsigned*)(lds + (bufoff) + ldsw + _i * 8192), 16, 0, 0); } while (0)
; #define PG8_LDA(dst, b, h) do { _Pragma("unroll") for (int m = 0; m < 4; ++m) _Pragma("unroll") for (int k = 0; k < 2; ++k) dst[m][k] = *(const PG8_LAS bf16x8*)(lds + PG8_SA(b, h) + aoff + m * 2048 + k * 1024); } while (0)
; #define PG8_LDB(dst, b, h) do { _Pragma("unroll") for (int n = 0; n < 2; ++n) _Pragma("unroll") for (int k = 0; k < 2; ++k) dst[n][k] = *(const PG8_LAS bf16x8*)(lds + PG8_SB(b, h) + boff + n * 2048 + k * 1024); } while (0)
; #define PG8_MMA(ai, bj, At, Bt) do { __builtin_amdgcn_s_setprio(1); _Pragma("unroll") for (int m = 0; m < 4; ++m) _Pragma("unroll") for (int n = 0; n < 2; ++n) _Pragma("unroll") for (int k = 0; k < 2; ++k) \
;         acc[ai][bj][m][n] = __builtin_amdgcn_mfma_f32_16x16x32_bf16(Bt[n][k], At[m][k], acc[ai][bj][m][n], 0, 0, 0); __builtin_amdgcn_s_setprio(0); } while (0)
; #define PG8_WAIT_V(n) asm volatile("s_waitcnt vmcnt(" #n ")" ::: "memory")
; #define PG8_WAIT_L(n) asm volatile("s_waitcnt lgkmcnt(" #n ")" ::: "memory")
; #define PG8_BAR __builtin_amdgcn_s_barrier()
; #define PG8_SCHED __builtin_amdgcn_sched_barrier(0)
; template <class Epi, class Sched, bool ALIGN_EPI = false, bool SP2 = false>
; __device__ __forceinline__ void gemm_phase(PG8_LAS unsigned char* lds, const Gemm g, const Sched& S, const Epi& E) {
;     ...
;             PG8_WAIT_V(8); PG8_WAIT_L(0); PG8_BAR; PG8_MMA(1, 0, At, B0); PG8_MMA(1, 1, At, B1); PG8_BAR; PG8_SCHED;
;             PG8_LDB(B0, 1, 0); PG8_LDB(B1, 1, 1); PG8_SCHED; PG8_LDA(At, 1, 0); PG8_STAGE(PG8_SA(0, 1), a2 + hstep, voffA);
;             PG8_WAIT_V(8); PG8_WAIT_L(0); PG8_BAR; PG8_MMA(0, 0, At, B0); PG8_MMA(0, 1, At, B1); PG8_BAR; PG8_SCHED;
	s_setprio 1
	s_waitcnt lgkmcnt(0)
	v_mfma_f32_16x16x32_bf16 v[60:63], v[128:131], v[182:185], v[60:63]
	v_mfma_f32_16x16x32_bf16 v[56:59], v[136:139], v[182:185], v[56:59]
	v_mfma_f32_16x16x32_bf16 v[44:47], v[136:139], v[190:193], v[44:47]
	v_mfma_f32_16x16x32_bf16 v[48:51], v[128:131], v[190:193], v[48:51]
	v_mfma_f32_16x16x32_bf16 v[36:39], v[128:131], v[198:201], v[36:39]
	v_mfma_f32_16x16x32_bf16 v[28:31], v[136:139], v[198:201], v[28:31]
	v_mfma_f32_16x16x32_bf16 v[12:15], v[136:139], v[206:209], v[12:15]
	v_mfma_f32_16x16x32_bf16 v[20:23], v[128:131], v[206:209], v[20:23]
	v_mfma_f32_16x16x32_bf16 v[60:63], v[132:135], v[186:189], v[60:63]
	v_mfma_f32_16x16x32_bf16 v[56:59], v[140:143], v[186:189], v[56:59]
	v_mfma_f32_16x16x32_bf16 v[44:47], v[140:143], v[194:197], v[44:47]
	v_mfma_f32_16x16x32_bf16 v[48:51], v[132:135], v[194:197], v[48:51]
	v_mfma_f32_16x16x32_bf16 v[36:39], v[132:135], v[202:205], v[36:39]
	v_mfma_f32_16x16x32_bf16 v[28:31], v[140:143], v[202:205], v[28:31]
	v_mfma_f32_16x16x32_bf16 v[12:15], v[140:143], v[210:213], v[12:15]
	v_mfma_f32_16x16x32_bf16 v[20:23], v[132:135], v[210:213], v[20:23]
	s_setprio 0
	s_setprio 1
	v_mfma_f32_16x16x32_bf16 v[52:55], v[160:163], v[182:185], v[52:55]
	v_mfma_f32_16x16x32_bf16 v[40:43], v[174:177], v[182:185], v[40:43]
	v_mfma_f32_16x16x32_bf16 v[24:27], v[174:177], v[190:193], v[24:27]
	v_mfma_f32_16x16x32_bf16 v[32:35], v[160:163], v[190:193], v[32:35]
	v_mfma_f32_16x16x32_bf16 v[16:19], v[160:163], v[198:201], v[16:19]
	v_mfma_f32_16x16x32_bf16 v[8:11], v[174:177], v[198:201], v[8:11]
	v_mfma_f32_16x16x32_bf16 v[0:3], v[174:177], v[206:209], v[0:3]
	v_mfma_f32_16x16x32_bf16 v[4:7], v[160:163], v[206:209], v[4:7]
	v_mfma_f32_16x16x32_bf16 v[52:55], v[170:173], v[186:189], v[52:55]
	v_mfma_f32_16x16x32_bf16 v[40:43], v[178:181], v[186:189], v[40:43]
	v_mfma_f32_16x16x32_bf16 v[24:27], v[178:181], v[194:197], v[24:27]
	v_mfma_f32_16x16x32_bf16 v[32:35], v[170:173], v[194:197], v[32:35]
	v_mfma_f32_16x16x32_bf16 v[16:19], v[170:173], v[202:205], v[16:19]
	v_mfma_f32_16x16x32_bf16 v[8:11], v[178:181], v[202:205], v[8:11]
	v_mfma_f32_16x16x32_bf16 v[0:3], v[178:181], v[210:213], v[0:3]
	v_mfma_f32_16x16x32_bf16 v[4:7], v[170:173], v[210:213], v[4:7]
	s_setprio 0
	s_barrier
	s_add_i32 s53, 0, 0x18000
	s_add_i32 s54, 0, 0x1c000
	v_add_u32_e32 v140, s53, v165
	v_add_u32_e32 v178, s54, v165
	ds_read_b128 v[128:131], v140
	ds_read_b128 v[132:135], v140 offset:1024
	ds_read_b128 v[136:139], v140 offset:2048
	ds_read_b128 v[140:143], v140 offset:3072
	ds_read_b128 v[160:163], v178
	ds_read_b128 v[170:173], v178 offset:1024
	ds_read_b128 v[174:177], v178 offset:2048
	ds_read_b128 v[178:181], v178 offset:3072
	s_add_u32 s18, s26, 0xb0000
	s_addc_u32 s19, s27, 0
	s_mov_b32 m0, s38
	v_lshl_add_u64 v[222:223], s[18:19], 0, v[150:151]
	ds_read_b128 v[182:185], v169 offset:32768
	ds_read_b128 v[186:189], v169 offset:33792
	ds_read_b128 v[190:193], v169 offset:34816
	ds_read_b128 v[194:197], v169 offset:35840
	ds_read_b128 v[198:201], v169 offset:36864
	ds_read_b128 v[202:205], v169 offset:37888
	ds_read_b128 v[206:209], v169 offset:38912
	ds_read_b128 v[210:213], v169 offset:39936
	global_load_lds_dwordx4 v[222:223], off
	v_lshl_add_u64 v[222:223], s[18:19], 0, v[146:147]
	s_mov_b32 m0, s39
	s_nop 0
	global_load_lds_dwordx4 v[222:223], off
	s_waitcnt vmcnt(8)
	s_waitcnt lgkmcnt(0)
	s_barrier
	s_setprio 1
	s_waitcnt lgkmcnt(0)
	v_mfma_f32_16x16x32_bf16 v[124:127], v[128:131], v[182:185], v[124:127]
	v_mfma_f32_16x16x32_bf16 v[120:123], v[136:139], v[182:185], v[120:123]
	v_mfma_f32_16x16x32_bf16 v[108:111], v[136:139], v[190:193], v[108:111]
	v_mfma_f32_16x16x32_bf16 v[116:119], v[128:131], v[190:193], v[116:119]
	v_mfma_f32_16x16x32_bf16 v[100:103], v[128:131], v[198:201], v[100:103]
	v_mfma_f32_16x16x32_bf16 v[92:95], v[136:139], v[198:201], v[92:95]
	v_mfma_f32_16x16x32_bf16 v[76:79], v[136:139], v[206:209], v[76:79]
	v_mfma_f32_16x16x32_bf16 v[84:87], v[128:131], v[206:209], v[84:87]
	v_mfma_f32_16x16x32_bf16 v[124:127], v[132:135], v[186:189], v[124:127]
	v_mfma_f32_16x16x32_bf16 v[120:123], v[140:143], v[186:189], v[120:123]
	v_mfma_f32_16x16x32_bf16 v[108:111], v[140:143], v[194:197], v[108:111]
	v_mfma_f32_16x16x32_bf16 v[116:119], v[132:135], v[194:197], v[116:119]
	v_mfma_f32_16x16x32_bf16 v[100:103], v[132:135], v[202:205], v[100:103]
	v_mfma_f32_16x16x32_bf16 v[92:95], v[140:143], v[202:205], v[92:95]
	v_mfma_f32_16x16x32_bf16 v[76:79], v[140:143], v[210:213], v[76:79]
	v_mfma_f32_16x16x32_bf16 v[84:87], v[132:135], v[210:213], v[84:87]
	s_setprio 0
	s_setprio 1
	v_mfma_f32_16x16x32_bf16 v[112:115], v[160:163], v[182:185], v[112:115]
	v_mfma_f32_16x16x32_bf16 v[104:107], v[174:177], v[182:185], v[104:107]
	v_mfma_f32_16x16x32_bf16 v[88:91], v[174:177], v[190:193], v[88:91]
	v_mfma_f32_16x16x32_bf16 v[96:99], v[160:163], v[190:193], v[96:99]
	v_mfma_f32_16x16x32_bf16 v[80:83], v[160:163], v[198:201], v[80:83]
	v_mfma_f32_16x16x32_bf16 v[72:75], v[174:177], v[198:201], v[72:75]
	v_mfma_f32_16x16x32_bf16 v[64:67], v[174:177], v[206:209], v[64:67]
	v_mfma_f32_16x16x32_bf16 v[68:71], v[160:163], v[206:209], v[68:71]
	v_mfma_f32_16x16x32_bf16 v[112:115], v[170:173], v[186:189], v[112:115]
	v_mfma_f32_16x16x32_bf16 v[104:107], v[178:181], v[186:189], v[104:107]
	v_mfma_f32_16x16x32_bf16 v[88:91], v[178:181], v[194:197], v[88:91]
	v_mfma_f32_16x16x32_bf16 v[96:99], v[170:173], v[194:197], v[96:99]
	v_mfma_f32_16x16x32_bf16 v[80:83], v[170:173], v[202:205], v[80:83]
	v_mfma_f32_16x16x32_bf16 v[72:75], v[178:181], v[202:205], v[72:75]
	v_mfma_f32_16x16x32_bf16 v[64:67], v[178:181], v[210:213], v[64:67]
	v_mfma_f32_16x16x32_bf16 v[68:71], v[170:173], v[210:213], v[68:71]
	s_setprio 0
	s_barrier
; #define PG8_STAGE(bufoff, gbase, voff) do { _Pragma("unroll") for (int _i = 0; _i < 2; ++_i) \
;         __builtin_amdgcn_global_load_lds((const unsigned*)((const char*)(gbase) + (voff)[_i]), (PG8_LAS unsigned*)(lds + (bufoff) + ldsw + _i * 8192), 16, 0, 0); } while (0)
; #define PG8_LDA(dst, b, h) do { _Pragma("unroll") for (int m = 0; m < 4; ++m) _Pragma("unroll") for (int k = 0; k < 2; ++k) dst[m][k] = *(const PG8_LAS bf16x8*)(lds + PG8_SA(b, h) + aoff + m * 2048 + k * 1024); } while (0)
; #define PG8_MMA(ai, bj, At, Bt) do { __builtin_amdgcn_s_setprio(1); _Pragma("unroll") for (int m = 0; m < 4; ++m) _Pragma("unroll") for (int n = 0; n < 2; ++n) _Pragma("unroll") for (int k = 0; k < 2; ++k) \
;         acc[ai][bj][m][n] = __builtin_amdgcn_mfma_f32_16x16x32_bf16(Bt[n][k], At[m][k], acc[ai][bj][m][n], 0, 0, 0); __builtin_amdgcn_s_setprio(0); } while (0)
; #define PG8_WAIT_V(n) asm volatile("s_waitcnt vmcnt(" #n ")" ::: "memory")
; #define PG8_WAIT_L(n) asm volatile("s_waitcnt lgkmcnt(" #n ")" ::: "memory")
; #define PG8_BAR __builtin_amdgcn_s_barrier()
; #define PG8_SCHED __builtin_amdgcn_sched_barrier(0)
; template <class Epi, class Sched, bool ALIGN_EPI = false, bool SP2 = false>
; __device__ __forceinline__ void gemm_phase(PG8_LAS unsigned char* lds, const Gemm g, const Sched& S, const Epi& E) {
;     ...
;         for (int t = 0; t < nt; t += 2) {
;     ...
;             PG8_LDA(At, 1, 1); PG8_STAGE(PG8_SB(1, 0), b3, voffB); PG8_STAGE(PG8_SB(1, 1), b3 + hstep, voffB); PG8_STAGE(PG8_SA(1, 0), a3, voffA);
;             PG8_WAIT_V(8); PG8_WAIT_L(0); PG8_BAR; PG8_MMA(1, 0, At, B0); PG8_MMA(1, 1, At, B1); PG8_BAR; PG8_SCHED;
	s_add_i32 s18, s53, s33
	v_lshl_add_u64 v[214:215], v[214:215], 0, s[12:13]
	s_mov_b32 m0, s18
	ds_read_b128 v[182:185], v169 offset:49152
	ds_read_b128 v[186:189], v169 offset:50176
	ds_read_b128 v[190:193], v169 offset:51200
	ds_read_b128 v[194:197], v169 offset:52224
	ds_read_b128 v[198:201], v169 offset:53248
	ds_read_b128 v[202:205], v169 offset:54272
	ds_read_b128 v[206:209], v169 offset:55296
	ds_read_b128 v[210:213], v169 offset:56320
	global_load_lds_dwordx4 v[214:215], off
	s_add_i32 m0, s18, 0x2000
	s_add_u32 s18, s22, 0xb0080
	v_lshl_add_u64 v[214:215], v[216:217], 0, s[12:13]
	s_addc_u32 s19, s23, 0
	s_add_i32 s22, s54, s33
	global_load_lds_dwordx4 v[214:215], off
	v_lshl_add_u64 v[214:215], s[18:19], 0, v[148:149]
	s_mov_b32 m0, s22
	s_nop 0
	global_load_lds_dwordx4 v[214:215], off
	v_lshl_add_u64 v[214:215], s[18:19], 0, v[144:145]
	s_add_i32 m0, s22, 0x2000
	s_nop 0
	global_load_lds_dwordx4 v[214:215], off
	v_lshl_add_u64 v[214:215], v[218:219], 0, s[12:13]
	s_mov_b32 m0, s41
	s_nop 0
	global_load_lds_dwordx4 v[214:215], off
	v_lshl_add_u64 v[214:215], v[220:221], 0, s[12:13]
	s_mov_b32 m0, s42
	s_nop 0
	global_load_lds_dwordx4 v[214:215], off
	s_waitcnt vmcnt(8)
	s_waitcnt lgkmcnt(0)
	s_barrier
	s_setprio 1
	s_waitcnt lgkmcnt(0)
	v_mfma_f32_16x16x32_bf16 v[60:63], v[128:131], v[182:185], v[60:63]
	v_mfma_f32_16x16x32_bf16 v[56:59], v[136:139], v[182:185], v[56:59]
	v_mfma_f32_16x16x32_bf16 v[44:47], v[136:139], v[190:193], v[44:47]
	v_mfma_f32_16x16x32_bf16 v[48:51], v[128:131], v[190:193], v[48:51]
	v_mfma_f32_16x16x32_bf16 v[36:39], v[128:131], v[198:201], v[36:39]
	v_mfma_f32_16x16x32_bf16 v[28:31], v[136:139], v[198:201], v[28:31]
	v_mfma_f32_16x16x32_bf16 v[12:15], v[136:139], v[206:209], v[12:15]
	v_mfma_f32_16x16x32_bf16 v[20:23], v[128:131], v[206:209], v[20:23]
	v_mfma_f32_16x16x32_bf16 v[60:63], v[132:135], v[186:189], v[60:63]
	v_mfma_f32_16x16x32_bf16 v[56:59], v[140:143], v[186:189], v[56:59]
	v_mfma_f32_16x16x32_bf16 v[44:47], v[140:143], v[194:197], v[44:47]
	v_mfma_f32_16x16x32_bf16 v[48:51], v[132:135], v[194:197], v[48:51]
	v_mfma_f32_16x16x32_bf16 v[36:39], v[132:135], v[202:205], v[36:39]
	v_mfma_f32_16x16x32_bf16 v[28:31], v[140:143], v[202:205], v[28:31]
	v_mfma_f32_16x16x32_bf16 v[12:15], v[140:143], v[210:213], v[12:15]
	v_mfma_f32_16x16x32_bf16 v[20:23], v[132:135], v[210:213], v[20:23]
	s_setprio 0
	s_setprio 1
	v_mfma_f32_16x16x32_bf16 v[52:55], v[160:163], v[182:185], v[52:55]
	v_mfma_f32_16x16x32_bf16 v[40:43], v[174:177], v[182:185], v[40:43]
	v_mfma_f32_16x16x32_bf16 v[24:27], v[174:177], v[190:193], v[24:27]
	v_mfma_f32_16x16x32_bf16 v[32:35], v[160:163], v[190:193], v[32:35]
	v_mfma_f32_16x16x32_bf16 v[16:19], v[160:163], v[198:201], v[16:19]
	v_mfma_f32_16x16x32_bf16 v[8:11], v[174:177], v[198:201], v[8:11]
	v_mfma_f32_16x16x32_bf16 v[0:3], v[174:177], v[206:209], v[0:3]
	v_mfma_f32_16x16x32_bf16 v[4:7], v[160:163], v[206:209], v[4:7]
	v_mfma_f32_16x16x32_bf16 v[52:55], v[170:173], v[186:189], v[52:55]
	v_mfma_f32_16x16x32_bf16 v[40:43], v[178:181], v[186:189], v[40:43]
	v_mfma_f32_16x16x32_bf16 v[24:27], v[178:181], v[194:197], v[24:27]
	v_mfma_f32_16x16x32_bf16 v[32:35], v[170:173], v[194:197], v[32:35]
	v_mfma_f32_16x16x32_bf16 v[16:19], v[170:173], v[202:205], v[16:19]
	v_mfma_f32_16x16x32_bf16 v[8:11], v[178:181], v[202:205], v[8:11]
	v_mfma_f32_16x16x32_bf16 v[0:3], v[178:181], v[210:213], v[0:3]
	v_mfma_f32_16x16x32_bf16 v[4:7], v[170:173], v[210:213], v[4:7]
	s_setprio 0
	s_barrier
	s_add_i32 s52, s52, 2
	s_add_u32 s50, s50, 0x100
	s_addc_u32 s51, s51, 0
	s_cmp_gt_u32 s52, 41
	s_mov_b64 s[18:19], s[20:21]
	s_cbranch_scc0 .LBB0_1432
	s_and_b64 vcc, exec, s[14:15]
	s_cbranch_vccz .LBB0_1435
	s_barrier
